# P2: loop-head vmcnt(0) dropped, rope table prefetched+deduped, epilogue stores widened to dwordx4 via permlane16_swap + cvt_pk_bf16; P2 table conversion through LDS-DMA ring; P5 epilogue rewritten (x
# speedup vs baseline: 1.0271x; 1.0271x over previous
; #define PG8_STAGE(bufoff, gbase, voff) do { _Pragma("unroll") for (int _i = 0; _i < 2; ++_i) \
;         __builtin_amdgcn_global_load_lds((const unsigned*)((const char*)(gbase) + (voff)[_i]), (PG8_LAS unsigned*)(lds + (bufoff) + ldsw + _i * 8192), 16, 0, 0); } while (0)
; #define PG8_LDA(dst, b, h) do { _Pragma("unroll") for (int m = 0; m < 4; ++m) _Pragma("unroll") for (int k = 0; k < 2; ++k) dst[m][k] = *(const PG8_LAS bf16x8*)(lds + PG8_SA(b, h) + aoff + m * 2048 + k * 1024); } while (0)
; #define PG8_LDB(dst, b, h) do { _Pragma("unroll") for (int n = 0; n < 2; ++n) _Pragma("unroll") for (int k = 0; k < 2; ++k) dst[n][k] = *(const PG8_LAS bf16x8*)(lds + PG8_SB(b, h) + boff + n * 2048 + k * 1024); } while (0)
; #define PG8_MMA(ai, bj, At, Bt) do { __builtin_amdgcn_s_setprio(1); _Pragma("unroll") for (int m = 0; m < 4; ++m) _Pragma("unroll") for (int n = 0; n < 2; ++n) _Pragma("unroll") for (int k = 0; k < 2; ++k) \
;         acc[ai][bj][m][n] = __builtin_amdgcn_mfma_f32_16x16x32_bf16(Bt[n][k], At[m][k], acc[ai][bj][m][n], 0, 0, 0); __builtin_amdgcn_s_setprio(0); } while (0)
; #define PG8_WAIT_V(n) asm volatile("s_waitcnt vmcnt(" #n ")" ::: "memory")
; #define PG8_BAR __builtin_amdgcn_s_barrier()
; template <class Epi, class Sched, bool ALIGN_EPI = false, bool SP2 = false>
; __device__ __forceinline__ void gemm_phase(PG8_LAS unsigned char* lds, const Gemm g, const Sched& S, const Epi& E) {
;     ...
;         for (int t = 0; t < nt; t += 2) {
;             const bool last = (t == nt - 2);
;             const char* a1 = cA + (size_t)(t + 1) * kstep;
;             const char* a2 = last ? nA : cA + (size_t)(t + 2) * kstep; const char* b2 = last ? nB : cB + (size_t)(t + 2) * kstep;
;             const char* a3 = a2 + kstep; const char* b3 = b2 + kstep;
;             if (last && has_next) S.a_ready(nxt);
;             if constexpr (SP2) {
;             PG8_LDB(B0, 0, 0); PG8_LDB(B1, 0, 1); PG8_SCHED; PG8_LDA(At, 0, 0); PG8_STAGE(PG8_SA(1, 1), a1 + hstep, voffA);
;             PG8_WAIT_V(8); PG8_WAIT_L(0); PG8_BAR; PG8_MMA(0, 0, At, B0); PG8_MMA(0, 1, At, B1); PG8_BAR; PG8_SCHED;
;             PG8_LDA(At, 0, 1); PG8_STAGE(PG8_SB(0, 0), b2, voffB); PG8_STAGE(PG8_SB(0, 1), b2 + hstep, voffB); PG8_STAGE(PG8_SA(0, 0), a2, voffA);
;             PG8_WAIT_V(8); PG8_WAIT_L(0); PG8_BAR; PG8_MMA(1, 0, At, B0); PG8_MMA(1, 1, At, B1); PG8_BAR; PG8_SCHED;
.LBB0_231:
	ds_read_b128 v[46:49], v168
	ds_read_b128 v[50:53], v168 offset:1024
	ds_read_b128 v[54:57], v168 offset:2048
	ds_read_b128 v[58:61], v168 offset:3072
	ds_read_b128 v[162:165], v169
	ds_read_b128 v[174:177], v169 offset:1024
	ds_read_b128 v[180:183], v169 offset:2048
	ds_read_b128 v[184:187], v169 offset:3072
	s_add_u32 s70, s4, 0xfffc0080
	s_addc_u32 s71, s5, -1
	s_cmp_eq_u32 s69, 12
	s_cselect_b32 s85, s7, s71
	s_cselect_b32 s84, s8, s70
	s_cselect_b32 s71, s17, s68
	s_cselect_b32 s70, s65, s67
	v_lshl_add_u64 v[166:167], s[4:5], 0, v[158:159]
	s_add_i32 m0, s35, 0xc000
	ds_read_b128 v[188:191], v170
	ds_read_b128 v[192:195], v170 offset:1024
	ds_read_b128 v[196:199], v170 offset:2048
	ds_read_b128 v[200:203], v170 offset:3072
	ds_read_b128 v[204:207], v170 offset:4096
	ds_read_b128 v[208:211], v170 offset:5120
	ds_read_b128 v[212:215], v170 offset:6144
	ds_read_b128 v[216:219], v170 offset:7168
	global_load_lds_dwordx4 v[166:167], off
	v_lshl_add_u64 v[166:167], s[4:5], 0, v[160:161]
	s_add_i32 m0, s35, 0xe000
	s_nop 0
	global_load_lds_dwordx4 v[166:167], off
	s_waitcnt vmcnt(8)
	s_waitcnt lgkmcnt(0)
	s_barrier
	s_setprio 1
	s_waitcnt lgkmcnt(0)
	v_mfma_f32_16x16x32_bf16 v[142:145], v[46:49], v[188:191], v[142:145]
	v_mfma_f32_16x16x32_bf16 v[138:141], v[54:57], v[188:191], v[138:141]
	v_mfma_f32_16x16x32_bf16 v[126:129], v[46:49], v[196:199], v[126:129]
	v_mfma_f32_16x16x32_bf16 v[122:125], v[54:57], v[196:199], v[122:125]
	v_mfma_f32_16x16x32_bf16 v[110:113], v[46:49], v[204:207], v[110:113]
	v_mfma_f32_16x16x32_bf16 v[106:109], v[54:57], v[204:207], v[106:109]
	v_mfma_f32_16x16x32_bf16 v[94:97], v[46:49], v[212:215], v[94:97]
	v_mfma_f32_16x16x32_bf16 v[90:93], v[54:57], v[212:215], v[90:93]
	v_mfma_f32_16x16x32_bf16 v[142:145], v[50:53], v[192:195], v[142:145]
	v_mfma_f32_16x16x32_bf16 v[138:141], v[58:61], v[192:195], v[138:141]
	v_mfma_f32_16x16x32_bf16 v[126:129], v[50:53], v[200:203], v[126:129]
	v_mfma_f32_16x16x32_bf16 v[122:125], v[58:61], v[200:203], v[122:125]
	v_mfma_f32_16x16x32_bf16 v[110:113], v[50:53], v[208:211], v[110:113]
	v_mfma_f32_16x16x32_bf16 v[106:109], v[58:61], v[208:211], v[106:109]
	v_mfma_f32_16x16x32_bf16 v[94:97], v[50:53], v[216:219], v[94:97]
	v_mfma_f32_16x16x32_bf16 v[90:93], v[58:61], v[216:219], v[90:93]
	s_setprio 0
	s_setprio 1
	v_mfma_f32_16x16x32_bf16 v[134:137], v[162:165], v[188:191], v[134:137]
	v_mfma_f32_16x16x32_bf16 v[130:133], v[180:183], v[188:191], v[130:133]
	v_mfma_f32_16x16x32_bf16 v[118:121], v[162:165], v[196:199], v[118:121]
	v_mfma_f32_16x16x32_bf16 v[114:117], v[180:183], v[196:199], v[114:117]
	v_mfma_f32_16x16x32_bf16 v[102:105], v[162:165], v[204:207], v[102:105]
	v_mfma_f32_16x16x32_bf16 v[98:101], v[180:183], v[204:207], v[98:101]
	v_mfma_f32_16x16x32_bf16 v[86:89], v[162:165], v[212:215], v[86:89]
	v_mfma_f32_16x16x32_bf16 v[82:85], v[180:183], v[212:215], v[82:85]
	v_mfma_f32_16x16x32_bf16 v[134:137], v[174:177], v[192:195], v[134:137]
	v_mfma_f32_16x16x32_bf16 v[130:133], v[184:187], v[192:195], v[130:133]
	v_mfma_f32_16x16x32_bf16 v[118:121], v[174:177], v[200:203], v[118:121]
	v_mfma_f32_16x16x32_bf16 v[114:117], v[184:187], v[200:203], v[114:117]
	v_mfma_f32_16x16x32_bf16 v[102:105], v[174:177], v[208:211], v[102:105]
	v_mfma_f32_16x16x32_bf16 v[98:101], v[184:187], v[208:211], v[98:101]
	v_mfma_f32_16x16x32_bf16 v[86:89], v[174:177], v[216:219], v[86:89]
	v_mfma_f32_16x16x32_bf16 v[82:85], v[184:187], v[216:219], v[82:85]
	s_setprio 0
	s_barrier
	s_add_i32 s86, s58, s34
	v_lshl_add_u64 v[166:167], s[70:71], 0, v[148:149]
	s_mov_b32 m0, s86
	ds_read_b128 v[188:191], v170 offset:16384
	ds_read_b128 v[192:195], v170 offset:17408
	ds_read_b128 v[196:199], v170 offset:18432
	ds_read_b128 v[200:203], v170 offset:19456
	ds_read_b128 v[204:207], v170 offset:20480
	ds_read_b128 v[208:211], v170 offset:21504
	ds_read_b128 v[212:215], v170 offset:22528
	ds_read_b128 v[216:219], v170 offset:23552
	global_load_lds_dwordx4 v[166:167], off
	s_add_i32 m0, s86, 0x2000
	s_add_u32 s86, s70, 0x40000
	v_lshl_add_u64 v[220:221], s[70:71], 0, v[146:147]
	s_addc_u32 s87, s71, 0
	s_add_i32 s88, s59, s34
	global_load_lds_dwordx4 v[220:221], off
	v_lshl_add_u64 v[222:223], s[86:87], 0, v[148:149]
	s_mov_b32 m0, s88
	v_lshl_add_u64 v[224:225], s[84:85], 0, v[146:147]
	global_load_lds_dwordx4 v[222:223], off
	v_lshl_add_u64 v[222:223], s[86:87], 0, v[146:147]
	s_add_i32 m0, s88, 0x2000
	s_nop 0
	global_load_lds_dwordx4 v[222:223], off
	v_lshl_add_u64 v[222:223], s[84:85], 0, v[148:149]
	s_mov_b32 m0, s35
	s_nop 0
	global_load_lds_dwordx4 v[222:223], off
	s_mov_b32 m0, s72
	s_nop 0
	global_load_lds_dwordx4 v[224:225], off
	s_waitcnt vmcnt(8)
	s_waitcnt lgkmcnt(0)
	s_barrier
; #define PG8_STAGE(bufoff, gbase, voff) do { _Pragma("unroll") for (int _i = 0; _i < 2; ++_i) \
;         __builtin_amdgcn_global_load_lds((const unsigned*)((const char*)(gbase) + (voff)[_i]), (PG8_LAS unsigned*)(lds + (bufoff) + ldsw + _i * 8192), 16, 0, 0); } while (0)
; #define PG8_LDA(dst, b, h) do { _Pragma("unroll") for (int m = 0; m < 4; ++m) _Pragma("unroll") for (int k = 0; k < 2; ++k) dst[m][k] = *(const PG8_LAS bf16x8*)(lds + PG8_SA(b, h) + aoff + m * 2048 + k * 1024); } while (0)
; #define PG8_LDB(dst, b, h) do { _Pragma("unroll") for (int n = 0; n < 2; ++n) _Pragma("unroll") for (int k = 0; k < 2; ++k) dst[n][k] = *(const PG8_LAS bf16x8*)(lds + PG8_SB(b, h) + boff + n * 2048 + k * 1024); } while (0)
; #define PG8_MMA(ai, bj, At, Bt) do { __builtin_amdgcn_s_setprio(1); _Pragma("unroll") for (int m = 0; m < 4; ++m) _Pragma("unroll") for (int n = 0; n < 2; ++n) _Pragma("unroll") for (int k = 0; k < 2; ++k) \
;         acc[ai][bj][m][n] = __builtin_amdgcn_mfma_f32_16x16x32_bf16(Bt[n][k], At[m][k], acc[ai][bj][m][n], 0, 0, 0); __builtin_amdgcn_s_setprio(0); } while (0)
; #define PG8_WAIT_V(n) asm volatile("s_waitcnt vmcnt(" #n ")" ::: "memory")
; #define PG8_WAIT_L(n) asm volatile("s_waitcnt lgkmcnt(" #n ")" ::: "memory")
; #define PG8_BAR __builtin_amdgcn_s_barrier()
; #define PG8_SCHED __builtin_amdgcn_sched_barrier(0)
; template <class Epi, class Sched, bool ALIGN_EPI = false, bool SP2 = false>
; __device__ __forceinline__ void gemm_phase(PG8_LAS unsigned char* lds, const Gemm g, const Sched& S, const Epi& E) {
;     ...
;             PG8_WAIT_V(8); PG8_WAIT_L(0); PG8_BAR; PG8_MMA(1, 0, At, B0); PG8_MMA(1, 1, At, B1); PG8_BAR; PG8_SCHED;
;             PG8_LDB(B0, 1, 0); PG8_LDB(B1, 1, 1); PG8_SCHED; PG8_LDA(At, 1, 0); PG8_STAGE(PG8_SA(0, 1), a2 + hstep, voffA);
;             PG8_WAIT_V(8); PG8_WAIT_L(0); PG8_BAR; PG8_MMA(0, 0, At, B0); PG8_MMA(0, 1, At, B1); PG8_BAR; PG8_SCHED;
	s_setprio 1
	s_waitcnt lgkmcnt(0)
	v_mfma_f32_16x16x32_bf16 v[78:81], v[46:49], v[188:191], v[78:81]
	v_mfma_f32_16x16x32_bf16 v[74:77], v[54:57], v[188:191], v[74:77]
	v_mfma_f32_16x16x32_bf16 v[62:65], v[46:49], v[196:199], v[62:65]
	v_mfma_f32_16x16x32_bf16 v[42:45], v[54:57], v[196:199], v[42:45]
	v_mfma_f32_16x16x32_bf16 v[30:33], v[46:49], v[204:207], v[30:33]
	v_mfma_f32_16x16x32_bf16 v[26:29], v[54:57], v[204:207], v[26:29]
	v_mfma_f32_16x16x32_bf16 v[14:17], v[46:49], v[212:215], v[14:17]
	v_mfma_f32_16x16x32_bf16 v[10:13], v[54:57], v[212:215], v[10:13]
	v_mfma_f32_16x16x32_bf16 v[78:81], v[50:53], v[192:195], v[78:81]
	v_mfma_f32_16x16x32_bf16 v[74:77], v[58:61], v[192:195], v[74:77]
	v_mfma_f32_16x16x32_bf16 v[62:65], v[50:53], v[200:203], v[62:65]
	v_mfma_f32_16x16x32_bf16 v[42:45], v[58:61], v[200:203], v[42:45]
	v_mfma_f32_16x16x32_bf16 v[30:33], v[50:53], v[208:211], v[30:33]
	v_mfma_f32_16x16x32_bf16 v[26:29], v[58:61], v[208:211], v[26:29]
	v_mfma_f32_16x16x32_bf16 v[14:17], v[50:53], v[216:219], v[14:17]
	v_mfma_f32_16x16x32_bf16 v[10:13], v[58:61], v[216:219], v[10:13]
	s_setprio 0
	s_setprio 1
	v_mfma_f32_16x16x32_bf16 v[38:41], v[162:165], v[196:199], v[38:41]
	v_mfma_f32_16x16x32_bf16 v[34:37], v[180:183], v[196:199], v[34:37]
	v_mfma_f32_16x16x32_bf16 v[22:25], v[162:165], v[204:207], v[22:25]
	v_mfma_f32_16x16x32_bf16 v[18:21], v[180:183], v[204:207], v[18:21]
	v_mfma_f32_16x16x32_bf16 v[6:9], v[162:165], v[212:215], v[6:9]
	v_mfma_f32_16x16x32_bf16 v[2:5], v[180:183], v[212:215], v[2:5]
	v_mfma_f32_16x16x32_bf16 v[46:49], v[162:165], v[188:191], v[70:73]
	v_mfma_f32_16x16x32_bf16 v[50:53], v[180:183], v[188:191], v[66:69]
	v_mfma_f32_16x16x32_bf16 v[38:41], v[174:177], v[200:203], v[38:41]
	v_mfma_f32_16x16x32_bf16 v[34:37], v[184:187], v[200:203], v[34:37]
	v_mfma_f32_16x16x32_bf16 v[22:25], v[174:177], v[208:211], v[22:25]
	v_mfma_f32_16x16x32_bf16 v[18:21], v[184:187], v[208:211], v[18:21]
	v_mfma_f32_16x16x32_bf16 v[6:9], v[174:177], v[216:219], v[6:9]
	v_mfma_f32_16x16x32_bf16 v[2:5], v[184:187], v[216:219], v[2:5]
	v_mfma_f32_16x16x32_bf16 v[46:49], v[174:177], v[192:195], v[46:49]
	v_mfma_f32_16x16x32_bf16 v[50:53], v[184:187], v[192:195], v[50:53]
	s_setprio 0
	s_barrier
	s_add_i32 s86, 0, 0x18000
	s_add_i32 s87, 0, 0x1c000
	v_add_u32_e32 v70, s86, v153
	v_add_u32_e32 v150, s87, v153
	ds_read_b128 v[54:57], v70
	ds_read_b128 v[58:61], v70 offset:1024
	ds_read_b128 v[66:69], v70 offset:2048
	ds_read_b128 v[70:73], v70 offset:3072
	ds_read_b128 v[162:165], v150
	ds_read_b128 v[174:177], v150 offset:1024
	ds_read_b128 v[180:183], v150 offset:2048
	ds_read_b128 v[184:187], v150 offset:3072
	s_add_u32 s84, s84, 0x40000
	s_addc_u32 s85, s85, 0
	s_mov_b32 m0, s73
	v_lshl_add_u64 v[226:227], s[84:85], 0, v[148:149]
	ds_read_b128 v[188:191], v170 offset:32768
	ds_read_b128 v[192:195], v170 offset:33792
	ds_read_b128 v[196:199], v170 offset:34816
	ds_read_b128 v[200:203], v170 offset:35840
	ds_read_b128 v[204:207], v170 offset:36864
	ds_read_b128 v[208:211], v170 offset:37888
	ds_read_b128 v[212:215], v170 offset:38912
	ds_read_b128 v[216:219], v170 offset:39936
	global_load_lds_dwordx4 v[226:227], off
	v_lshl_add_u64 v[226:227], s[84:85], 0, v[146:147]
	s_mov_b32 m0, s79
	s_nop 0
	global_load_lds_dwordx4 v[226:227], off
	s_waitcnt vmcnt(8)
	s_waitcnt lgkmcnt(0)
	s_barrier
	s_setprio 1
	s_waitcnt lgkmcnt(0)
	v_mfma_f32_16x16x32_bf16 v[142:145], v[54:57], v[188:191], v[142:145]
	v_mfma_f32_16x16x32_bf16 v[138:141], v[66:69], v[188:191], v[138:141]
	v_mfma_f32_16x16x32_bf16 v[126:129], v[54:57], v[196:199], v[126:129]
	v_mfma_f32_16x16x32_bf16 v[122:125], v[66:69], v[196:199], v[122:125]
	v_mfma_f32_16x16x32_bf16 v[110:113], v[54:57], v[204:207], v[110:113]
	v_mfma_f32_16x16x32_bf16 v[106:109], v[66:69], v[204:207], v[106:109]
	v_mfma_f32_16x16x32_bf16 v[94:97], v[54:57], v[212:215], v[94:97]
	v_mfma_f32_16x16x32_bf16 v[90:93], v[66:69], v[212:215], v[90:93]
	v_mfma_f32_16x16x32_bf16 v[142:145], v[58:61], v[192:195], v[142:145]
	v_mfma_f32_16x16x32_bf16 v[138:141], v[70:73], v[192:195], v[138:141]
	v_mfma_f32_16x16x32_bf16 v[126:129], v[58:61], v[200:203], v[126:129]
	v_mfma_f32_16x16x32_bf16 v[122:125], v[70:73], v[200:203], v[122:125]
	v_mfma_f32_16x16x32_bf16 v[110:113], v[58:61], v[208:211], v[110:113]
	v_mfma_f32_16x16x32_bf16 v[106:109], v[70:73], v[208:211], v[106:109]
	v_mfma_f32_16x16x32_bf16 v[94:97], v[58:61], v[216:219], v[94:97]
	v_mfma_f32_16x16x32_bf16 v[90:93], v[70:73], v[216:219], v[90:93]
	s_setprio 0
	s_setprio 1
	v_mfma_f32_16x16x32_bf16 v[134:137], v[162:165], v[188:191], v[134:137]
	v_mfma_f32_16x16x32_bf16 v[130:133], v[180:183], v[188:191], v[130:133]
	v_mfma_f32_16x16x32_bf16 v[118:121], v[162:165], v[196:199], v[118:121]
	v_mfma_f32_16x16x32_bf16 v[114:117], v[180:183], v[196:199], v[114:117]
	v_mfma_f32_16x16x32_bf16 v[102:105], v[162:165], v[204:207], v[102:105]
	v_mfma_f32_16x16x32_bf16 v[98:101], v[180:183], v[204:207], v[98:101]
	v_mfma_f32_16x16x32_bf16 v[86:89], v[162:165], v[212:215], v[86:89]
	v_mfma_f32_16x16x32_bf16 v[82:85], v[180:183], v[212:215], v[82:85]
	v_mfma_f32_16x16x32_bf16 v[134:137], v[174:177], v[192:195], v[134:137]
	v_mfma_f32_16x16x32_bf16 v[130:133], v[184:187], v[192:195], v[130:133]
	v_mfma_f32_16x16x32_bf16 v[118:121], v[174:177], v[200:203], v[118:121]
	v_mfma_f32_16x16x32_bf16 v[114:117], v[184:187], v[200:203], v[114:117]
	v_mfma_f32_16x16x32_bf16 v[102:105], v[174:177], v[208:211], v[102:105]
	v_mfma_f32_16x16x32_bf16 v[98:101], v[184:187], v[208:211], v[98:101]
	v_mfma_f32_16x16x32_bf16 v[86:89], v[174:177], v[216:219], v[86:89]
	v_mfma_f32_16x16x32_bf16 v[82:85], v[184:187], v[216:219], v[82:85]
	s_setprio 0
	s_barrier
; #define PG8_STAGE(bufoff, gbase, voff) do { _Pragma("unroll") for (int _i = 0; _i < 2; ++_i) \
;         __builtin_amdgcn_global_load_lds((const unsigned*)((const char*)(gbase) + (voff)[_i]), (PG8_LAS unsigned*)(lds + (bufoff) + ldsw + _i * 8192), 16, 0, 0); } while (0)
; #define PG8_LDA(dst, b, h) do { _Pragma("unroll") for (int m = 0; m < 4; ++m) _Pragma("unroll") for (int k = 0; k < 2; ++k) dst[m][k] = *(const PG8_LAS bf16x8*)(lds + PG8_SA(b, h) + aoff + m * 2048 + k * 1024); } while (0)
; #define PG8_MMA(ai, bj, At, Bt) do { __builtin_amdgcn_s_setprio(1); _Pragma("unroll") for (int m = 0; m < 4; ++m) _Pragma("unroll") for (int n = 0; n < 2; ++n) _Pragma("unroll") for (int k = 0; k < 2; ++k) \
;         acc[ai][bj][m][n] = __builtin_amdgcn_mfma_f32_16x16x32_bf16(Bt[n][k], At[m][k], acc[ai][bj][m][n], 0, 0, 0); __builtin_amdgcn_s_setprio(0); } while (0)
; #define PG8_WAIT_V(n) asm volatile("s_waitcnt vmcnt(" #n ")" ::: "memory")
; #define PG8_WAIT_L(n) asm volatile("s_waitcnt lgkmcnt(" #n ")" ::: "memory")
; #define PG8_BAR __builtin_amdgcn_s_barrier()
; #define PG8_SCHED __builtin_amdgcn_sched_barrier(0)
; template <class Epi, class Sched, bool ALIGN_EPI = false, bool SP2 = false>
; __device__ __forceinline__ void gemm_phase(PG8_LAS unsigned char* lds, const Gemm g, const Sched& S, const Epi& E) {
;     ...
;             PG8_LDA(At, 1, 1); PG8_STAGE(PG8_SB(1, 0), b3, voffB); PG8_STAGE(PG8_SB(1, 1), b3 + hstep, voffB); PG8_STAGE(PG8_SA(1, 0), a3, voffA);
;             PG8_WAIT_V(8); PG8_WAIT_L(0); PG8_BAR; PG8_MMA(1, 0, At, B0); PG8_MMA(1, 1, At, B1); PG8_BAR; PG8_SCHED;
;     __device__ __forceinline__ void operator()(const pg8::f32x4 (&acc)[2][2][4][2], const pg8::Unit& u, int wr, int wc, int fr, int fq) const {
;     ...
;                 const bool rope = (grp == 0 || grp == 1 || grp == 4 || grp == 5) && !isctx;
;                 if (rope) {
; #pragma unroll
;                     for (int bj = 0; bj < 2; ++bj) {
;                         const f32x4 cs = *(const f32x4*)(tab + (size_t)l * 64 + 16 * bj + 4 * fq), sn = *(const f32x4*)(tab + (size_t)l * 64 + 32 + 16 * bj + 4 * fq);
	s_add_i32 s84, s86, s34
	v_lshl_add_u64 v[166:167], v[166:167], 0, s[48:49]
	s_mov_b32 m0, s84
	ds_read_b128 v[188:191], v170 offset:49152
	ds_read_b128 v[192:195], v170 offset:50176
	ds_read_b128 v[196:199], v170 offset:51200
	ds_read_b128 v[200:203], v170 offset:52224
	ds_read_b128 v[204:207], v170 offset:53248
	ds_read_b128 v[208:211], v170 offset:54272
	ds_read_b128 v[212:215], v170 offset:55296
	ds_read_b128 v[216:219], v170 offset:56320
	global_load_lds_dwordx4 v[166:167], off
	s_add_i32 m0, s84, 0x2000
	s_add_u32 s70, s70, 0x40080
	v_lshl_add_u64 v[166:167], v[220:221], 0, s[48:49]
	s_addc_u32 s71, s71, 0
	s_add_i32 s84, s87, s34
	global_load_lds_dwordx4 v[166:167], off
	v_lshl_add_u64 v[166:167], s[70:71], 0, v[148:149]
	s_mov_b32 m0, s84
	s_nop 0
	global_load_lds_dwordx4 v[166:167], off
	v_lshl_add_u64 v[166:167], s[70:71], 0, v[146:147]
	s_add_i32 m0, s84, 0x2000
	s_nop 0
	global_load_lds_dwordx4 v[166:167], off
	v_lshl_add_u64 v[166:167], v[222:223], 0, s[48:49]
	s_mov_b32 m0, s74
	s_nop 0
	global_load_lds_dwordx4 v[166:167], off
	v_lshl_add_u64 v[166:167], v[224:225], 0, s[48:49]
	s_mov_b32 m0, s75
	s_nop 0
	global_load_lds_dwordx4 v[166:167], off
	s_waitcnt vmcnt(8)
	s_waitcnt lgkmcnt(0)
	s_barrier
	s_setprio 1
	s_waitcnt lgkmcnt(0)
	v_mfma_f32_16x16x32_bf16 v[78:81], v[54:57], v[188:191], v[78:81]
	v_mfma_f32_16x16x32_bf16 v[74:77], v[66:69], v[188:191], v[74:77]
	v_mfma_f32_16x16x32_bf16 v[62:65], v[54:57], v[196:199], v[62:65]
	v_mfma_f32_16x16x32_bf16 v[42:45], v[66:69], v[196:199], v[42:45]
	v_mfma_f32_16x16x32_bf16 v[30:33], v[54:57], v[204:207], v[30:33]
	v_mfma_f32_16x16x32_bf16 v[26:29], v[66:69], v[204:207], v[26:29]
	v_mfma_f32_16x16x32_bf16 v[14:17], v[54:57], v[212:215], v[14:17]
	v_mfma_f32_16x16x32_bf16 v[10:13], v[66:69], v[212:215], v[10:13]
	v_mfma_f32_16x16x32_bf16 v[78:81], v[58:61], v[192:195], v[78:81]
	v_mfma_f32_16x16x32_bf16 v[74:77], v[70:73], v[192:195], v[74:77]
	v_mfma_f32_16x16x32_bf16 v[62:65], v[58:61], v[200:203], v[62:65]
	v_mfma_f32_16x16x32_bf16 v[42:45], v[70:73], v[200:203], v[42:45]
	v_mfma_f32_16x16x32_bf16 v[30:33], v[58:61], v[208:211], v[30:33]
	v_mfma_f32_16x16x32_bf16 v[26:29], v[70:73], v[208:211], v[26:29]
	v_mfma_f32_16x16x32_bf16 v[14:17], v[58:61], v[216:219], v[14:17]
	v_mfma_f32_16x16x32_bf16 v[10:13], v[70:73], v[216:219], v[10:13]
	s_setprio 0
	s_setprio 1
	v_mfma_f32_16x16x32_bf16 v[46:49], v[162:165], v[188:191], v[46:49]
	v_mfma_f32_16x16x32_bf16 v[70:73], v[174:177], v[192:195], v[46:49]
	v_mfma_f32_16x16x32_bf16 v[46:49], v[180:183], v[188:191], v[50:53]
	v_mfma_f32_16x16x32_bf16 v[38:41], v[162:165], v[196:199], v[38:41]
	v_mfma_f32_16x16x32_bf16 v[34:37], v[180:183], v[196:199], v[34:37]
	v_mfma_f32_16x16x32_bf16 v[22:25], v[162:165], v[204:207], v[22:25]
	v_mfma_f32_16x16x32_bf16 v[18:21], v[180:183], v[204:207], v[18:21]
	v_mfma_f32_16x16x32_bf16 v[6:9], v[162:165], v[212:215], v[6:9]
	v_mfma_f32_16x16x32_bf16 v[2:5], v[180:183], v[212:215], v[2:5]
	v_mfma_f32_16x16x32_bf16 v[66:69], v[184:187], v[192:195], v[46:49]
	v_mfma_f32_16x16x32_bf16 v[38:41], v[174:177], v[200:203], v[38:41]
	v_mfma_f32_16x16x32_bf16 v[34:37], v[184:187], v[200:203], v[34:37]
	v_mfma_f32_16x16x32_bf16 v[22:25], v[174:177], v[208:211], v[22:25]
	v_mfma_f32_16x16x32_bf16 v[18:21], v[184:187], v[208:211], v[18:21]
	v_mfma_f32_16x16x32_bf16 v[6:9], v[174:177], v[216:219], v[6:9]
	v_mfma_f32_16x16x32_bf16 v[2:5], v[184:187], v[216:219], v[2:5]
	s_setprio 0
	s_barrier
	s_add_i32 s69, s69, 2
	s_add_u32 s4, s4, 0x100
	s_addc_u32 s5, s5, 0
	s_add_u32 s67, s67, 0x100
	s_addc_u32 s68, s68, 0
	s_cmp_gt_u32 s69, 13
	s_cbranch_scc0 .LBB0_231
	s_mul_hi_i32 s98, s6, 0x38e38e39
	s_lshr_b32 s99, s98, 31
	s_ashr_i32 s98, s98, 1
	s_add_i32 s98, s98, s99
	s_mul_i32 s98, s98, 9
	s_sub_i32 s98, s6, s98
	s_cmp_eq_u32 s98, 0
	s_cbranch_scc1 .Lp2_rope_pf_skip
	s_cmp_lt_u32 s16, 2
	s_cbranch_scc1 .Lp2_rope_pf_do
	s_cmp_lt_u32 s16, 6
	s_cbranch_scc1 .Lp2_rope_pf_skip
	s_cmp_gt_u32 s16, 9
	s_cbranch_scc1 .Lp2_rope_pf_skip
.Lp2_rope_pf_do:
	v_lshl_add_u32 v238, s98, 8, v1
	s_mov_b64 s[100:101], 0x2000
	v_add_u32_e32 v238, 0xffffff10, v238
	v_ashrrev_i32_e32 v239, 31, v238
	v_lshlrev_b64 v[242:243], 8, v[238:239]
	v_lshl_add_u64 v[242:243], v[156:157], 0, v[242:243]
	v_lshl_add_u64 v[244:245], v[242:243], 0, s[100:101]
	s_mov_b64 s[100:101], 0x7000
	global_load_dwordx4 v[190:193], v[242:243], off offset:-4096
	global_load_dwordx4 v[194:197], v[242:243], off offset:-3968
	global_load_dwordx4 v[206:209], v[242:243], off offset:-4032
	global_load_dwordx4 v[210:213], v[242:243], off offset:-3904
	v_lshl_add_u64 v[246:247], v[242:243], 0, s[100:101]
	global_load_dwordx4 v[214:217], v[242:243], off offset:64
	global_load_dwordx4 v[218:221], v[242:243], off offset:192
	global_load_dwordx4 v[222:225], v[244:245], off offset:-4032
	global_load_dwordx4 v[226:229], v[244:245], off offset:-3904
	global_load_dwordx4 v[230:233], v[244:245], off offset:64
	global_load_dwordx4 v[234:237], v[244:245], off offset:192
	global_load_dwordx4 v[198:201], v[246:247], off
	global_load_dwordx4 v[202:205], v[246:247], off offset:128
.Lp2_rope_pf_skip:
	s_and_b64 vcc, exec, s[50:51]
	s_cbranch_vccz .LBB0_234
	s_barrier

;     __device__ __forceinline__ void operator()(const pg8::f32x4 (&acc)[2][2][4][2], const pg8::Unit& u, int wr, int wc, int fr, int fq) const {
;     ...
;                 const bool rope = (grp == 0 || grp == 1 || grp == 4 || grp == 5) && !isctx;
;                 if (rope) {
; #pragma unroll
;                     for (int bj = 0; bj < 2; ++bj) {
;                         const f32x4 cs = *(const f32x4*)(tab + (size_t)l * 64 + 16 * bj + 4 * fq), sn = *(const f32x4*)(tab + (size_t)l * 64 + 32 + 16 * bj + 4 * fq);
;                         const f32x4 x0 = v[bj][0], x1 = v[bj][1];
;                         v[bj][0] = x0 * cs - x1 * sn; v[bj][1] = x1 * cs + x0 * sn;
;                     }
.LBB0_240:
	s_mul_hi_i32 s7, s6, 0x38e38e39
	s_lshr_b32 s8, s7, 31
	s_ashr_i32 s7, s7, 1
	s_add_i32 s86, s7, s8
	s_mul_i32 s7, s86, 9
	s_sub_i32 s8, s6, s7
	s_cmp_lg_u32 s8, 0
	s_cselect_b64 s[6:7], -1, 0
	s_cmp_lt_u32 s65, 2
	s_cselect_b64 s[68:69], -1, 0
	s_or_b64 s[68:69], s[68:69], s[70:71]
	s_and_b64 s[68:69], s[68:69], s[6:7]
	v_lshl_add_u32 v162, s8, 8, v1
	v_cndmask_b32_e64 v150, 0, 1, s[68:69]
	v_cmp_ne_u32_e64 s[6:7], 1, v150
	s_andn2_b64 vcc, exec, s[68:69]
	v_add_u32_e32 v164, 0xffffff00, v162
	s_cbranch_vccnz .LBB0_242
	v_ashrrev_i32_e32 v165, 31, v164
	s_waitcnt vmcnt(0)
	v_pk_mul_f32 v[184:185], v[140:141], v[196:197]
	v_pk_mul_f32 v[188:189], v[138:139], v[194:195]
	v_pk_fma_f32 v[186:187], v[144:145], v[192:193], v[184:185] neg_lo:[0,0,1] neg_hi:[0,0,1]
	v_pk_fma_f32 v[184:185], v[142:143], v[190:191], v[188:189] neg_lo:[0,0,1] neg_hi:[0,0,1]
	v_pk_mul_f32 v[144:145], v[144:145], v[196:197]
	v_pk_mul_f32 v[142:143], v[142:143], v[194:195]
	v_pk_fma_f32 v[140:141], v[140:141], v[192:193], v[144:145]
	v_pk_fma_f32 v[138:139], v[138:139], v[190:191], v[142:143]
	v_pk_mul_f32 v[166:167], v[132:133], v[212:213]
	v_pk_mul_f32 v[180:181], v[130:131], v[210:211]
	v_pk_fma_f32 v[182:183], v[136:137], v[208:209], v[166:167] neg_lo:[0,0,1] neg_hi:[0,0,1]
	v_pk_fma_f32 v[180:181], v[134:135], v[206:207], v[180:181] neg_lo:[0,0,1] neg_hi:[0,0,1]
	v_pk_mul_f32 v[136:137], v[136:137], v[212:213]
	v_pk_mul_f32 v[134:135], v[134:135], v[210:211]
	v_pk_fma_f32 v[132:133], v[132:133], v[208:209], v[136:137]
	v_pk_fma_f32 v[130:131], v[130:131], v[206:207], v[134:135]
	v_mov_b64_e32 v[134:135], v[180:181]
	v_mov_b64_e32 v[142:143], v[184:185]
	v_mov_b64_e32 v[136:137], v[182:183]
	v_mov_b64_e32 v[144:145], v[186:187]

; __device__ __forceinline__ unsigned pk2(float lo, float hi) { return f2bf(lo) | (f2bf(hi) << 16); }
;     __device__ __forceinline__ void operator()(const pg8::f32x4 (&acc)[2][2][4][2], const pg8::Unit& u, int wr, int wc, int fr, int fq) const {
;     ...
;                 if (grp == 4 || grp == 5) {
;                     float ss = 0.f;
; #pragma unroll
;                     for (int bj = 0; bj < 2; ++bj)
; #pragma unroll
;                         for (int n = 0; n < 2; ++n) ss += (v[bj][n].x * v[bj][n].x + v[bj][n].y * v[bj][n].y) + (v[bj][n].z * v[bj][n].z + v[bj][n].w * v[bj][n].w);
;                     ss += __shfl_xor(ss, 16); ss += __shfl_xor(ss, 32);
;                     const float rstd = rsqrtf(ss * (1.f / 64.f) + EPS);
; #pragma unroll
;                     for (int bj = 0; bj < 2; ++bj)
; #pragma unroll
;                         for (int n = 0; n < 2; ++n) v[bj][n] = v[bj][n] * rstd * gq[bj][n];
;                 }
;     ...
; #pragma unroll
;                 for (int bj = 0; bj < 2; ++bj)
; #pragma unroll
;                     for (int n = 0; n < 2; ++n) { const f32x4 o = v[bj][n] * scl; v2u pk; pk.x = pk2(o.x, o.y); pk.y = pk2(o.z, o.w);
;                         *(v2u*)(dst + 32 * bj + 16 * n + 4 * fq) = pk; }
.LBB0_265:
	v_pk_mul_f32 v[142:143], v[142:143], s[8:9] op_sel_hi:[1,0]
	v_pk_mul_f32 v[144:145], v[144:145], s[8:9] op_sel_hi:[1,0]
	v_pk_mul_f32 v[138:139], v[138:139], s[8:9] op_sel_hi:[1,0]
	v_pk_mul_f32 v[140:141], v[140:141], s[8:9] op_sel_hi:[1,0]
	v_pk_mul_f32 v[134:135], v[134:135], s[8:9] op_sel_hi:[1,0]
	v_pk_mul_f32 v[136:137], v[136:137], s[8:9] op_sel_hi:[1,0]
	v_pk_mul_f32 v[130:131], v[130:131], s[8:9] op_sel_hi:[1,0]
	v_pk_mul_f32 v[132:133], v[132:133], s[8:9] op_sel_hi:[1,0]
	v_and_b32_e32 v150, 4, v152
	v_and_b32_e32 v239, 8, v152
	v_lshlrev_b32_e32 v150, 3, v150
	v_lshl_or_b32 v150, v239, 1, v150
	v_lshl_add_u64 v[164:165], v[166:167], 0, v[150:151]
	v_cvt_pk_bf16_f32 v142, v142, v143
	v_cvt_pk_bf16_f32 v143, v144, v145
	v_cvt_pk_bf16_f32 v144, v138, v139
	v_cvt_pk_bf16_f32 v145, v140, v141
	v_cvt_pk_bf16_f32 v134, v134, v135
	v_cvt_pk_bf16_f32 v135, v136, v137
	v_cvt_pk_bf16_f32 v136, v130, v131
	v_cvt_pk_bf16_f32 v137, v132, v133
	s_nop 1
	v_permlane16_swap_b32_e32 v142, v144
	v_permlane16_swap_b32_e32 v143, v145
	v_permlane16_swap_b32_e32 v134, v136
	v_permlane16_swap_b32_e32 v135, v137
	s_and_b64 vcc, exec, s[4:5]
	global_store_dwordx4 v[164:165], v[142:145], off
	global_store_dwordx4 v[164:165], v[134:137], off offset:64
	s_nop 1
	s_cbranch_vccnz .LBB0_267
	v_pk_mul_f32 v[130:131], v[128:129], v[128:129]
	v_pk_mul_f32 v[132:133], v[126:127], v[126:127]
	s_nop 0
	v_pk_mov_b32 v[134:135], v[132:133], v[130:131] op_sel:[1,0]
	v_mov_b32_e32 v133, v131
	v_pk_add_f32 v[130:131], v[134:135], v[132:133]
	v_pk_mul_f32 v[132:133], v[124:125], v[124:125]
	v_pk_mul_f32 v[134:135], v[122:123], v[122:123]
	v_pk_add_f32 v[130:131], v[130:131], v[130:131] op_sel:[0,1] op_sel_hi:[1,0]
	v_pk_mov_b32 v[136:137], v[134:135], v[132:133] op_sel:[1,0]
	v_mov_b32_e32 v135, v133
	v_pk_add_f32 v[132:133], v[136:137], v[134:135]
	v_mul_f32_e32 v134, v114, v114
	v_mul_f32_e32 v135, v115, v115
	v_pk_add_f32 v[132:133], v[132:133], v[132:133] op_sel:[0,1] op_sel_hi:[1,0]
	v_mov_b32_e32 v131, v134
	v_mov_b32_e32 v133, v135
	v_pk_add_f32 v[130:131], v[130:131], v[132:133]
	v_mul_f32_e32 v132, v119, v119
	v_mul_f32_e32 v134, v121, v121
	v_mul_f32_e32 v136, v116, v116
	v_mul_f32_e32 v137, v117, v117
	v_pk_fma_f32 v[132:133], v[118:119], v[118:119], v[132:133] op_sel_hi:[1,1,0]
	v_pk_fma_f32 v[134:135], v[120:121], v[120:121], v[134:135] op_sel_hi:[1,1,0]
	v_mov_b32_e32 v133, v136
	v_mov_b32_e32 v135, v137
	v_pk_add_f32 v[132:133], v[132:133], v[134:135]
	s_nop 0
	v_pk_add_f32 v[130:131], v[130:131], v[132:133]
	v_and_b32_e32 v132, 64, v172
	v_add_f32_e32 v130, v130, v131
	v_xor_b32_e32 v131, 16, v172
	v_add_u32_e32 v132, 64, v132
	v_cmp_lt_i32_e32 vcc, v131, v132
	s_nop 1
	v_cndmask_b32_e32 v131, v172, v131, vcc
	v_lshlrev_b32_e32 v131, 2, v131
	ds_bpermute_b32 v131, v131, v130
	s_waitcnt lgkmcnt(0)
	v_add_f32_e32 v130, v130, v131
	v_xor_b32_e32 v131, 32, v172
	v_cmp_lt_i32_e32 vcc, v131, v132
	s_nop 1
	v_cndmask_b32_e32 v131, v172, v131, vcc
	v_lshlrev_b32_e32 v131, 2, v131
	ds_bpermute_b32 v131, v131, v130
	s_waitcnt lgkmcnt(0)
	v_add_f32_e32 v130, v130, v131
	v_fmamk_f32 v130, v130, 0x3c800000, v171
	v_mul_f32_e32 v131, 0x4b800000, v130
	v_cmp_gt_f32_e32 vcc, s10, v130
	s_nop 1
	v_cndmask_b32_e32 v130, v130, v131, vcc
	v_rsq_f32_e32 v130, v130
	s_nop 0
	v_mul_f32_e32 v131, 0x45800000, v130
	v_cndmask_b32_e32 v130, v130, v131, vcc
	v_pk_mul_f32 v[126:127], v[126:127], v[130:131] op_sel_hi:[1,0]
	v_pk_mul_f32 v[128:129], v[128:129], v[130:131] op_sel_hi:[1,0]
	v_pk_mul_f32 v[122:123], v[122:123], v[130:131] op_sel_hi:[1,0]
	v_pk_mul_f32 v[124:125], v[124:125], v[130:131] op_sel_hi:[1,0]
	v_pk_mul_f32 v[118:119], v[118:119], v[130:131] op_sel_hi:[1,0]
	v_pk_mul_f32 v[120:121], v[120:121], v[130:131] op_sel_hi:[1,0]
	v_pk_mul_f32 v[114:115], v[114:115], v[130:131] op_sel_hi:[1,0]
	v_pk_mul_f32 v[116:117], v[116:117], v[130:131] op_sel_hi:[1,0]
	v_pk_mul_f32 v[128:129], v[60:61], v[128:129]
	v_pk_mul_f32 v[126:127], v[58:59], v[126:127]
	v_pk_mul_f32 v[124:125], v[56:57], v[124:125]
	v_pk_mul_f32 v[122:123], v[54:55], v[122:123]
	v_pk_mul_f32 v[120:121], v[52:53], v[120:121]
	v_pk_mul_f32 v[118:119], v[50:51], v[118:119]
	v_pk_mul_f32 v[116:117], v[48:49], v[116:117]
	v_pk_mul_f32 v[114:115], v[46:47], v[114:115]
	s_and_b64 vcc, exec, s[6:7]
	v_add_u32_e32 v130, 0xffffff10, v162
	s_cbranch_vccnz .LBB0_269
	s_branch .LBB0_268

;     __device__ __forceinline__ void operator()(const pg8::f32x4 (&acc)[2][2][4][2], const pg8::Unit& u, int wr, int wc, int fr, int fq) const {
;     ...
;                 if (rope) {
; #pragma unroll
;                     for (int bj = 0; bj < 2; ++bj) {
;                         const f32x4 cs = *(const f32x4*)(tab + (size_t)l * 64 + 16 * bj + 4 * fq), sn = *(const f32x4*)(tab + (size_t)l * 64 + 32 + 16 * bj + 4 * fq);
;                         const f32x4 x0 = v[bj][0], x1 = v[bj][1];
;                         v[bj][0] = x0 * cs - x1 * sn; v[bj][1] = x1 * cs + x0 * sn;
;                     }
.LBB0_268:
	v_ashrrev_i32_e32 v131, 31, v130
	v_pk_mul_f32 v[140:141], v[124:125], v[196:197]
	v_pk_mul_f32 v[164:165], v[122:123], v[194:195]
	v_pk_fma_f32 v[142:143], v[128:129], v[192:193], v[140:141] neg_lo:[0,0,1] neg_hi:[0,0,1]
	v_pk_fma_f32 v[140:141], v[126:127], v[190:191], v[164:165] neg_lo:[0,0,1] neg_hi:[0,0,1]
	v_pk_mul_f32 v[128:129], v[128:129], v[196:197]
	v_pk_mul_f32 v[126:127], v[126:127], v[194:195]
	v_pk_fma_f32 v[124:125], v[124:125], v[192:193], v[128:129]
	v_pk_fma_f32 v[122:123], v[122:123], v[190:191], v[126:127]
	v_pk_mul_f32 v[136:137], v[116:117], v[220:221]
	v_pk_mul_f32 v[144:145], v[114:115], v[218:219]
	v_pk_fma_f32 v[138:139], v[120:121], v[216:217], v[136:137] neg_lo:[0,0,1] neg_hi:[0,0,1]
	v_pk_fma_f32 v[136:137], v[118:119], v[214:215], v[144:145] neg_lo:[0,0,1] neg_hi:[0,0,1]
	v_pk_mul_f32 v[120:121], v[120:121], v[220:221]
	v_pk_mul_f32 v[118:119], v[118:119], v[218:219]
	v_pk_fma_f32 v[116:117], v[116:117], v[216:217], v[120:121]
	v_pk_fma_f32 v[114:115], v[114:115], v[214:215], v[118:119]
	v_mov_b64_e32 v[118:119], v[136:137]
	v_mov_b64_e32 v[126:127], v[140:141]
	v_mov_b64_e32 v[120:121], v[138:139]
	v_mov_b64_e32 v[128:129], v[142:143]

; __device__ __forceinline__ unsigned pk2(float lo, float hi) { return f2bf(lo) | (f2bf(hi) << 16); }
;     __device__ __forceinline__ void operator()(const pg8::f32x4 (&acc)[2][2][4][2], const pg8::Unit& u, int wr, int wc, int fr, int fq) const {
;     ...
;                 if (grp == 4 || grp == 5) {
;                     float ss = 0.f;
; #pragma unroll
;                     for (int bj = 0; bj < 2; ++bj)
; #pragma unroll
;                         for (int n = 0; n < 2; ++n) ss += (v[bj][n].x * v[bj][n].x + v[bj][n].y * v[bj][n].y) + (v[bj][n].z * v[bj][n].z + v[bj][n].w * v[bj][n].w);
;                     ss += __shfl_xor(ss, 16); ss += __shfl_xor(ss, 32);
;                     const float rstd = rsqrtf(ss * (1.f / 64.f) + EPS);
; #pragma unroll
;                     for (int bj = 0; bj < 2; ++bj)
; #pragma unroll
;                         for (int n = 0; n < 2; ++n) v[bj][n] = v[bj][n] * rstd * gq[bj][n];
;                 }
;     ...
; #pragma unroll
;                 for (int bj = 0; bj < 2; ++bj)
; #pragma unroll
;                     for (int n = 0; n < 2; ++n) { const f32x4 o = v[bj][n] * scl; v2u pk; pk.x = pk2(o.x, o.y); pk.y = pk2(o.z, o.w);
;                         *(v2u*)(dst + 32 * bj + 16 * n + 4 * fq) = pk; }
.LBB0_292:
	v_pk_mul_f32 v[126:127], v[126:127], s[8:9] op_sel_hi:[1,0]
	v_pk_mul_f32 v[128:129], v[128:129], s[8:9] op_sel_hi:[1,0]
	v_pk_mul_f32 v[122:123], v[122:123], s[8:9] op_sel_hi:[1,0]
	v_pk_mul_f32 v[124:125], v[124:125], s[8:9] op_sel_hi:[1,0]
	v_pk_mul_f32 v[118:119], v[118:119], s[8:9] op_sel_hi:[1,0]
	v_pk_mul_f32 v[120:121], v[120:121], s[8:9] op_sel_hi:[1,0]
	v_pk_mul_f32 v[114:115], v[114:115], s[8:9] op_sel_hi:[1,0]
	v_pk_mul_f32 v[116:117], v[116:117], s[8:9] op_sel_hi:[1,0]
	v_lshl_add_u64 v[130:131], v[134:135], 0, v[150:151]
	v_cvt_pk_bf16_f32 v126, v126, v127
	v_cvt_pk_bf16_f32 v127, v128, v129
	v_cvt_pk_bf16_f32 v128, v122, v123
	v_cvt_pk_bf16_f32 v129, v124, v125
	v_cvt_pk_bf16_f32 v118, v118, v119
	v_cvt_pk_bf16_f32 v119, v120, v121
	v_cvt_pk_bf16_f32 v120, v114, v115
	v_cvt_pk_bf16_f32 v121, v116, v117
	s_nop 1
	v_permlane16_swap_b32_e32 v126, v128
	v_permlane16_swap_b32_e32 v127, v129
	v_permlane16_swap_b32_e32 v118, v120
	v_permlane16_swap_b32_e32 v119, v121
	s_and_b64 vcc, exec, s[4:5]
	global_store_dwordx4 v[130:131], v[126:129], off
	global_store_dwordx4 v[130:131], v[118:121], off offset:64
	s_nop 1
	s_cbranch_vccnz .LBB0_294
	v_pk_mul_f32 v[114:115], v[112:113], v[112:113]
	v_pk_mul_f32 v[116:117], v[110:111], v[110:111]
	s_nop 0
	v_pk_mov_b32 v[118:119], v[116:117], v[114:115] op_sel:[1,0]
	v_mov_b32_e32 v117, v115
	v_pk_add_f32 v[114:115], v[118:119], v[116:117]
	v_pk_mul_f32 v[116:117], v[108:109], v[108:109]
	v_pk_mul_f32 v[118:119], v[106:107], v[106:107]
	v_pk_add_f32 v[114:115], v[114:115], v[114:115] op_sel:[0,1] op_sel_hi:[1,0]
	v_pk_mov_b32 v[120:121], v[118:119], v[116:117] op_sel:[1,0]
	v_mov_b32_e32 v119, v117
	v_pk_add_f32 v[116:117], v[120:121], v[118:119]
	v_mul_f32_e32 v118, v98, v98
	v_mul_f32_e32 v119, v99, v99
	v_pk_add_f32 v[116:117], v[116:117], v[116:117] op_sel:[0,1] op_sel_hi:[1,0]
	v_mov_b32_e32 v115, v118
	v_mov_b32_e32 v117, v119
	v_pk_add_f32 v[114:115], v[114:115], v[116:117]
	v_mul_f32_e32 v116, v103, v103
	v_mul_f32_e32 v118, v105, v105
	v_mul_f32_e32 v120, v100, v100
	v_mul_f32_e32 v121, v101, v101
	v_pk_fma_f32 v[116:117], v[102:103], v[102:103], v[116:117] op_sel_hi:[1,1,0]
	v_pk_fma_f32 v[118:119], v[104:105], v[104:105], v[118:119] op_sel_hi:[1,1,0]
	v_mov_b32_e32 v117, v120
	v_mov_b32_e32 v119, v121
	v_pk_add_f32 v[116:117], v[116:117], v[118:119]
	s_nop 0
	v_pk_add_f32 v[114:115], v[114:115], v[116:117]
	v_and_b32_e32 v116, 64, v172
	v_add_f32_e32 v114, v114, v115
	v_xor_b32_e32 v115, 16, v172
	v_add_u32_e32 v116, 64, v116
	v_cmp_lt_i32_e32 vcc, v115, v116
	s_nop 1
	v_cndmask_b32_e32 v115, v172, v115, vcc
	v_lshlrev_b32_e32 v115, 2, v115
	ds_bpermute_b32 v115, v115, v114
	s_waitcnt lgkmcnt(0)
	v_add_f32_e32 v114, v114, v115
	v_xor_b32_e32 v115, 32, v172
	v_cmp_lt_i32_e32 vcc, v115, v116
	s_nop 1
	v_cndmask_b32_e32 v115, v172, v115, vcc
	v_lshlrev_b32_e32 v115, 2, v115
	ds_bpermute_b32 v115, v115, v114
	s_waitcnt lgkmcnt(0)
	v_add_f32_e32 v114, v114, v115
	v_fmamk_f32 v114, v114, 0x3c800000, v171
	v_mul_f32_e32 v115, 0x4b800000, v114
	v_cmp_gt_f32_e32 vcc, s10, v114
	s_nop 1
	v_cndmask_b32_e32 v114, v114, v115, vcc
	v_rsq_f32_e32 v114, v114
	s_nop 0
	v_mul_f32_e32 v115, 0x45800000, v114
	v_cndmask_b32_e32 v114, v114, v115, vcc
	v_pk_mul_f32 v[110:111], v[110:111], v[114:115] op_sel_hi:[1,0]
	v_pk_mul_f32 v[112:113], v[112:113], v[114:115] op_sel_hi:[1,0]
	v_pk_mul_f32 v[106:107], v[106:107], v[114:115] op_sel_hi:[1,0]
	v_pk_mul_f32 v[108:109], v[108:109], v[114:115] op_sel_hi:[1,0]
	v_pk_mul_f32 v[102:103], v[102:103], v[114:115] op_sel_hi:[1,0]
	v_pk_mul_f32 v[104:105], v[104:105], v[114:115] op_sel_hi:[1,0]
	v_pk_mul_f32 v[98:99], v[98:99], v[114:115] op_sel_hi:[1,0]
	v_pk_mul_f32 v[100:101], v[100:101], v[114:115] op_sel_hi:[1,0]
	v_pk_mul_f32 v[112:113], v[60:61], v[112:113]
	v_pk_mul_f32 v[110:111], v[58:59], v[110:111]
	v_pk_mul_f32 v[108:109], v[56:57], v[108:109]
	v_pk_mul_f32 v[106:107], v[54:55], v[106:107]
	v_pk_mul_f32 v[104:105], v[52:53], v[104:105]
	v_pk_mul_f32 v[102:103], v[50:51], v[102:103]
	v_pk_mul_f32 v[100:101], v[48:49], v[100:101]
	v_pk_mul_f32 v[98:99], v[46:47], v[98:99]
	s_and_b64 vcc, exec, s[6:7]
	v_add_u32_e32 v114, 0xffffff20, v162
	s_cbranch_vccnz .LBB0_296
	s_branch .LBB0_295

;     __device__ __forceinline__ void operator()(const pg8::f32x4 (&acc)[2][2][4][2], const pg8::Unit& u, int wr, int wc, int fr, int fq) const {
;     ...
;                 if (rope) {
; #pragma unroll
;                     for (int bj = 0; bj < 2; ++bj) {
;                         const f32x4 cs = *(const f32x4*)(tab + (size_t)l * 64 + 16 * bj + 4 * fq), sn = *(const f32x4*)(tab + (size_t)l * 64 + 32 + 16 * bj + 4 * fq);
;                         const f32x4 x0 = v[bj][0], x1 = v[bj][1];
;                         v[bj][0] = x0 * cs - x1 * sn; v[bj][1] = x1 * cs + x0 * sn;
;                     }
.LBB0_295:
	v_ashrrev_i32_e32 v115, 31, v114
	v_pk_mul_f32 v[124:125], v[108:109], v[196:197]
	v_pk_mul_f32 v[130:131], v[106:107], v[194:195]
	v_pk_fma_f32 v[126:127], v[112:113], v[192:193], v[124:125] neg_lo:[0,0,1] neg_hi:[0,0,1]
	v_pk_fma_f32 v[124:125], v[110:111], v[190:191], v[130:131] neg_lo:[0,0,1] neg_hi:[0,0,1]
	v_pk_mul_f32 v[112:113], v[112:113], v[196:197]
	v_pk_mul_f32 v[110:111], v[110:111], v[194:195]
	v_pk_fma_f32 v[108:109], v[108:109], v[192:193], v[112:113]
	v_pk_fma_f32 v[106:107], v[106:107], v[190:191], v[110:111]
	v_pk_mul_f32 v[120:121], v[100:101], v[228:229]
	v_pk_mul_f32 v[128:129], v[98:99], v[226:227]
	v_pk_fma_f32 v[122:123], v[104:105], v[224:225], v[120:121] neg_lo:[0,0,1] neg_hi:[0,0,1]
	v_pk_fma_f32 v[120:121], v[102:103], v[222:223], v[128:129] neg_lo:[0,0,1] neg_hi:[0,0,1]
	v_pk_mul_f32 v[104:105], v[104:105], v[228:229]
	v_pk_mul_f32 v[102:103], v[102:103], v[226:227]
	v_pk_fma_f32 v[100:101], v[100:101], v[224:225], v[104:105]
	v_pk_fma_f32 v[98:99], v[98:99], v[222:223], v[102:103]
	v_mov_b64_e32 v[102:103], v[120:121]
	v_mov_b64_e32 v[110:111], v[124:125]
	v_mov_b64_e32 v[104:105], v[122:123]
	v_mov_b64_e32 v[112:113], v[126:127]

; __device__ __forceinline__ unsigned pk2(float lo, float hi) { return f2bf(lo) | (f2bf(hi) << 16); }
;     __device__ __forceinline__ void operator()(const pg8::f32x4 (&acc)[2][2][4][2], const pg8::Unit& u, int wr, int wc, int fr, int fq) const {
;     ...
;                 if (grp == 4 || grp == 5) {
;                     float ss = 0.f;
; #pragma unroll
;                     for (int bj = 0; bj < 2; ++bj)
; #pragma unroll
;                         for (int n = 0; n < 2; ++n) ss += (v[bj][n].x * v[bj][n].x + v[bj][n].y * v[bj][n].y) + (v[bj][n].z * v[bj][n].z + v[bj][n].w * v[bj][n].w);
;                     ss += __shfl_xor(ss, 16); ss += __shfl_xor(ss, 32);
;                     const float rstd = rsqrtf(ss * (1.f / 64.f) + EPS);
; #pragma unroll
;                     for (int bj = 0; bj < 2; ++bj)
; #pragma unroll
;                         for (int n = 0; n < 2; ++n) v[bj][n] = v[bj][n] * rstd * gq[bj][n];
;                 }
;     ...
; #pragma unroll
;                 for (int bj = 0; bj < 2; ++bj)
; #pragma unroll
;                     for (int n = 0; n < 2; ++n) { const f32x4 o = v[bj][n] * scl; v2u pk; pk.x = pk2(o.x, o.y); pk.y = pk2(o.z, o.w);
;                         *(v2u*)(dst + 32 * bj + 16 * n + 4 * fq) = pk; }
.LBB0_319:
	v_pk_mul_f32 v[110:111], v[110:111], s[8:9] op_sel_hi:[1,0]
	v_pk_mul_f32 v[112:113], v[112:113], s[8:9] op_sel_hi:[1,0]
	v_pk_mul_f32 v[106:107], v[106:107], s[8:9] op_sel_hi:[1,0]
	v_pk_mul_f32 v[108:109], v[108:109], s[8:9] op_sel_hi:[1,0]
	v_pk_mul_f32 v[102:103], v[102:103], s[8:9] op_sel_hi:[1,0]
	v_pk_mul_f32 v[104:105], v[104:105], s[8:9] op_sel_hi:[1,0]
	v_pk_mul_f32 v[98:99], v[98:99], s[8:9] op_sel_hi:[1,0]
	v_pk_mul_f32 v[100:101], v[100:101], s[8:9] op_sel_hi:[1,0]
	v_lshl_add_u64 v[114:115], v[118:119], 0, v[150:151]
	v_cvt_pk_bf16_f32 v110, v110, v111
	v_cvt_pk_bf16_f32 v111, v112, v113
	v_cvt_pk_bf16_f32 v112, v106, v107
	v_cvt_pk_bf16_f32 v113, v108, v109
	v_cvt_pk_bf16_f32 v102, v102, v103
	v_cvt_pk_bf16_f32 v103, v104, v105
	v_cvt_pk_bf16_f32 v104, v98, v99
	v_cvt_pk_bf16_f32 v105, v100, v101
	s_nop 1
	v_permlane16_swap_b32_e32 v110, v112
	v_permlane16_swap_b32_e32 v111, v113
	v_permlane16_swap_b32_e32 v102, v104
	v_permlane16_swap_b32_e32 v103, v105
	s_and_b64 vcc, exec, s[4:5]
	global_store_dwordx4 v[114:115], v[110:113], off
	global_store_dwordx4 v[114:115], v[102:105], off offset:64
	s_nop 1
	s_cbranch_vccnz .LBB0_321
	v_pk_mul_f32 v[98:99], v[96:97], v[96:97]
	v_pk_mul_f32 v[100:101], v[94:95], v[94:95]
	s_nop 0
	v_pk_mov_b32 v[102:103], v[100:101], v[98:99] op_sel:[1,0]
	v_mov_b32_e32 v101, v99
	v_pk_add_f32 v[98:99], v[102:103], v[100:101]
	v_pk_mul_f32 v[100:101], v[92:93], v[92:93]
	v_pk_mul_f32 v[102:103], v[90:91], v[90:91]
	v_pk_add_f32 v[98:99], v[98:99], v[98:99] op_sel:[0,1] op_sel_hi:[1,0]
	v_pk_mov_b32 v[104:105], v[102:103], v[100:101] op_sel:[1,0]
	v_mov_b32_e32 v103, v101
	v_pk_add_f32 v[100:101], v[104:105], v[102:103]
	v_mul_f32_e32 v102, v82, v82
	v_mul_f32_e32 v103, v83, v83
	v_pk_add_f32 v[100:101], v[100:101], v[100:101] op_sel:[0,1] op_sel_hi:[1,0]
	v_mov_b32_e32 v99, v102
	v_mov_b32_e32 v101, v103
	v_pk_add_f32 v[98:99], v[98:99], v[100:101]
	v_mul_f32_e32 v100, v87, v87
	v_mul_f32_e32 v102, v89, v89
	v_mul_f32_e32 v104, v84, v84
	v_mul_f32_e32 v105, v85, v85
	v_pk_fma_f32 v[100:101], v[86:87], v[86:87], v[100:101] op_sel_hi:[1,1,0]
	v_pk_fma_f32 v[102:103], v[88:89], v[88:89], v[102:103] op_sel_hi:[1,1,0]
	v_mov_b32_e32 v101, v104
	v_mov_b32_e32 v103, v105
	v_pk_add_f32 v[100:101], v[100:101], v[102:103]
	s_nop 0
	v_pk_add_f32 v[98:99], v[98:99], v[100:101]
	v_and_b32_e32 v100, 64, v172
	v_add_f32_e32 v98, v98, v99
	v_xor_b32_e32 v99, 16, v172
	v_add_u32_e32 v100, 64, v100
	v_cmp_lt_i32_e32 vcc, v99, v100
	s_nop 1
	v_cndmask_b32_e32 v99, v172, v99, vcc
	v_lshlrev_b32_e32 v99, 2, v99
	ds_bpermute_b32 v99, v99, v98
	s_waitcnt lgkmcnt(0)
	v_add_f32_e32 v98, v98, v99
	v_xor_b32_e32 v99, 32, v172
	v_cmp_lt_i32_e32 vcc, v99, v100
	s_nop 1
	v_cndmask_b32_e32 v99, v172, v99, vcc
	v_lshlrev_b32_e32 v99, 2, v99
	ds_bpermute_b32 v99, v99, v98
	s_waitcnt lgkmcnt(0)
	v_add_f32_e32 v98, v98, v99
	v_fmamk_f32 v98, v98, 0x3c800000, v171
	v_mul_f32_e32 v99, 0x4b800000, v98
	v_cmp_gt_f32_e32 vcc, s10, v98
	s_nop 1
	v_cndmask_b32_e32 v98, v98, v99, vcc
	v_rsq_f32_e32 v98, v98
	s_nop 0
	v_mul_f32_e32 v99, 0x45800000, v98
	v_cndmask_b32_e32 v98, v98, v99, vcc
	v_pk_mul_f32 v[94:95], v[94:95], v[98:99] op_sel_hi:[1,0]
	v_pk_mul_f32 v[96:97], v[96:97], v[98:99] op_sel_hi:[1,0]
	v_pk_mul_f32 v[90:91], v[90:91], v[98:99] op_sel_hi:[1,0]
	v_pk_mul_f32 v[92:93], v[92:93], v[98:99] op_sel_hi:[1,0]
	v_pk_mul_f32 v[86:87], v[86:87], v[98:99] op_sel_hi:[1,0]
	v_pk_mul_f32 v[88:89], v[88:89], v[98:99] op_sel_hi:[1,0]
	v_pk_mul_f32 v[82:83], v[82:83], v[98:99] op_sel_hi:[1,0]
	v_pk_mul_f32 v[84:85], v[84:85], v[98:99] op_sel_hi:[1,0]
	v_pk_mul_f32 v[96:97], v[60:61], v[96:97]
	v_pk_mul_f32 v[94:95], v[58:59], v[94:95]
	v_pk_mul_f32 v[92:93], v[56:57], v[92:93]
	v_pk_mul_f32 v[90:91], v[54:55], v[90:91]
	v_pk_mul_f32 v[88:89], v[52:53], v[88:89]
	v_pk_mul_f32 v[86:87], v[50:51], v[86:87]
	v_pk_mul_f32 v[84:85], v[48:49], v[84:85]
	v_pk_mul_f32 v[82:83], v[46:47], v[82:83]
	s_and_b64 vcc, exec, s[6:7]
	v_add_u32_e32 v98, 0xffffff30, v162
	s_cbranch_vccnz .LBB0_323
	s_branch .LBB0_322

;     __device__ __forceinline__ void operator()(const pg8::f32x4 (&acc)[2][2][4][2], const pg8::Unit& u, int wr, int wc, int fr, int fq) const {
;     ...
;                 if (rope) {
; #pragma unroll
;                     for (int bj = 0; bj < 2; ++bj) {
;                         const f32x4 cs = *(const f32x4*)(tab + (size_t)l * 64 + 16 * bj + 4 * fq), sn = *(const f32x4*)(tab + (size_t)l * 64 + 32 + 16 * bj + 4 * fq);
;                         const f32x4 x0 = v[bj][0], x1 = v[bj][1];
;                         v[bj][0] = x0 * cs - x1 * sn; v[bj][1] = x1 * cs + x0 * sn;
;                     }
.LBB0_322:
	v_ashrrev_i32_e32 v99, 31, v98
	v_pk_mul_f32 v[108:109], v[92:93], v[196:197]
	v_pk_mul_f32 v[114:115], v[90:91], v[194:195]
	v_pk_fma_f32 v[110:111], v[96:97], v[192:193], v[108:109] neg_lo:[0,0,1] neg_hi:[0,0,1]
	v_pk_fma_f32 v[108:109], v[94:95], v[190:191], v[114:115] neg_lo:[0,0,1] neg_hi:[0,0,1]
	v_pk_mul_f32 v[96:97], v[96:97], v[196:197]
	v_pk_mul_f32 v[94:95], v[94:95], v[194:195]
	v_pk_fma_f32 v[92:93], v[92:93], v[192:193], v[96:97]
	v_pk_fma_f32 v[90:91], v[90:91], v[190:191], v[94:95]
	v_pk_mul_f32 v[104:105], v[84:85], v[236:237]
	v_pk_mul_f32 v[112:113], v[82:83], v[234:235]
	v_pk_fma_f32 v[106:107], v[88:89], v[232:233], v[104:105] neg_lo:[0,0,1] neg_hi:[0,0,1]
	v_pk_fma_f32 v[104:105], v[86:87], v[230:231], v[112:113] neg_lo:[0,0,1] neg_hi:[0,0,1]
	v_pk_mul_f32 v[88:89], v[88:89], v[236:237]
	v_pk_mul_f32 v[86:87], v[86:87], v[234:235]
	v_pk_fma_f32 v[84:85], v[84:85], v[232:233], v[88:89]
	v_pk_fma_f32 v[82:83], v[82:83], v[230:231], v[86:87]
	v_mov_b64_e32 v[86:87], v[104:105]
	v_mov_b64_e32 v[94:95], v[108:109]
	v_mov_b64_e32 v[88:89], v[106:107]
	v_mov_b64_e32 v[96:97], v[110:111]

; __device__ __forceinline__ unsigned pk2(float lo, float hi) { return f2bf(lo) | (f2bf(hi) << 16); }
;     __device__ __forceinline__ void operator()(const pg8::f32x4 (&acc)[2][2][4][2], const pg8::Unit& u, int wr, int wc, int fr, int fq) const {
;     ...
;                 if (grp == 4 || grp == 5) {
;                     float ss = 0.f;
; #pragma unroll
;                     for (int bj = 0; bj < 2; ++bj)
; #pragma unroll
;                         for (int n = 0; n < 2; ++n) ss += (v[bj][n].x * v[bj][n].x + v[bj][n].y * v[bj][n].y) + (v[bj][n].z * v[bj][n].z + v[bj][n].w * v[bj][n].w);
;                     ss += __shfl_xor(ss, 16); ss += __shfl_xor(ss, 32);
;                     const float rstd = rsqrtf(ss * (1.f / 64.f) + EPS);
; #pragma unroll
;                     for (int bj = 0; bj < 2; ++bj)
; #pragma unroll
;                         for (int n = 0; n < 2; ++n) v[bj][n] = v[bj][n] * rstd * gq[bj][n];
;                 }
;     ...
; #pragma unroll
;                 for (int bj = 0; bj < 2; ++bj)
; #pragma unroll
;                     for (int n = 0; n < 2; ++n) { const f32x4 o = v[bj][n] * scl; v2u pk; pk.x = pk2(o.x, o.y); pk.y = pk2(o.z, o.w);
;                         *(v2u*)(dst + 32 * bj + 16 * n + 4 * fq) = pk; }
.LBB0_346:
	v_pk_mul_f32 v[94:95], v[94:95], s[8:9] op_sel_hi:[1,0]
	v_pk_mul_f32 v[96:97], v[96:97], s[8:9] op_sel_hi:[1,0]
	v_pk_mul_f32 v[90:91], v[90:91], s[8:9] op_sel_hi:[1,0]
	v_pk_mul_f32 v[92:93], v[92:93], s[8:9] op_sel_hi:[1,0]
	v_pk_mul_f32 v[86:87], v[86:87], s[8:9] op_sel_hi:[1,0]
	v_pk_mul_f32 v[88:89], v[88:89], s[8:9] op_sel_hi:[1,0]
	v_pk_mul_f32 v[82:83], v[82:83], s[8:9] op_sel_hi:[1,0]
	v_pk_mul_f32 v[84:85], v[84:85], s[8:9] op_sel_hi:[1,0]
	v_lshl_add_u64 v[98:99], v[102:103], 0, v[150:151]
	v_cvt_pk_bf16_f32 v94, v94, v95
	v_cvt_pk_bf16_f32 v95, v96, v97
	v_cvt_pk_bf16_f32 v96, v90, v91
	v_cvt_pk_bf16_f32 v97, v92, v93
	v_cvt_pk_bf16_f32 v86, v86, v87
	v_cvt_pk_bf16_f32 v87, v88, v89
	v_cvt_pk_bf16_f32 v88, v82, v83
	v_cvt_pk_bf16_f32 v89, v84, v85
	s_nop 1
	v_permlane16_swap_b32_e32 v94, v96
	v_permlane16_swap_b32_e32 v95, v97
	v_permlane16_swap_b32_e32 v86, v88
	v_permlane16_swap_b32_e32 v87, v89
	s_and_b64 vcc, exec, s[4:5]
	global_store_dwordx4 v[98:99], v[94:97], off
	global_store_dwordx4 v[98:99], v[86:89], off offset:64
	s_nop 1
	s_cbranch_vccnz .LBB0_348
	v_pk_mul_f32 v[82:83], v[80:81], v[80:81]
	v_pk_mul_f32 v[84:85], v[78:79], v[78:79]
	s_nop 0
	v_pk_mov_b32 v[86:87], v[84:85], v[82:83] op_sel:[1,0]
	v_mov_b32_e32 v85, v83
	v_pk_add_f32 v[82:83], v[86:87], v[84:85]
	v_pk_mul_f32 v[84:85], v[76:77], v[76:77]
	v_pk_mul_f32 v[86:87], v[74:75], v[74:75]
	v_pk_add_f32 v[82:83], v[82:83], v[82:83] op_sel:[0,1] op_sel_hi:[1,0]
	v_pk_mov_b32 v[88:89], v[86:87], v[84:85] op_sel:[1,0]
	v_mov_b32_e32 v87, v85
	v_pk_add_f32 v[84:85], v[88:89], v[86:87]
	v_mul_f32_e32 v86, v66, v66
	v_mul_f32_e32 v87, v67, v67
	v_pk_add_f32 v[84:85], v[84:85], v[84:85] op_sel:[0,1] op_sel_hi:[1,0]
	v_mov_b32_e32 v83, v86
	v_mov_b32_e32 v85, v87
	v_pk_add_f32 v[82:83], v[82:83], v[84:85]
	v_mul_f32_e32 v84, v71, v71
	v_mul_f32_e32 v86, v73, v73
	v_mul_f32_e32 v88, v68, v68
	v_mul_f32_e32 v89, v69, v69
	v_pk_fma_f32 v[84:85], v[70:71], v[70:71], v[84:85] op_sel_hi:[1,1,0]
	v_pk_fma_f32 v[86:87], v[72:73], v[72:73], v[86:87] op_sel_hi:[1,1,0]
	v_mov_b32_e32 v85, v88
	v_mov_b32_e32 v87, v89
	v_pk_add_f32 v[84:85], v[84:85], v[86:87]
	s_nop 0
	v_pk_add_f32 v[82:83], v[82:83], v[84:85]
	v_and_b32_e32 v84, 64, v172
	v_add_f32_e32 v82, v82, v83
	v_xor_b32_e32 v83, 16, v172
	v_add_u32_e32 v84, 64, v84
	v_cmp_lt_i32_e32 vcc, v83, v84
	s_nop 1
	v_cndmask_b32_e32 v83, v172, v83, vcc
	v_lshlrev_b32_e32 v83, 2, v83
	ds_bpermute_b32 v83, v83, v82
	s_waitcnt lgkmcnt(0)
	v_add_f32_e32 v82, v82, v83
	v_xor_b32_e32 v83, 32, v172
	v_cmp_lt_i32_e32 vcc, v83, v84
	s_nop 1
	v_cndmask_b32_e32 v83, v172, v83, vcc
	v_lshlrev_b32_e32 v83, 2, v83
	ds_bpermute_b32 v83, v83, v82
	s_waitcnt lgkmcnt(0)
	v_add_f32_e32 v82, v82, v83
	v_fmamk_f32 v82, v82, 0x3c800000, v171
	v_mul_f32_e32 v83, 0x4b800000, v82
	v_cmp_gt_f32_e32 vcc, s10, v82
	s_nop 1
	v_cndmask_b32_e32 v82, v82, v83, vcc
	v_rsq_f32_e32 v82, v82
	s_nop 0
	v_mul_f32_e32 v83, 0x45800000, v82
	v_cndmask_b32_e32 v82, v82, v83, vcc
	v_pk_mul_f32 v[78:79], v[78:79], v[82:83] op_sel_hi:[1,0]
	v_pk_mul_f32 v[80:81], v[80:81], v[82:83] op_sel_hi:[1,0]
	v_pk_mul_f32 v[74:75], v[74:75], v[82:83] op_sel_hi:[1,0]
	v_pk_mul_f32 v[76:77], v[76:77], v[82:83] op_sel_hi:[1,0]
	v_pk_mul_f32 v[70:71], v[70:71], v[82:83] op_sel_hi:[1,0]
	v_pk_mul_f32 v[72:73], v[72:73], v[82:83] op_sel_hi:[1,0]
	v_pk_mul_f32 v[66:67], v[66:67], v[82:83] op_sel_hi:[1,0]
	v_pk_mul_f32 v[68:69], v[68:69], v[82:83] op_sel_hi:[1,0]
	v_pk_mul_f32 v[80:81], v[60:61], v[80:81]
	v_pk_mul_f32 v[78:79], v[58:59], v[78:79]
	v_pk_mul_f32 v[76:77], v[56:57], v[76:77]
	v_pk_mul_f32 v[74:75], v[54:55], v[74:75]
	v_pk_mul_f32 v[72:73], v[52:53], v[72:73]
	v_pk_mul_f32 v[70:71], v[50:51], v[70:71]
	v_pk_mul_f32 v[68:69], v[48:49], v[68:69]
	v_pk_mul_f32 v[66:67], v[46:47], v[66:67]
	s_and_b64 vcc, exec, s[6:7]
	v_add_u32_e32 v82, 0xffffff80, v162
	s_cbranch_vccnz .LBB0_350
	s_branch .LBB0_349

;     __device__ __forceinline__ void operator()(const pg8::f32x4 (&acc)[2][2][4][2], const pg8::Unit& u, int wr, int wc, int fr, int fq) const {
;     ...
;                 if (rope) {
; #pragma unroll
;                     for (int bj = 0; bj < 2; ++bj) {
;                         const f32x4 cs = *(const f32x4*)(tab + (size_t)l * 64 + 16 * bj + 4 * fq), sn = *(const f32x4*)(tab + (size_t)l * 64 + 32 + 16 * bj + 4 * fq);
;                         const f32x4 x0 = v[bj][0], x1 = v[bj][1];
;                         v[bj][0] = x0 * cs - x1 * sn; v[bj][1] = x1 * cs + x0 * sn;
;                     }
.LBB0_349:
	v_ashrrev_i32_e32 v83, 31, v82
	v_pk_mul_f32 v[92:93], v[76:77], v[204:205]
	v_pk_mul_f32 v[98:99], v[74:75], v[202:203]
	v_pk_fma_f32 v[94:95], v[80:81], v[200:201], v[92:93] neg_lo:[0,0,1] neg_hi:[0,0,1]
	v_pk_fma_f32 v[92:93], v[78:79], v[198:199], v[98:99] neg_lo:[0,0,1] neg_hi:[0,0,1]
	v_pk_mul_f32 v[80:81], v[80:81], v[204:205]
	v_pk_mul_f32 v[78:79], v[78:79], v[202:203]
	v_pk_fma_f32 v[76:77], v[76:77], v[200:201], v[80:81]
	v_pk_fma_f32 v[74:75], v[74:75], v[198:199], v[78:79]
	v_pk_mul_f32 v[88:89], v[68:69], v[212:213]
	v_pk_mul_f32 v[96:97], v[66:67], v[210:211]
	v_pk_fma_f32 v[90:91], v[72:73], v[208:209], v[88:89] neg_lo:[0,0,1] neg_hi:[0,0,1]
	v_pk_fma_f32 v[88:89], v[70:71], v[206:207], v[96:97] neg_lo:[0,0,1] neg_hi:[0,0,1]
	v_pk_mul_f32 v[72:73], v[72:73], v[212:213]
	v_pk_mul_f32 v[70:71], v[70:71], v[210:211]
	v_pk_fma_f32 v[68:69], v[68:69], v[208:209], v[72:73]
	v_pk_fma_f32 v[66:67], v[66:67], v[206:207], v[70:71]
	v_mov_b64_e32 v[70:71], v[88:89]
	v_mov_b64_e32 v[78:79], v[92:93]
	v_mov_b64_e32 v[72:73], v[90:91]
	v_mov_b64_e32 v[80:81], v[94:95]

; __device__ __forceinline__ unsigned pk2(float lo, float hi) { return f2bf(lo) | (f2bf(hi) << 16); }
;     __device__ __forceinline__ void operator()(const pg8::f32x4 (&acc)[2][2][4][2], const pg8::Unit& u, int wr, int wc, int fr, int fq) const {
;     ...
;                 if (grp == 4 || grp == 5) {
;                     float ss = 0.f;
; #pragma unroll
;                     for (int bj = 0; bj < 2; ++bj)
; #pragma unroll
;                         for (int n = 0; n < 2; ++n) ss += (v[bj][n].x * v[bj][n].x + v[bj][n].y * v[bj][n].y) + (v[bj][n].z * v[bj][n].z + v[bj][n].w * v[bj][n].w);
;                     ss += __shfl_xor(ss, 16); ss += __shfl_xor(ss, 32);
;                     const float rstd = rsqrtf(ss * (1.f / 64.f) + EPS);
; #pragma unroll
;                     for (int bj = 0; bj < 2; ++bj)
; #pragma unroll
;                         for (int n = 0; n < 2; ++n) v[bj][n] = v[bj][n] * rstd * gq[bj][n];
;                 }
;     ...
; #pragma unroll
;                 for (int bj = 0; bj < 2; ++bj)
; #pragma unroll
;                     for (int n = 0; n < 2; ++n) { const f32x4 o = v[bj][n] * scl; v2u pk; pk.x = pk2(o.x, o.y); pk.y = pk2(o.z, o.w);
;                         *(v2u*)(dst + 32 * bj + 16 * n + 4 * fq) = pk; }
.LBB0_373:
	v_pk_mul_f32 v[78:79], v[78:79], s[8:9] op_sel_hi:[1,0]
	v_pk_mul_f32 v[80:81], v[80:81], s[8:9] op_sel_hi:[1,0]
	v_pk_mul_f32 v[74:75], v[74:75], s[8:9] op_sel_hi:[1,0]
	v_pk_mul_f32 v[76:77], v[76:77], s[8:9] op_sel_hi:[1,0]
	v_pk_mul_f32 v[70:71], v[70:71], s[8:9] op_sel_hi:[1,0]
	v_pk_mul_f32 v[72:73], v[72:73], s[8:9] op_sel_hi:[1,0]
	v_pk_mul_f32 v[66:67], v[66:67], s[8:9] op_sel_hi:[1,0]
	v_pk_mul_f32 v[68:69], v[68:69], s[8:9] op_sel_hi:[1,0]
	v_lshl_add_u64 v[82:83], v[86:87], 0, v[150:151]
	v_cvt_pk_bf16_f32 v78, v78, v79
	v_cvt_pk_bf16_f32 v79, v80, v81
	v_cvt_pk_bf16_f32 v80, v74, v75
	v_cvt_pk_bf16_f32 v81, v76, v77
	v_cvt_pk_bf16_f32 v70, v70, v71
	v_cvt_pk_bf16_f32 v71, v72, v73
	v_cvt_pk_bf16_f32 v72, v66, v67
	v_cvt_pk_bf16_f32 v73, v68, v69
	s_nop 1
	v_permlane16_swap_b32_e32 v78, v80
	v_permlane16_swap_b32_e32 v79, v81
	v_permlane16_swap_b32_e32 v70, v72
	v_permlane16_swap_b32_e32 v71, v73
	s_and_b64 vcc, exec, s[4:5]
	global_store_dwordx4 v[82:83], v[78:81], off
	global_store_dwordx4 v[82:83], v[70:73], off offset:64
	s_nop 1
	s_cbranch_vccnz .LBB0_375
	v_pk_mul_f32 v[66:67], v[64:65], v[64:65]
	v_pk_mul_f32 v[68:69], v[62:63], v[62:63]
	s_nop 0
	v_pk_mov_b32 v[70:71], v[68:69], v[66:67] op_sel:[1,0]
	v_mov_b32_e32 v69, v67
	v_pk_add_f32 v[66:67], v[70:71], v[68:69]
	v_pk_mul_f32 v[68:69], v[44:45], v[44:45]
	v_pk_mul_f32 v[70:71], v[42:43], v[42:43]
	v_pk_add_f32 v[66:67], v[66:67], v[66:67] op_sel:[0,1] op_sel_hi:[1,0]
	v_pk_mov_b32 v[72:73], v[70:71], v[68:69] op_sel:[1,0]
	v_mov_b32_e32 v71, v69
	v_pk_add_f32 v[68:69], v[72:73], v[70:71]
	v_mul_f32_e32 v70, v34, v34
	v_mul_f32_e32 v71, v35, v35
	v_pk_add_f32 v[68:69], v[68:69], v[68:69] op_sel:[0,1] op_sel_hi:[1,0]
	v_mov_b32_e32 v67, v70
	v_mov_b32_e32 v69, v71
	v_pk_add_f32 v[66:67], v[66:67], v[68:69]
	v_mul_f32_e32 v68, v39, v39
	v_mul_f32_e32 v70, v41, v41
	v_mul_f32_e32 v72, v36, v36
	v_mul_f32_e32 v73, v37, v37
	v_pk_fma_f32 v[68:69], v[38:39], v[38:39], v[68:69] op_sel_hi:[1,1,0]
	v_pk_fma_f32 v[70:71], v[40:41], v[40:41], v[70:71] op_sel_hi:[1,1,0]
	v_mov_b32_e32 v69, v72
	v_mov_b32_e32 v71, v73
	v_pk_add_f32 v[68:69], v[68:69], v[70:71]
	s_nop 0
	v_pk_add_f32 v[66:67], v[66:67], v[68:69]
	v_and_b32_e32 v68, 64, v172
	v_add_f32_e32 v66, v66, v67
	v_xor_b32_e32 v67, 16, v172
	v_add_u32_e32 v68, 64, v68
	v_cmp_lt_i32_e32 vcc, v67, v68
	s_nop 1
	v_cndmask_b32_e32 v67, v172, v67, vcc
	v_lshlrev_b32_e32 v67, 2, v67
	ds_bpermute_b32 v67, v67, v66
	s_waitcnt lgkmcnt(0)
	v_add_f32_e32 v66, v66, v67
	v_xor_b32_e32 v67, 32, v172
	v_cmp_lt_i32_e32 vcc, v67, v68
	s_nop 1
	v_cndmask_b32_e32 v67, v172, v67, vcc
	v_lshlrev_b32_e32 v67, 2, v67
	ds_bpermute_b32 v67, v67, v66
	s_waitcnt lgkmcnt(0)
	v_add_f32_e32 v66, v66, v67
	v_fmamk_f32 v66, v66, 0x3c800000, v171
	v_mul_f32_e32 v67, 0x4b800000, v66
	v_cmp_gt_f32_e32 vcc, s10, v66
	s_nop 1
	v_cndmask_b32_e32 v66, v66, v67, vcc
	v_rsq_f32_e32 v66, v66
	s_nop 0
	v_mul_f32_e32 v67, 0x45800000, v66
	v_cndmask_b32_e32 v66, v66, v67, vcc
	v_pk_mul_f32 v[62:63], v[62:63], v[66:67] op_sel_hi:[1,0]
	v_pk_mul_f32 v[64:65], v[64:65], v[66:67] op_sel_hi:[1,0]
	v_pk_mul_f32 v[42:43], v[42:43], v[66:67] op_sel_hi:[1,0]
	v_pk_mul_f32 v[44:45], v[44:45], v[66:67] op_sel_hi:[1,0]
	v_pk_mul_f32 v[38:39], v[38:39], v[66:67] op_sel_hi:[1,0]
	v_pk_mul_f32 v[40:41], v[40:41], v[66:67] op_sel_hi:[1,0]
	v_pk_mul_f32 v[34:35], v[34:35], v[66:67] op_sel_hi:[1,0]
	v_pk_mul_f32 v[36:37], v[36:37], v[66:67] op_sel_hi:[1,0]
	v_pk_mul_f32 v[64:65], v[60:61], v[64:65]
	v_pk_mul_f32 v[62:63], v[58:59], v[62:63]
	v_pk_mul_f32 v[44:45], v[56:57], v[44:45]
	v_pk_mul_f32 v[42:43], v[54:55], v[42:43]
	v_pk_mul_f32 v[40:41], v[52:53], v[40:41]
	v_pk_mul_f32 v[38:39], v[50:51], v[38:39]
	v_pk_mul_f32 v[36:37], v[48:49], v[36:37]
	v_pk_mul_f32 v[34:35], v[46:47], v[34:35]
	s_and_b64 vcc, exec, s[6:7]
	v_add_u32_e32 v66, 0xffffff90, v162
	s_cbranch_vccnz .LBB0_377
	s_branch .LBB0_376

;     __device__ __forceinline__ void operator()(const pg8::f32x4 (&acc)[2][2][4][2], const pg8::Unit& u, int wr, int wc, int fr, int fq) const {
;     ...
;                 if (rope) {
; #pragma unroll
;                     for (int bj = 0; bj < 2; ++bj) {
;                         const f32x4 cs = *(const f32x4*)(tab + (size_t)l * 64 + 16 * bj + 4 * fq), sn = *(const f32x4*)(tab + (size_t)l * 64 + 32 + 16 * bj + 4 * fq);
;                         const f32x4 x0 = v[bj][0], x1 = v[bj][1];
;                         v[bj][0] = x0 * cs - x1 * sn; v[bj][1] = x1 * cs + x0 * sn;
;                     }
.LBB0_376:
	v_ashrrev_i32_e32 v67, 31, v66
	v_pk_mul_f32 v[76:77], v[44:45], v[204:205]
	v_pk_mul_f32 v[82:83], v[42:43], v[202:203]
	v_pk_fma_f32 v[78:79], v[64:65], v[200:201], v[76:77] neg_lo:[0,0,1] neg_hi:[0,0,1]
	v_pk_fma_f32 v[76:77], v[62:63], v[198:199], v[82:83] neg_lo:[0,0,1] neg_hi:[0,0,1]
	v_pk_mul_f32 v[64:65], v[64:65], v[204:205]
	v_pk_mul_f32 v[62:63], v[62:63], v[202:203]
	v_pk_fma_f32 v[44:45], v[44:45], v[200:201], v[64:65]
	v_pk_fma_f32 v[42:43], v[42:43], v[198:199], v[62:63]
	v_pk_mul_f32 v[72:73], v[36:37], v[220:221]
	v_pk_mul_f32 v[80:81], v[34:35], v[218:219]
	v_pk_fma_f32 v[74:75], v[40:41], v[216:217], v[72:73] neg_lo:[0,0,1] neg_hi:[0,0,1]
	v_pk_fma_f32 v[72:73], v[38:39], v[214:215], v[80:81] neg_lo:[0,0,1] neg_hi:[0,0,1]
	v_pk_mul_f32 v[40:41], v[40:41], v[220:221]
	v_pk_mul_f32 v[38:39], v[38:39], v[218:219]
	v_pk_fma_f32 v[36:37], v[36:37], v[216:217], v[40:41]
	v_pk_fma_f32 v[34:35], v[34:35], v[214:215], v[38:39]
	v_mov_b64_e32 v[38:39], v[72:73]
	v_mov_b64_e32 v[62:63], v[76:77]
	v_mov_b64_e32 v[40:41], v[74:75]
	v_mov_b64_e32 v[64:65], v[78:79]

; __device__ __forceinline__ unsigned pk2(float lo, float hi) { return f2bf(lo) | (f2bf(hi) << 16); }
;     __device__ __forceinline__ void operator()(const pg8::f32x4 (&acc)[2][2][4][2], const pg8::Unit& u, int wr, int wc, int fr, int fq) const {
;     ...
;                 if (grp == 4 || grp == 5) {
;                     float ss = 0.f;
; #pragma unroll
;                     for (int bj = 0; bj < 2; ++bj)
; #pragma unroll
;                         for (int n = 0; n < 2; ++n) ss += (v[bj][n].x * v[bj][n].x + v[bj][n].y * v[bj][n].y) + (v[bj][n].z * v[bj][n].z + v[bj][n].w * v[bj][n].w);
;                     ss += __shfl_xor(ss, 16); ss += __shfl_xor(ss, 32);
;                     const float rstd = rsqrtf(ss * (1.f / 64.f) + EPS);
; #pragma unroll
;                     for (int bj = 0; bj < 2; ++bj)
; #pragma unroll
;                         for (int n = 0; n < 2; ++n) v[bj][n] = v[bj][n] * rstd * gq[bj][n];
;                 }
;     ...
; #pragma unroll
;                 for (int bj = 0; bj < 2; ++bj)
; #pragma unroll
;                     for (int n = 0; n < 2; ++n) { const f32x4 o = v[bj][n] * scl; v2u pk; pk.x = pk2(o.x, o.y); pk.y = pk2(o.z, o.w);
;                         *(v2u*)(dst + 32 * bj + 16 * n + 4 * fq) = pk; }
.LBB0_400:
	v_pk_mul_f32 v[62:63], v[62:63], s[8:9] op_sel_hi:[1,0]
	v_pk_mul_f32 v[64:65], v[64:65], s[8:9] op_sel_hi:[1,0]
	v_pk_mul_f32 v[42:43], v[42:43], s[8:9] op_sel_hi:[1,0]
	v_pk_mul_f32 v[44:45], v[44:45], s[8:9] op_sel_hi:[1,0]
	v_pk_mul_f32 v[38:39], v[38:39], s[8:9] op_sel_hi:[1,0]
	v_pk_mul_f32 v[40:41], v[40:41], s[8:9] op_sel_hi:[1,0]
	v_pk_mul_f32 v[34:35], v[34:35], s[8:9] op_sel_hi:[1,0]
	v_pk_mul_f32 v[36:37], v[36:37], s[8:9] op_sel_hi:[1,0]
	v_lshl_add_u64 v[66:67], v[70:71], 0, v[150:151]
	v_cvt_pk_bf16_f32 v62, v62, v63
	v_cvt_pk_bf16_f32 v63, v64, v65
	v_cvt_pk_bf16_f32 v64, v42, v43
	v_cvt_pk_bf16_f32 v65, v44, v45
	v_cvt_pk_bf16_f32 v38, v38, v39
	v_cvt_pk_bf16_f32 v39, v40, v41
	v_cvt_pk_bf16_f32 v40, v34, v35
	v_cvt_pk_bf16_f32 v41, v36, v37
	s_nop 1
	v_permlane16_swap_b32_e32 v62, v64
	v_permlane16_swap_b32_e32 v63, v65
	v_permlane16_swap_b32_e32 v38, v40
	v_permlane16_swap_b32_e32 v39, v41
	s_and_b64 vcc, exec, s[4:5]
	global_store_dwordx4 v[66:67], v[62:65], off
	global_store_dwordx4 v[66:67], v[38:41], off offset:64
	s_nop 1
	s_cbranch_vccnz .LBB0_402
	v_pk_mul_f32 v[34:35], v[32:33], v[32:33]
	v_pk_mul_f32 v[36:37], v[30:31], v[30:31]
	s_nop 0
	v_pk_mov_b32 v[38:39], v[36:37], v[34:35] op_sel:[1,0]
	v_mov_b32_e32 v37, v35
	v_pk_add_f32 v[34:35], v[38:39], v[36:37]
	v_pk_mul_f32 v[36:37], v[28:29], v[28:29]
	v_pk_mul_f32 v[38:39], v[26:27], v[26:27]
	v_pk_add_f32 v[34:35], v[34:35], v[34:35] op_sel:[0,1] op_sel_hi:[1,0]
	v_pk_mov_b32 v[40:41], v[38:39], v[36:37] op_sel:[1,0]
	v_mov_b32_e32 v39, v37
	v_pk_add_f32 v[36:37], v[40:41], v[38:39]
	v_mul_f32_e32 v38, v18, v18
	v_mul_f32_e32 v39, v19, v19
	v_pk_add_f32 v[36:37], v[36:37], v[36:37] op_sel:[0,1] op_sel_hi:[1,0]
	v_mov_b32_e32 v35, v38
	v_mov_b32_e32 v37, v39
	v_pk_add_f32 v[34:35], v[34:35], v[36:37]
	v_mul_f32_e32 v36, v23, v23
	v_mul_f32_e32 v38, v25, v25
	v_mul_f32_e32 v40, v20, v20
	v_mul_f32_e32 v41, v21, v21
	v_pk_fma_f32 v[36:37], v[22:23], v[22:23], v[36:37] op_sel_hi:[1,1,0]
	v_pk_fma_f32 v[38:39], v[24:25], v[24:25], v[38:39] op_sel_hi:[1,1,0]
	v_mov_b32_e32 v37, v40
	v_mov_b32_e32 v39, v41
	v_pk_add_f32 v[36:37], v[36:37], v[38:39]
	s_nop 0
	v_pk_add_f32 v[34:35], v[34:35], v[36:37]
	v_and_b32_e32 v36, 64, v172
	v_add_f32_e32 v34, v34, v35
	v_xor_b32_e32 v35, 16, v172
	v_add_u32_e32 v36, 64, v36
	v_cmp_lt_i32_e32 vcc, v35, v36
	s_nop 1
	v_cndmask_b32_e32 v35, v172, v35, vcc
	v_lshlrev_b32_e32 v35, 2, v35
	ds_bpermute_b32 v35, v35, v34
	s_waitcnt lgkmcnt(0)
	v_add_f32_e32 v34, v34, v35
	v_xor_b32_e32 v35, 32, v172
	v_cmp_lt_i32_e32 vcc, v35, v36
	s_nop 1
	v_cndmask_b32_e32 v35, v172, v35, vcc
	v_lshlrev_b32_e32 v35, 2, v35
	ds_bpermute_b32 v35, v35, v34
	s_waitcnt lgkmcnt(0)
	v_add_f32_e32 v34, v34, v35
	v_fmamk_f32 v34, v34, 0x3c800000, v171
	v_mul_f32_e32 v35, 0x4b800000, v34
	v_cmp_gt_f32_e32 vcc, s10, v34
	s_nop 1
	v_cndmask_b32_e32 v34, v34, v35, vcc
	v_rsq_f32_e32 v34, v34
	s_nop 0
	v_mul_f32_e32 v35, 0x45800000, v34
	v_cndmask_b32_e32 v34, v34, v35, vcc
	v_pk_mul_f32 v[30:31], v[30:31], v[34:35] op_sel_hi:[1,0]
	v_pk_mul_f32 v[32:33], v[32:33], v[34:35] op_sel_hi:[1,0]
	v_pk_mul_f32 v[26:27], v[26:27], v[34:35] op_sel_hi:[1,0]
	v_pk_mul_f32 v[28:29], v[28:29], v[34:35] op_sel_hi:[1,0]
	v_pk_mul_f32 v[22:23], v[22:23], v[34:35] op_sel_hi:[1,0]
	v_pk_mul_f32 v[24:25], v[24:25], v[34:35] op_sel_hi:[1,0]
	v_pk_mul_f32 v[18:19], v[18:19], v[34:35] op_sel_hi:[1,0]
	v_pk_mul_f32 v[20:21], v[20:21], v[34:35] op_sel_hi:[1,0]
	v_pk_mul_f32 v[32:33], v[60:61], v[32:33]
	v_pk_mul_f32 v[30:31], v[58:59], v[30:31]
	v_pk_mul_f32 v[28:29], v[56:57], v[28:29]
	v_pk_mul_f32 v[26:27], v[54:55], v[26:27]
	v_pk_mul_f32 v[24:25], v[52:53], v[24:25]
	v_pk_mul_f32 v[22:23], v[50:51], v[22:23]
	v_pk_mul_f32 v[20:21], v[48:49], v[20:21]
	v_pk_mul_f32 v[18:19], v[46:47], v[18:19]
	s_and_b64 vcc, exec, s[6:7]
	v_add_u32_e32 v34, 0xffffffa0, v162
	s_cbranch_vccnz .LBB0_404
	s_branch .LBB0_403

;     __device__ __forceinline__ void operator()(const pg8::f32x4 (&acc)[2][2][4][2], const pg8::Unit& u, int wr, int wc, int fr, int fq) const {
;     ...
;                 if (rope) {
; #pragma unroll
;                     for (int bj = 0; bj < 2; ++bj) {
;                         const f32x4 cs = *(const f32x4*)(tab + (size_t)l * 64 + 16 * bj + 4 * fq), sn = *(const f32x4*)(tab + (size_t)l * 64 + 32 + 16 * bj + 4 * fq);
;                         const f32x4 x0 = v[bj][0], x1 = v[bj][1];
;                         v[bj][0] = x0 * cs - x1 * sn; v[bj][1] = x1 * cs + x0 * sn;
;                     }
.LBB0_403:
	v_ashrrev_i32_e32 v35, 31, v34
	v_pk_mul_f32 v[62:63], v[28:29], v[204:205]
	v_pk_mul_f32 v[66:67], v[26:27], v[202:203]
	v_pk_fma_f32 v[64:65], v[32:33], v[200:201], v[62:63] neg_lo:[0,0,1] neg_hi:[0,0,1]
	v_pk_fma_f32 v[62:63], v[30:31], v[198:199], v[66:67] neg_lo:[0,0,1] neg_hi:[0,0,1]
	v_pk_mul_f32 v[32:33], v[32:33], v[204:205]
	v_pk_mul_f32 v[30:31], v[30:31], v[202:203]
	v_pk_fma_f32 v[28:29], v[28:29], v[200:201], v[32:33]
	v_pk_fma_f32 v[26:27], v[26:27], v[198:199], v[30:31]
	v_pk_mul_f32 v[40:41], v[20:21], v[228:229]
	v_pk_mul_f32 v[44:45], v[18:19], v[226:227]
	v_pk_fma_f32 v[42:43], v[24:25], v[224:225], v[40:41] neg_lo:[0,0,1] neg_hi:[0,0,1]
	v_pk_fma_f32 v[40:41], v[22:23], v[222:223], v[44:45] neg_lo:[0,0,1] neg_hi:[0,0,1]
	v_pk_mul_f32 v[24:25], v[24:25], v[228:229]
	v_pk_mul_f32 v[22:23], v[22:23], v[226:227]
	v_pk_fma_f32 v[20:21], v[20:21], v[224:225], v[24:25]
	v_pk_fma_f32 v[18:19], v[18:19], v[222:223], v[22:23]
	v_mov_b64_e32 v[22:23], v[40:41]
	v_mov_b64_e32 v[30:31], v[62:63]
	v_mov_b64_e32 v[24:25], v[42:43]
	v_mov_b64_e32 v[32:33], v[64:65]

; __device__ __forceinline__ unsigned pk2(float lo, float hi) { return f2bf(lo) | (f2bf(hi) << 16); }
;     __device__ __forceinline__ void operator()(const pg8::f32x4 (&acc)[2][2][4][2], const pg8::Unit& u, int wr, int wc, int fr, int fq) const {
;     ...
;                 if (grp == 4 || grp == 5) {
;                     float ss = 0.f;
; #pragma unroll
;                     for (int bj = 0; bj < 2; ++bj)
; #pragma unroll
;                         for (int n = 0; n < 2; ++n) ss += (v[bj][n].x * v[bj][n].x + v[bj][n].y * v[bj][n].y) + (v[bj][n].z * v[bj][n].z + v[bj][n].w * v[bj][n].w);
;                     ss += __shfl_xor(ss, 16); ss += __shfl_xor(ss, 32);
;                     const float rstd = rsqrtf(ss * (1.f / 64.f) + EPS);
; #pragma unroll
;                     for (int bj = 0; bj < 2; ++bj)
; #pragma unroll
;                         for (int n = 0; n < 2; ++n) v[bj][n] = v[bj][n] * rstd * gq[bj][n];
;                 }
;     ...
; #pragma unroll
;                 for (int bj = 0; bj < 2; ++bj)
; #pragma unroll
;                     for (int n = 0; n < 2; ++n) { const f32x4 o = v[bj][n] * scl; v2u pk; pk.x = pk2(o.x, o.y); pk.y = pk2(o.z, o.w);
;                         *(v2u*)(dst + 32 * bj + 16 * n + 4 * fq) = pk; }
.LBB0_427:
	v_pk_mul_f32 v[30:31], v[30:31], s[8:9] op_sel_hi:[1,0]
	v_pk_mul_f32 v[32:33], v[32:33], s[8:9] op_sel_hi:[1,0]
	v_pk_mul_f32 v[26:27], v[26:27], s[8:9] op_sel_hi:[1,0]
	v_pk_mul_f32 v[28:29], v[28:29], s[8:9] op_sel_hi:[1,0]
	v_pk_mul_f32 v[22:23], v[22:23], s[8:9] op_sel_hi:[1,0]
	v_pk_mul_f32 v[24:25], v[24:25], s[8:9] op_sel_hi:[1,0]
	v_pk_mul_f32 v[18:19], v[18:19], s[8:9] op_sel_hi:[1,0]
	v_pk_mul_f32 v[20:21], v[20:21], s[8:9] op_sel_hi:[1,0]
	v_lshl_add_u64 v[34:35], v[38:39], 0, v[150:151]
	v_cvt_pk_bf16_f32 v30, v30, v31
	v_cvt_pk_bf16_f32 v31, v32, v33
	v_cvt_pk_bf16_f32 v32, v26, v27
	v_cvt_pk_bf16_f32 v33, v28, v29
	v_cvt_pk_bf16_f32 v22, v22, v23
	v_cvt_pk_bf16_f32 v23, v24, v25
	v_cvt_pk_bf16_f32 v24, v18, v19
	v_cvt_pk_bf16_f32 v25, v20, v21
	s_nop 1
	v_permlane16_swap_b32_e32 v30, v32
	v_permlane16_swap_b32_e32 v31, v33
	v_permlane16_swap_b32_e32 v22, v24
	v_permlane16_swap_b32_e32 v23, v25
	s_and_b64 vcc, exec, s[4:5]
	global_store_dwordx4 v[34:35], v[30:33], off
	global_store_dwordx4 v[34:35], v[22:25], off offset:64
	s_nop 1
	s_cbranch_vccnz .LBB0_429
	v_pk_mul_f32 v[18:19], v[16:17], v[16:17]
	v_pk_mul_f32 v[20:21], v[14:15], v[14:15]
	s_nop 0
	v_pk_mov_b32 v[22:23], v[20:21], v[18:19] op_sel:[1,0]
	v_mov_b32_e32 v21, v19
	v_pk_add_f32 v[18:19], v[22:23], v[20:21]
	v_pk_mul_f32 v[20:21], v[12:13], v[12:13]
	v_pk_mul_f32 v[22:23], v[10:11], v[10:11]
	v_pk_add_f32 v[18:19], v[18:19], v[18:19] op_sel:[0,1] op_sel_hi:[1,0]
	v_pk_mov_b32 v[24:25], v[22:23], v[20:21] op_sel:[1,0]
	v_mov_b32_e32 v23, v21
	v_pk_add_f32 v[20:21], v[24:25], v[22:23]
	v_mul_f32_e32 v22, v2, v2
	v_mul_f32_e32 v23, v3, v3
	v_pk_add_f32 v[20:21], v[20:21], v[20:21] op_sel:[0,1] op_sel_hi:[1,0]
	v_mov_b32_e32 v19, v22
	v_mov_b32_e32 v21, v23
	v_pk_add_f32 v[18:19], v[18:19], v[20:21]
	v_mul_f32_e32 v20, v7, v7
	v_mul_f32_e32 v22, v9, v9
	v_mul_f32_e32 v24, v4, v4
	v_mul_f32_e32 v25, v5, v5
	v_pk_fma_f32 v[20:21], v[6:7], v[6:7], v[20:21] op_sel_hi:[1,1,0]
	v_pk_fma_f32 v[22:23], v[8:9], v[8:9], v[22:23] op_sel_hi:[1,1,0]
	v_mov_b32_e32 v21, v24
	v_mov_b32_e32 v23, v25
	v_pk_add_f32 v[20:21], v[20:21], v[22:23]
	s_nop 0
	v_pk_add_f32 v[18:19], v[18:19], v[20:21]
	v_and_b32_e32 v20, 64, v172
	v_add_f32_e32 v18, v18, v19
	v_xor_b32_e32 v19, 16, v172
	v_add_u32_e32 v20, 64, v20
	v_cmp_lt_i32_e32 vcc, v19, v20
	s_nop 1
	v_cndmask_b32_e32 v19, v172, v19, vcc
	v_lshlrev_b32_e32 v19, 2, v19
	ds_bpermute_b32 v19, v19, v18
	s_waitcnt lgkmcnt(0)
	v_add_f32_e32 v18, v18, v19
	v_xor_b32_e32 v19, 32, v172
	v_cmp_lt_i32_e32 vcc, v19, v20
	s_nop 1
	v_cndmask_b32_e32 v19, v172, v19, vcc
	v_lshlrev_b32_e32 v19, 2, v19
	ds_bpermute_b32 v19, v19, v18
	s_waitcnt lgkmcnt(0)
	v_add_f32_e32 v18, v18, v19
	v_fmamk_f32 v18, v18, 0x3c800000, v171
	v_mul_f32_e32 v19, 0x4b800000, v18
	v_cmp_gt_f32_e32 vcc, s10, v18
	s_nop 1
	v_cndmask_b32_e32 v18, v18, v19, vcc
	v_rsq_f32_e32 v18, v18
	s_nop 0
	v_mul_f32_e32 v19, 0x45800000, v18
	v_cndmask_b32_e32 v18, v18, v19, vcc
	v_pk_mul_f32 v[14:15], v[14:15], v[18:19] op_sel_hi:[1,0]
	v_pk_mul_f32 v[16:17], v[16:17], v[18:19] op_sel_hi:[1,0]
	v_pk_mul_f32 v[10:11], v[10:11], v[18:19] op_sel_hi:[1,0]
	v_pk_mul_f32 v[12:13], v[12:13], v[18:19] op_sel_hi:[1,0]
	v_pk_mul_f32 v[6:7], v[6:7], v[18:19] op_sel_hi:[1,0]
	v_pk_mul_f32 v[8:9], v[8:9], v[18:19] op_sel_hi:[1,0]
	v_pk_mul_f32 v[2:3], v[2:3], v[18:19] op_sel_hi:[1,0]
	v_pk_mul_f32 v[4:5], v[4:5], v[18:19] op_sel_hi:[1,0]
	v_pk_mul_f32 v[16:17], v[60:61], v[16:17]
	v_pk_mul_f32 v[14:15], v[58:59], v[14:15]
	v_pk_mul_f32 v[12:13], v[56:57], v[12:13]
	v_pk_mul_f32 v[10:11], v[54:55], v[10:11]
	v_pk_mul_f32 v[8:9], v[52:53], v[8:9]
	v_pk_mul_f32 v[6:7], v[50:51], v[6:7]
	v_pk_mul_f32 v[4:5], v[48:49], v[4:5]
	v_pk_mul_f32 v[2:3], v[46:47], v[2:3]
	s_and_b64 vcc, exec, s[6:7]
	v_add_u32_e32 v18, 0xffffffb0, v162
	s_cbranch_vccnz .LBB0_431
	s_branch .LBB0_430

;     __device__ __forceinline__ void operator()(const pg8::f32x4 (&acc)[2][2][4][2], const pg8::Unit& u, int wr, int wc, int fr, int fq) const {
;     ...
;                 if (rope) {
; #pragma unroll
;                     for (int bj = 0; bj < 2; ++bj) {
;                         const f32x4 cs = *(const f32x4*)(tab + (size_t)l * 64 + 16 * bj + 4 * fq), sn = *(const f32x4*)(tab + (size_t)l * 64 + 32 + 16 * bj + 4 * fq);
;                         const f32x4 x0 = v[bj][0], x1 = v[bj][1];
;                         v[bj][0] = x0 * cs - x1 * sn; v[bj][1] = x1 * cs + x0 * sn;
;                     }
.LBB0_430:
	v_ashrrev_i32_e32 v19, 31, v18
	v_pk_mul_f32 v[28:29], v[12:13], v[204:205]
	v_pk_mul_f32 v[34:35], v[10:11], v[202:203]
	v_pk_fma_f32 v[30:31], v[16:17], v[200:201], v[28:29] neg_lo:[0,0,1] neg_hi:[0,0,1]
	v_pk_fma_f32 v[28:29], v[14:15], v[198:199], v[34:35] neg_lo:[0,0,1] neg_hi:[0,0,1]
	v_pk_mul_f32 v[16:17], v[16:17], v[204:205]
	v_pk_mul_f32 v[14:15], v[14:15], v[202:203]
	v_pk_fma_f32 v[12:13], v[12:13], v[200:201], v[16:17]
	v_pk_fma_f32 v[10:11], v[10:11], v[198:199], v[14:15]
	v_pk_mul_f32 v[24:25], v[4:5], v[236:237]
	v_pk_mul_f32 v[32:33], v[2:3], v[234:235]
	v_pk_fma_f32 v[26:27], v[8:9], v[232:233], v[24:25] neg_lo:[0,0,1] neg_hi:[0,0,1]
	v_pk_fma_f32 v[24:25], v[6:7], v[230:231], v[32:33] neg_lo:[0,0,1] neg_hi:[0,0,1]
	v_pk_mul_f32 v[8:9], v[8:9], v[236:237]
	v_pk_mul_f32 v[6:7], v[6:7], v[234:235]
	v_pk_fma_f32 v[4:5], v[4:5], v[232:233], v[8:9]
	v_pk_fma_f32 v[2:3], v[2:3], v[230:231], v[6:7]
	v_mov_b64_e32 v[6:7], v[24:25]
	v_mov_b64_e32 v[14:15], v[28:29]
	v_mov_b64_e32 v[8:9], v[26:27]
	v_mov_b64_e32 v[16:17], v[30:31]

; __device__ __forceinline__ unsigned pk2(float lo, float hi) { return f2bf(lo) | (f2bf(hi) << 16); }
; #define PG8_BAR __builtin_amdgcn_s_barrier()
; template <class Epi, class Sched, bool ALIGN_EPI = false, bool SP2 = false>
; __device__ __forceinline__ void gemm_phase(PG8_LAS unsigned char* lds, const Gemm g, const Sched& S, const Epi& E) {
;     ...
;         if constexpr (!Epi::AFTER_DRAIN) { E(acc, cur, wr, wc, fr, fq); S.done(cur); }
;         if (!has_next) break;
; #pragma unroll
;         for (int a = 0; a < 2; ++a)
; #pragma unroll
;             for (int b = 0; b < 2; ++b)
; #pragma unroll
;                 for (int m = 0; m < 4; ++m)
; #pragma unroll
;                     for (int n = 0; n < 2; ++n) acc[a][b][m][n] = (f32x4){0.f, 0.f, 0.f, 0.f};
;         cur = nxt; cA = nA; cB = nB; ++ui;
;         if constexpr (ALIGN_EPI) { if (wr == 1) PG8_BAR; }
;     }
;     __device__ __forceinline__ void operator()(const pg8::f32x4 (&acc)[2][2][4][2], const pg8::Unit& u, int wr, int wc, int fr, int fq) const {
;     ...
; #pragma unroll
;                 for (int bj = 0; bj < 2; ++bj)
; #pragma unroll
;                     for (int n = 0; n < 2; ++n) { const f32x4 o = v[bj][n] * scl; v2u pk; pk.x = pk2(o.x, o.y); pk.y = pk2(o.z, o.w);
;                         *(v2u*)(dst + 32 * bj + 16 * n + 4 * fq) = pk; }
.LBB0_454:
	v_pk_mul_f32 v[14:15], v[14:15], s[4:5] op_sel_hi:[1,0]
	v_pk_mul_f32 v[16:17], v[16:17], s[4:5] op_sel_hi:[1,0]
	v_pk_mul_f32 v[10:11], v[10:11], s[4:5] op_sel_hi:[1,0]
	v_pk_mul_f32 v[12:13], v[12:13], s[4:5] op_sel_hi:[1,0]
	v_pk_mul_f32 v[6:7], v[6:7], s[4:5] op_sel_hi:[1,0]
	v_pk_mul_f32 v[8:9], v[8:9], s[4:5] op_sel_hi:[1,0]
	v_pk_mul_f32 v[2:3], v[2:3], s[4:5] op_sel_hi:[1,0]
	v_pk_mul_f32 v[4:5], v[4:5], s[4:5] op_sel_hi:[1,0]
	v_lshl_add_u64 v[18:19], v[22:23], 0, v[150:151]
	v_cvt_pk_bf16_f32 v14, v14, v15
	v_cvt_pk_bf16_f32 v15, v16, v17
	v_cvt_pk_bf16_f32 v16, v10, v11
	v_cvt_pk_bf16_f32 v17, v12, v13
	v_cvt_pk_bf16_f32 v6, v6, v7
	v_cvt_pk_bf16_f32 v7, v8, v9
	v_cvt_pk_bf16_f32 v8, v2, v3
	v_cvt_pk_bf16_f32 v9, v4, v5
	s_nop 1
	v_permlane16_swap_b32_e32 v14, v16
	v_permlane16_swap_b32_e32 v15, v17
	v_permlane16_swap_b32_e32 v6, v8
	v_permlane16_swap_b32_e32 v7, v9
	s_andn2_b64 vcc, exec, s[12:13]
	s_mov_b64 s[4:5], -1
	global_store_dwordx4 v[18:19], v[14:17], off
	global_store_dwordx4 v[18:19], v[6:9], off offset:64
	s_nop 1
	s_cbranch_vccnz .LBB0_227
	v_readlane_b32 s4, v240, 24
	v_readlane_b32 s5, v240, 25
	s_andn2_b64 vcc, exec, s[4:5]
	s_cbranch_vccnz .LBB0_226
	s_barrier
	s_branch .LBB0_226

; __device__ __forceinline__ void cvt_row_fp4(const float* __restrict__ src, unsigned char* __restrict__ T4, float* __restrict__ inv_scale, int e, int lane) {
;     f32x4 v[4]; float am = 0.f;
; #pragma unroll
;     for (int j = 0; j < 4; ++j) { v[j] = *(const f32x4*)(src + (size_t)e * 1024 + 16 * lane + 4 * j);
; __global__ void __launch_bounds__(NTHR, 2) mega(Args args) {
;     ...
;         {
;             const int nslots = G >> 3, rr = 103 % nslots, xcd = (int)blockIdx.x & 7, slot = (int)blockIdx.x >> 3;
;             const bool freewg = rr == 0 || slot >= rr;
;             const int fidx = rr == 0 ? (int)blockIdx.x : (slot - rr) * 8 + xcd, nfree = rr == 0 ? G : (nslots - rr) * 8;
;             if (freewg && rep == 0)
;                 for (int e = fidx * NWAVES + wave; e < 2 * 16384 - CVT_LATE; e += nfree * NWAVES) { if (e < 16384) peer::cvt_row_i4(pu, UT8, SUs, e, lane); else peer::cvt_row_fp4(pv, VT8, SVs, e - 16384, lane); }
.LBB0_458:
	s_ashr_i32 s1, s18, 3
	s_abs_i32 s3, s1
	v_cvt_f32_u32_e32 v1, s3
	s_sub_i32 s4, 0, s3
	s_ashr_i32 s0, s2, 3
	v_rcp_iflag_f32_e32 v1, v1
	s_nop 0
	v_mul_f32_e32 v1, 0x4f7ffffe, v1
	v_cvt_u32_f32_e32 v1, v1
	s_nop 0
	v_readfirstlane_b32 s5, v1
	s_mul_i32 s4, s4, s5
	s_mul_hi_u32 s4, s5, s4
	s_add_i32 s5, s5, s4
	s_mul_hi_u32 s4, s5, 0x67
	s_mul_i32 s4, s4, s3
	s_sub_i32 s4, 0x67, s4
	s_sub_i32 s5, s4, s3
	s_cmp_ge_u32 s4, s3
	s_cselect_b32 s4, s5, s4
	s_sub_i32 s5, s4, s3
	s_cmp_ge_u32 s4, s3
	s_cselect_b32 s6, s5, s4
	s_cmp_eq_u32 s6, 0
	s_cselect_b64 s[4:5], -1, 0
	s_cmp_lg_u32 s6, 0
	s_cselect_b64 s[8:9], -1, 0
	s_cmp_lt_i32 s0, s6
	s_cselect_b64 s[10:11], -1, 0
	s_and_b64 s[8:9], s[8:9], s[10:11]
	s_and_b64 vcc, exec, s[8:9]
	s_cbranch_vccnz .LBB0_472
	s_sub_i32 s0, s0, s6
	s_and_b32 s3, s2, 7
	s_lshl_b32 s0, s0, 3
	s_or_b32 s0, s0, s3
	s_and_b64 s[8:9], s[4:5], exec
	s_cselect_b32 s0, s2, s0
	s_lshl_b32 s3, s0, 3
	s_add_i32 s0, s3, s77
	s_cmpk_gt_i32 s0, 0x6aff
	s_cbranch_scc1 .LBB0_472
	s_sub_i32 s1, s1, s6
	s_lshl_b32 s1, s1, 3
	s_and_b64 s[4:5], s[4:5], exec
	s_cselect_b32 s1, s18, s1
	s_lshl_b32 s10, s1, 3
	s_ashr_i32 s1, s3, 31
	s_add_u32 s34, s77, s3
	v_and_b32_e32 v1, 1, v0
	s_addc_u32 s35, 0, s1
	v_mov_b32_e32 v3, 0
	v_cmp_eq_u32_e64 s[4:5], 0, v1
	v_lshlrev_b32_e32 v1, 10, v0
	s_lshl_b64 s[12:13], s[34:35], 2
	v_and_b32_e32 v6, 0xc000, v1
	v_mov_b32_e32 v7, v3
	s_add_u32 s1, s30, s12
	s_addc_u32 s3, s31, s13
	v_lshl_add_u64 v[10:11], s[34:35], 0, v[6:7]
	v_lshlrev_b32_e32 v1, 3, v0
	s_add_u32 s12, s1, 0x3000000
	v_lshlrev_b64 v[10:11], 7, v[10:11]
	s_movk_i32 s1, 0x78
	v_and_or_b32 v10, v1, s1, v10
	s_addc_u32 s13, s3, 0
	s_ashr_i32 s11, s10, 31
	v_lshl_add_u64 v[10:11], s[30:31], 0, v[10:11]
	s_mov_b64 s[16:17], 0x1000000
	s_lshl_b64 s[14:15], s[10:11], 2
	v_lshl_add_u64 v[10:11], v[10:11], 0, s[16:17]
	s_lshl_b64 s[16:17], s[10:11], 7
	s_lshl_b64 s[34:35], s[34:35], 12
	v_and_b32_e32 v8, 0x70, v1
	s_mov_b64 s[82:83], s[22:23]
	s_add_u32 s22, s22, s34
	v_mbcnt_lo_u32_b32 v1, -1, 0
	v_lshlrev_b32_e32 v2, 6, v178
	s_addc_u32 s23, s23, s35
	v_mbcnt_hi_u32_b32 v1, -1, v1
	v_lshl_add_u64 v[4:5], s[24:25], 0, v[2:3]
	v_mov_b32_e32 v9, v3
	v_lshl_add_u64 v[12:13], s[22:23], 0, v[2:3]
	v_and_b32_e32 v2, 64, v1
	s_mov_b32 s9, 0
	v_lshl_add_u64 v[8:9], s[20:21], 0, v[8:9]
	v_cmp_eq_u32_e64 s[6:7], 0, v178
	v_lshl_add_u64 v[12:13], v[12:13], 0, 32
	s_lshl_b64 s[22:23], s[10:11], 12
	s_mov_b32 s1, 0x40e00000
	s_movk_i32 s3, 0xf0
	s_movk_i32 s11, 0xf00
	s_mov_b32 s19, 0xf0000
	s_mov_b32 s34, 0xf000000
	s_mov_b32 s35, 0xc050c00
	s_mov_b32 s42, 0xf0f0f0f
	s_mov_b32 s43, 0xff00ff
	v_add_u32_e32 v7, 64, v2
	v_xor_b32_e32 v14, 1, v1
	v_xor_b32_e32 v15, 2, v1
	v_xor_b32_e32 v16, 4, v1
	v_xor_b32_e32 v17, 8, v1
	v_xor_b32_e32 v18, 16, v1
	v_xor_b32_e32 v19, 32, v1
	s_lshl_b32 s79, s77, 14
	s_mov_b32 s80, s79
	v_lshlrev_b32_e32 v44, 4, v178
	v_lshlrev_b32_e32 v45, 6, v178
	s_mov_b32 s81, s0
	s_cmpk_lt_i32 s81, 0x6b00
	s_cselect_b32 s84, s81, s0
	s_cmpk_lt_i32 s84, 0x4000
	s_cselect_b32 s86, s82, s24
	s_cselect_b32 s87, s83, s25
	s_and_b32 s85, s84, 0x3fff
	s_lshl_b32 s85, s85, 12
	s_add_u32 s86, s86, s85
	s_addc_u32 s87, s87, 0
	s_mov_b32 m0, s80
	s_nop 0
	global_load_lds_dwordx4 v45, s[86:87]
	s_add_i32 m0, s80, 0x3f0
	s_nop 0
	global_load_lds_dwordx4 v45, s[86:87] offset:16
	s_add_i32 m0, s80, 0x7e0
	s_nop 0
	global_load_lds_dwordx4 v45, s[86:87] offset:32
	s_add_i32 m0, s80, 0xbd0
	s_nop 0
	global_load_lds_dwordx4 v45, s[86:87] offset:48
	global_load_dword v47, v45, s[86:87]
	global_load_dword v47, v45, s[86:87]
	s_add_i32 s80, s80, 0x1000
	s_sub_i32 s85, s80, s79
	s_and_b32 s85, s85, 0x3fff
	s_add_i32 s80, s79, s85
	s_add_i32 s81, s81, s10
	s_cmpk_lt_i32 s81, 0x6b00
	s_cselect_b32 s84, s81, s0
	s_cmpk_lt_i32 s84, 0x4000
	s_cselect_b32 s86, s82, s24
	s_cselect_b32 s87, s83, s25
	s_and_b32 s85, s84, 0x3fff
	s_lshl_b32 s85, s85, 12
	s_add_u32 s86, s86, s85
	s_addc_u32 s87, s87, 0
	s_mov_b32 m0, s80
	s_nop 0
	global_load_lds_dwordx4 v45, s[86:87]
	s_add_i32 m0, s80, 0x3f0
	s_nop 0
	global_load_lds_dwordx4 v45, s[86:87] offset:16
	s_add_i32 m0, s80, 0x7e0
	s_nop 0
	global_load_lds_dwordx4 v45, s[86:87] offset:32
	s_add_i32 m0, s80, 0xbd0
	s_nop 0
	global_load_lds_dwordx4 v45, s[86:87] offset:48
	global_load_dword v47, v45, s[86:87]
	global_load_dword v47, v45, s[86:87]
	s_add_i32 s80, s80, 0x1000
	s_sub_i32 s85, s80, s79
	s_and_b32 s85, s85, 0x3fff
	s_add_i32 s80, s79, s85
	s_add_i32 s81, s81, s10
	s_cmpk_lt_i32 s81, 0x6b00
	s_cselect_b32 s84, s81, s0
	s_cmpk_lt_i32 s84, 0x4000
	s_cselect_b32 s86, s82, s24
	s_cselect_b32 s87, s83, s25
	s_and_b32 s85, s84, 0x3fff
	s_lshl_b32 s85, s85, 12
	s_add_u32 s86, s86, s85
	s_addc_u32 s87, s87, 0
	s_mov_b32 m0, s80
	s_nop 0
	global_load_lds_dwordx4 v45, s[86:87]
	s_add_i32 m0, s80, 0x3f0
	s_nop 0
	global_load_lds_dwordx4 v45, s[86:87] offset:16
	s_add_i32 m0, s80, 0x7e0
	s_nop 0
	global_load_lds_dwordx4 v45, s[86:87] offset:32
	s_add_i32 m0, s80, 0xbd0
	s_nop 0
	global_load_lds_dwordx4 v45, s[86:87] offset:48
	global_load_dword v47, v45, s[86:87]
	global_load_dword v47, v45, s[86:87]
	s_add_i32 s80, s80, 0x1000
	s_sub_i32 s85, s80, s79
	s_and_b32 s85, s85, 0x3fff
	s_add_i32 s80, s79, s85
	s_add_i32 s81, s81, s10
	s_cmpk_lt_i32 s81, 0x6b00
	s_cselect_b32 s84, s81, s0
	s_cmpk_lt_i32 s84, 0x4000
	s_cselect_b32 s86, s82, s24
	s_cselect_b32 s87, s83, s25
	s_and_b32 s85, s84, 0x3fff
	s_lshl_b32 s85, s85, 12
	s_add_u32 s86, s86, s85
	s_addc_u32 s87, s87, 0
	s_mov_b32 m0, s80
	s_nop 0
	global_load_lds_dwordx4 v45, s[86:87]
	s_add_i32 m0, s80, 0x3f0
	s_nop 0
	global_load_lds_dwordx4 v45, s[86:87] offset:16
	s_add_i32 m0, s80, 0x7e0
	s_nop 0
	global_load_lds_dwordx4 v45, s[86:87] offset:32
	s_add_i32 m0, s80, 0xbd0
	s_nop 0
	global_load_lds_dwordx4 v45, s[86:87] offset:48
	global_load_dword v47, v45, s[86:87]
	global_load_dword v47, v45, s[86:87]
	s_add_i32 s80, s80, 0x1000
	s_sub_i32 s85, s80, s79
	s_and_b32 s85, s85, 0x3fff
	s_add_i32 s80, s79, s85
	s_add_i32 s81, s81, s10
	s_branch .LBB0_463

; __device__ __forceinline__ unsigned fp4_code(float y) { const int q = (int)rintf(y); return (unsigned)q & 15u; }
; __device__ __forceinline__ void cvt_row_fp4(const float* __restrict__ src, unsigned char* __restrict__ T4, float* __restrict__ inv_scale, int e, int lane) {
;     f32x4 v[4]; float am = 0.f;
; #pragma unroll
;     for (int j = 0; j < 4; ++j) { v[j] = *(const f32x4*)(src + (size_t)e * 1024 + 16 * lane + 4 * j);
;         am = fmaxf(am, fmaxf(fmaxf(fabsf(v[j].x), fabsf(v[j].y)), fmaxf(fabsf(v[j].z), fabsf(v[j].w)))); }
; #pragma unroll
;     for (int o = 1; o < 64; o <<= 1) am = fmaxf(am, __shfl_xor(am, o));
;     const float sc = am > 0.f ? 7.f / am : 0.f;
;     unsigned n0 = 0u, n1 = 0u;
; #pragma unroll
;     for (int i = 0; i < 8; ++i) { n0 |= fp4_code(v[i >> 2][i & 3] * sc) << (4 * i); n1 |= fp4_code(v[2 + (i >> 2)][i & 3] * sc) << (4 * i); }
;     const unsigned p0 = (unsigned)__builtin_amdgcn_update_dpp(0, (int)n0, 0xB1, 0xf, 0xf, true), p1 = (unsigned)__builtin_amdgcn_update_dpp(0, (int)n1, 0xB1, 0xf, 0xf, true);
.LBB0_463:
	s_cmpk_gt_i32 s0, 0x3fff
	s_mov_b64 s[40:41], -1
	s_cbranch_scc0 .LBB0_469
	s_add_i32 s8, s0, 0xffffc000
	s_waitcnt vmcnt(20)
	v_add_u32_e32 v46, s80, v44
	ds_read_b128 v[22:25], v46
	ds_read_b128 v[26:29], v46 offset:1024
	ds_read_b128 v[30:33], v46 offset:2048
	ds_read_b128 v[34:37], v46 offset:3072
	s_lshl_b32 s84, s10, 2
	s_add_i32 s84, s84, s0
	s_cmpk_lt_i32 s84, 0x6b00
	s_cselect_b32 s84, s84, s0
	s_cmpk_lt_i32 s84, 0x4000
	s_cselect_b32 s86, s82, s24
	s_cselect_b32 s87, s83, s25
	s_and_b32 s85, s84, 0x3fff
	s_lshl_b32 s85, s85, 12
	s_add_u32 s86, s86, s85
	s_addc_u32 s87, s87, 0
	v_cmp_lt_i32_e32 vcc, v14, v7
	s_waitcnt lgkmcnt(0)
	s_mov_b32 m0, s80
	s_nop 0
	global_load_lds_dwordx4 v45, s[86:87]
	s_add_i32 m0, s80, 0x3f0
	s_nop 0
	global_load_lds_dwordx4 v45, s[86:87] offset:16
	s_add_i32 m0, s80, 0x7e0
	s_nop 0
	global_load_lds_dwordx4 v45, s[86:87] offset:32
	s_add_i32 m0, s80, 0xbd0
	s_nop 0
	global_load_lds_dwordx4 v45, s[86:87] offset:48
	s_add_i32 s80, s80, 0x1000
	s_sub_i32 s85, s80, s79
	s_and_b32 s85, s85, 0x3fff
	s_add_i32 s80, s79, s85
	v_max_f32_e64 v20, |v25|, |v25|
	v_max_f32_e64 v21, |v24|, |v24|
	v_max_f32_e64 v38, |v29|, |v29|
	v_max_f32_e64 v39, |v28|, |v28|
	v_max_f32_e64 v40, |v33|, |v33|
	v_max_f32_e64 v41, |v32|, |v32|
	v_max_f32_e64 v42, |v37|, |v37|
	v_max_f32_e64 v43, |v36|, |v36|
	v_max_f32_e32 v20, v21, v20
	v_max_f32_e32 v21, v39, v38
	v_max_f32_e32 v38, v41, v40
	v_max_f32_e32 v39, v43, v42
	v_max3_f32 v20, |v22|, |v23|, v20
	v_max3_f32 v21, |v26|, |v27|, v21
	v_cndmask_b32_e32 v2, v1, v14, vcc
	v_max3_f32 v38, |v30|, |v31|, v38
	v_max3_f32 v39, |v34|, |v35|, v39
	v_max3_f32 v20, v20, 0, v21
	v_lshlrev_b32_e32 v2, 2, v2
	v_max3_f32 v20, v20, v38, v39
	ds_bpermute_b32 v2, v2, v20
	v_cmp_lt_i32_e32 vcc, v15, v7
	s_waitcnt lgkmcnt(0)
	v_max_f32_e32 v2, v2, v2
	v_cndmask_b32_e32 v21, v1, v15, vcc
	v_lshlrev_b32_e32 v21, 2, v21
	v_max_f32_e32 v2, v20, v2
	ds_bpermute_b32 v20, v21, v2
	v_cmp_lt_i32_e32 vcc, v16, v7
	s_waitcnt lgkmcnt(0)
	v_max_f32_e32 v20, v20, v20
	v_cndmask_b32_e32 v21, v1, v16, vcc
	v_lshlrev_b32_e32 v21, 2, v21
	v_max_f32_e32 v2, v2, v20
	ds_bpermute_b32 v20, v21, v2
	v_cmp_lt_i32_e32 vcc, v17, v7
	s_waitcnt lgkmcnt(0)
	v_max_f32_e32 v20, v20, v20
	v_cndmask_b32_e32 v21, v1, v17, vcc
	v_lshlrev_b32_e32 v21, 2, v21
	v_max_f32_e32 v2, v2, v20
	ds_bpermute_b32 v20, v21, v2
	v_cmp_lt_i32_e32 vcc, v18, v7
	s_waitcnt lgkmcnt(0)
	v_max_f32_e32 v20, v20, v20
	v_cndmask_b32_e32 v21, v1, v18, vcc
	v_lshlrev_b32_e32 v21, 2, v21
	v_max_f32_e32 v2, v2, v20
	ds_bpermute_b32 v20, v21, v2
	v_cmp_lt_i32_e32 vcc, v19, v7
	s_waitcnt lgkmcnt(0)
	v_max_f32_e32 v20, v20, v20
	v_cndmask_b32_e32 v21, v1, v19, vcc
	v_lshlrev_b32_e32 v21, 2, v21
	v_max_f32_e32 v2, v2, v20
	ds_bpermute_b32 v20, v21, v2
	s_waitcnt lgkmcnt(0)
	v_max_f32_e32 v20, v20, v20
	v_max_f32_e32 v20, v2, v20
	v_div_scale_f32 v2, s[40:41], v20, v20, s1
	v_rcp_f32_e32 v21, v2
	v_div_scale_f32 v38, vcc, s1, v20, s1
	v_fma_f32 v39, -v2, v21, 1.0
	v_fmac_f32_e32 v21, v39, v21
	v_mul_f32_e32 v39, v38, v21
	v_fma_f32 v40, -v2, v39, v38
	v_fmac_f32_e32 v39, v40, v21
	v_fma_f32 v2, -v2, v39, v38
	v_div_fmas_f32 v2, v2, v21, v39
	v_div_fixup_f32 v2, v2, v20, s1
	v_cmp_lt_f32_e32 vcc, 0, v20
	s_nop 1
	v_cndmask_b32_e32 v2, 0, v2, vcc
	v_mul_f32_e32 v21, v22, v2
	v_mul_f32_e32 v22, v30, v2
	v_mul_f32_e32 v23, v23, v2
	v_mul_f32_e32 v30, v31, v2
	v_mul_f32_e32 v31, v32, v2
	v_mul_f32_e32 v25, v25, v2
	v_mul_f32_e32 v32, v33, v2
	v_mul_f32_e32 v26, v26, v2
	v_mul_f32_e32 v33, v34, v2
	v_mul_f32_e32 v27, v27, v2
	v_mul_f32_e32 v34, v35, v2
	v_mul_f32_e32 v24, v24, v2
	v_mul_f32_e32 v28, v28, v2
	v_mul_f32_e32 v35, v36, v2
	v_mul_f32_e32 v29, v29, v2
	v_mul_f32_e32 v2, v37, v2
	v_rndne_f32_e32 v21, v21
	v_rndne_f32_e32 v22, v22
	v_rndne_f32_e32 v23, v23
	v_rndne_f32_e32 v30, v30
	v_rndne_f32_e32 v25, v25
	v_rndne_f32_e32 v32, v32
	v_rndne_f32_e32 v26, v26
	v_rndne_f32_e32 v27, v27
	v_rndne_f32_e32 v34, v34
	v_rndne_f32_e32 v24, v24
	v_rndne_f32_e32 v29, v29
	v_rndne_f32_e32 v2, v2
	v_cvt_i32_f32_e32 v21, v21
	v_cvt_i32_f32_e32 v22, v22
	v_cvt_i32_f32_e32 v23, v23
	v_cvt_i32_f32_e32 v30, v30
	v_cvt_i32_f32_e32 v25, v25
	v_cvt_i32_f32_e32 v32, v32
	v_cvt_i32_f32_sdwa v36, v26 dst_sel:WORD_1 dst_unused:UNUSED_PAD src0_sel:DWORD
	v_cvt_i32_f32_e32 v26, v27
	v_cvt_i32_f32_e32 v27, v34
	v_rndne_f32_e32 v31, v31
	v_rndne_f32_e32 v33, v33
	v_rndne_f32_e32 v28, v28
	v_rndne_f32_e32 v35, v35
	v_cvt_i32_f32_e32 v24, v24
	v_cvt_i32_f32_e32 v29, v29
	v_cvt_i32_f32_e32 v2, v2
	v_cvt_i32_f32_e32 v31, v31
	v_cvt_i32_f32_sdwa v33, v33 dst_sel:WORD_1 dst_unused:UNUSED_PAD src0_sel:DWORD
	v_cvt_i32_f32_sdwa v28, v28 dst_sel:BYTE_3 dst_unused:UNUSED_PAD src0_sel:DWORD
	v_cvt_i32_f32_sdwa v34, v35 dst_sel:BYTE_3 dst_unused:UNUSED_PAD src0_sel:DWORD
	v_and_b32_e32 v21, 15, v21
	v_and_b32_e32 v22, 15, v22
	v_lshlrev_b32_e32 v23, 4, v23
	v_lshlrev_b32_e32 v30, 4, v30
	v_lshlrev_b32_e32 v35, 12, v25
	v_lshlrev_b32_e32 v32, 12, v32
	v_lshlrev_b32_e32 v26, 20, v26
	v_lshlrev_b32_e32 v27, 20, v27
	v_lshlrev_b32_e32 v24, 8, v24
	v_lshlrev_b32_e32 v29, 28, v29
	v_lshlrev_b32_e32 v37, 28, v2
	v_and_or_b32 v25, v23, s3, v21
	v_and_or_b32 v2, v30, s3, v22
	v_and_b32_e32 v22, 0xf000, v35
	v_and_b32_e32 v23, 0xf000, v32
	v_and_b32_e32 v30, 0xf00000, v26
	v_and_b32_e32 v32, 0xf00000, v27
	v_lshlrev_b32_e32 v31, 8, v31
	v_and_or_b32 v26, v28, s34, v29
	v_and_or_b32 v21, v34, s34, v37
	v_and_or_b32 v29, v24, s11, v22
	v_and_or_b32 v27, v36, s19, v30
	v_and_or_b32 v22, v33, s19, v32
	v_and_or_b32 v24, v31, s11, v23
	v_or_b32_e32 v23, v27, v26
	v_or_b32_e32 v28, v22, v21
	v_or3_b32 v23, v23, v25, v29
	v_or3_b32 v30, v28, v2, v24
	s_nop 0
	v_mov_b32_dpp v28, v23 quad_perm:[1,0,3,2] row_mask:0xf bank_mask:0xf bound_ctrl:1
	v_mov_b32_dpp v23, v30 quad_perm:[1,0,3,2] row_mask:0xf bank_mask:0xf bound_ctrl:1
	s_and_saveexec_b64 s[40:41], s[4:5]
	s_cbranch_execz .LBB0_466
; __device__ __forceinline__ void cvt_row_fp4(const float* __restrict__ src, unsigned char* __restrict__ T4, float* __restrict__ inv_scale, int e, int lane) {
;     ...
;     if ((lane & 1) == 0) {
;         v4u o;
;         o.x = spread4(n0) | (spread4(p0) << 4); o.y = spread4(n0 >> 16) | (spread4(p0 >> 16) << 4);
;         o.z = spread4(n1) | (spread4(p1) << 4); o.w = spread4(n1 >> 16) | (spread4(p1 >> 16) << 4);
;         *(v4u*)(T4 + ((size_t)(lane >> 4) * 16384 + e) * 128 + 16 * ((lane & 15) >> 1)) = o;
;     }
;     if (lane == 0) inv_scale[e] = am * (1.f / (7.f * 16.f));
	v_lshl_or_b32 v25, v29, 8, v25
	v_perm_b32 v29, v28, v28, s35
	v_lshlrev_b32_e32 v30, 4, v29
	v_lshl_or_b32 v25, v25, 4, v25
	v_lshl_or_b32 v29, v29, 8, v30
	v_bfi_b32 v30, s42, v25, v29
	v_lshrrev_b32_e32 v25, 8, v26
	v_lshrrev_b32_e32 v26, 16, v28
	v_or_b32_sdwa v25, v25, v27 dst_sel:DWORD dst_unused:UNUSED_PAD src0_sel:DWORD src1_sel:WORD_1
	v_lshlrev_b32_e32 v27, 8, v26
	v_bitop3_b32 v26, v27, s43, v26 bitop3:0xc8
	v_lshlrev_b32_e32 v27, 4, v26
	v_lshl_or_b32 v25, v25, 4, v25
	v_lshl_or_b32 v26, v26, 8, v27
	v_lshl_or_b32 v2, v24, 8, v2
	v_perm_b32 v24, v23, v23, s35
	v_bfi_b32 v31, s42, v25, v26
	v_lshlrev_b32_e32 v25, 4, v24
	v_lshl_or_b32 v2, v2, 4, v2
	v_lshl_or_b32 v24, v24, 8, v25
	v_bfi_b32 v32, s42, v2, v24
	v_lshrrev_b32_e32 v2, 8, v21
	v_lshrrev_b32_e32 v21, 16, v23
	v_or_b32_sdwa v2, v2, v22 dst_sel:DWORD dst_unused:UNUSED_PAD src0_sel:DWORD src1_sel:WORD_1
	v_lshlrev_b32_e32 v22, 8, v21
	v_bitop3_b32 v21, v22, s43, v21 bitop3:0xc8
	v_lshlrev_b32_e32 v22, 4, v21
	v_lshl_or_b32 v2, v2, 4, v2
	v_lshl_or_b32 v21, v21, 8, v22
	v_bfi_b32 v33, s42, v2, v21
	v_add_u32_e32 v2, s8, v6
	v_lshlrev_b64 v[22:23], 7, v[2:3]
	v_lshl_add_u64 v[22:23], v[8:9], 0, v[22:23]
	global_store_dwordx4 v[22:23], v[30:33], off

; __device__ __forceinline__ void cvt_row_i4(const float* __restrict__ src, unsigned char* __restrict__ T4, float* __restrict__ inv_scale, int e, int lane) {
;     f32x4 v[4]; float am = 0.f;
; #pragma unroll
;     for (int j = 0; j < 4; ++j) { v[j] = *(const f32x4*)(src + (size_t)e * 1024 + 16 * lane + 4 * j);
;         am = fmaxf(am, fmaxf(fmaxf(fabsf(v[j].x), fabsf(v[j].y)), fmaxf(fabsf(v[j].z), fabsf(v[j].w)))); }
; #pragma unroll
;     for (int o = 1; o < 64; o <<= 1) am = fmaxf(am, __shfl_xor(am, o));
;     const float sc = am > 0.f ? 7.f / am : 0.f;
;     v2u o;
; #pragma unroll
;     for (int k = 0; k < 2; ++k) { unsigned w = 0u;
; #pragma unroll
;         for (int i = 0; i < 8; ++i) { const int q = (int)rintf(v[2 * k + (i >> 2)][i & 3] * sc); w |= ((unsigned)q & 15u) << (4 * i); }
;         o[k] = w; }
;     *(v2u*)(T4 + ((size_t)(lane >> 4) * 16384 + e) * 128 + 8 * (lane & 15)) = o;
;     if (lane == 0) inv_scale[e] = am * (1.f / 7.f);
.LBB0_469:
	s_and_b64 vcc, exec, s[40:41]
	s_cbranch_vccz .LBB0_462
	s_waitcnt vmcnt(20)
	v_add_u32_e32 v46, s80, v44
	ds_read_b128 v[20:23], v46
	ds_read_b128 v[24:27], v46 offset:1024
	ds_read_b128 v[28:31], v46 offset:2048
	ds_read_b128 v[32:35], v46 offset:3072
	s_lshl_b32 s84, s10, 2
	s_add_i32 s84, s84, s0
	s_cmpk_lt_i32 s84, 0x6b00
	s_cselect_b32 s84, s84, s0
	s_cmpk_lt_i32 s84, 0x4000
	s_cselect_b32 s86, s82, s24
	s_cselect_b32 s87, s83, s25
	s_and_b32 s85, s84, 0x3fff
	s_lshl_b32 s85, s85, 12
	s_add_u32 s86, s86, s85
	s_addc_u32 s87, s87, 0
	v_cmp_lt_i32_e32 vcc, v14, v7
	s_waitcnt lgkmcnt(0)
	s_mov_b32 m0, s80
	s_nop 0
	global_load_lds_dwordx4 v45, s[86:87]
	s_add_i32 m0, s80, 0x3f0
	s_nop 0
	global_load_lds_dwordx4 v45, s[86:87] offset:16
	s_add_i32 m0, s80, 0x7e0
	s_nop 0
	global_load_lds_dwordx4 v45, s[86:87] offset:32
	s_add_i32 m0, s80, 0xbd0
	s_nop 0
	global_load_lds_dwordx4 v45, s[86:87] offset:48
	s_add_i32 s80, s80, 0x1000
	s_sub_i32 s85, s80, s79
	s_and_b32 s85, s85, 0x3fff
	s_add_i32 s80, s79, s85
	v_max_f32_e64 v36, |v23|, |v23|
	v_max_f32_e64 v37, |v22|, |v22|
	v_max_f32_e64 v38, |v27|, |v27|
	v_max_f32_e64 v39, |v26|, |v26|
	v_max_f32_e64 v40, |v31|, |v31|
	v_max_f32_e64 v41, |v30|, |v30|
	v_max_f32_e64 v42, |v35|, |v35|
	v_max_f32_e64 v43, |v34|, |v34|
	v_max_f32_e32 v36, v37, v36
	v_max_f32_e32 v37, v39, v38
	v_max_f32_e32 v38, v41, v40
	v_max_f32_e32 v39, v43, v42
	v_max3_f32 v36, |v20|, |v21|, v36
	v_max3_f32 v37, |v24|, |v25|, v37
	v_cndmask_b32_e32 v2, v1, v14, vcc
	v_max3_f32 v38, |v28|, |v29|, v38
	v_max3_f32 v39, |v32|, |v33|, v39
	v_max3_f32 v36, v36, 0, v37
	v_lshlrev_b32_e32 v2, 2, v2
	v_max3_f32 v36, v36, v38, v39
	ds_bpermute_b32 v2, v2, v36
	v_cmp_lt_i32_e32 vcc, v15, v7
	s_waitcnt lgkmcnt(0)
	v_max_f32_e32 v2, v2, v2
	v_cndmask_b32_e32 v37, v1, v15, vcc
	v_lshlrev_b32_e32 v37, 2, v37
	v_max_f32_e32 v2, v36, v2
	ds_bpermute_b32 v36, v37, v2
	v_cmp_lt_i32_e32 vcc, v16, v7
	s_waitcnt lgkmcnt(0)
	v_max_f32_e32 v36, v36, v36
	v_cndmask_b32_e32 v37, v1, v16, vcc
	v_lshlrev_b32_e32 v37, 2, v37
	v_max_f32_e32 v2, v2, v36
	ds_bpermute_b32 v36, v37, v2
	v_cmp_lt_i32_e32 vcc, v17, v7
	s_waitcnt lgkmcnt(0)
	v_max_f32_e32 v36, v36, v36
	v_cndmask_b32_e32 v37, v1, v17, vcc
	v_lshlrev_b32_e32 v37, 2, v37
	v_max_f32_e32 v2, v2, v36
	ds_bpermute_b32 v36, v37, v2
	v_cmp_lt_i32_e32 vcc, v18, v7
	s_waitcnt lgkmcnt(0)
	v_max_f32_e32 v36, v36, v36
	v_cndmask_b32_e32 v37, v1, v18, vcc
	v_lshlrev_b32_e32 v37, 2, v37
	v_max_f32_e32 v2, v2, v36
	ds_bpermute_b32 v36, v37, v2
	v_cmp_lt_i32_e32 vcc, v19, v7
	s_waitcnt lgkmcnt(0)
	v_max_f32_e32 v36, v36, v36
	v_cndmask_b32_e32 v37, v1, v19, vcc
	v_lshlrev_b32_e32 v37, 2, v37
	v_max_f32_e32 v2, v2, v36
	ds_bpermute_b32 v36, v37, v2
	s_waitcnt lgkmcnt(0)
	v_max_f32_e32 v36, v36, v36
	v_max_f32_e32 v2, v2, v36
	v_div_scale_f32 v36, s[40:41], v2, v2, s1
	v_rcp_f32_e32 v37, v36
	v_div_scale_f32 v38, vcc, s1, v2, s1
	v_fma_f32 v39, -v36, v37, 1.0
	v_fmac_f32_e32 v37, v39, v37
	v_mul_f32_e32 v39, v38, v37
	v_fma_f32 v40, -v36, v39, v38
	v_fmac_f32_e32 v39, v40, v37
	v_fma_f32 v36, -v36, v39, v38
	v_div_fmas_f32 v36, v36, v37, v39
	v_div_fixup_f32 v36, v36, v2, s1
	v_cmp_lt_f32_e32 vcc, 0, v2
	s_nop 1
	v_cndmask_b32_e32 v36, 0, v36, vcc
	v_mul_f32_e32 v20, v20, v36
	v_mul_f32_e32 v21, v21, v36
	v_mul_f32_e32 v22, v22, v36
	v_mul_f32_e32 v28, v28, v36
	v_mul_f32_e32 v29, v29, v36
	v_mul_f32_e32 v30, v30, v36
	v_mul_f32_e32 v23, v23, v36
	v_mul_f32_e32 v27, v27, v36
	v_mul_f32_e32 v31, v31, v36
	v_mul_f32_e32 v35, v35, v36
	v_rndne_f32_e32 v20, v20
	v_rndne_f32_e32 v21, v21
	v_rndne_f32_e32 v22, v22
	v_rndne_f32_e32 v28, v28
	v_rndne_f32_e32 v29, v29
	v_rndne_f32_e32 v30, v30
	v_mul_f32_e32 v24, v24, v36
	v_mul_f32_e32 v25, v25, v36
	v_mul_f32_e32 v32, v32, v36
	v_mul_f32_e32 v33, v33, v36
	v_rndne_f32_e32 v23, v23
	v_rndne_f32_e32 v27, v27
	v_rndne_f32_e32 v31, v31
	v_rndne_f32_e32 v35, v35
	v_cvt_i32_f32_e32 v20, v20
	v_cvt_i32_f32_e32 v21, v21
	v_cvt_i32_f32_e32 v22, v22
	v_cvt_i32_f32_e32 v28, v28
	v_cvt_i32_f32_e32 v29, v29
	v_cvt_i32_f32_e32 v30, v30
	v_mul_f32_e32 v26, v26, v36
	v_mul_f32_e32 v34, v34, v36
	v_rndne_f32_e32 v24, v24
	v_rndne_f32_e32 v25, v25
	v_rndne_f32_e32 v32, v32
	v_rndne_f32_e32 v33, v33
	v_cvt_i32_f32_e32 v23, v23
	v_cvt_i32_f32_e32 v27, v27
	v_cvt_i32_f32_e32 v31, v31
	v_cvt_i32_f32_e32 v35, v35
	v_rndne_f32_e32 v26, v26
	v_rndne_f32_e32 v34, v34
	v_cvt_i32_f32_sdwa v24, v24 dst_sel:WORD_1 dst_unused:UNUSED_PAD src0_sel:DWORD
	v_cvt_i32_f32_e32 v25, v25
	v_cvt_i32_f32_sdwa v32, v32 dst_sel:WORD_1 dst_unused:UNUSED_PAD src0_sel:DWORD
	v_cvt_i32_f32_e32 v33, v33
	v_cvt_i32_f32_sdwa v26, v26 dst_sel:BYTE_3 dst_unused:UNUSED_PAD src0_sel:DWORD
	v_cvt_i32_f32_sdwa v34, v34 dst_sel:BYTE_3 dst_unused:UNUSED_PAD src0_sel:DWORD
	v_and_b32_e32 v20, 15, v20
	v_lshlrev_b32_e32 v21, 4, v21
	v_lshlrev_b32_e32 v22, 8, v22
	v_and_b32_e32 v28, 15, v28
	v_lshlrev_b32_e32 v29, 4, v29
	v_lshlrev_b32_e32 v30, 8, v30
	v_lshlrev_b32_e32 v23, 12, v23
	v_lshlrev_b32_e32 v31, 12, v31
	v_and_b32_e32 v21, 0xf0, v21
	v_and_b32_e32 v22, 0xf00, v22
	v_lshl_or_b32 v20, v27, 28, v20
	v_and_b32_e32 v27, 0xf0, v29
	v_and_b32_e32 v29, 0xf00, v30
	v_lshl_or_b32 v28, v35, 28, v28
	v_and_b32_e32 v24, 0xf0000, v24
	v_lshlrev_b32_e32 v25, 20, v25
	v_and_b32_e32 v32, 0xf0000, v32
	v_lshlrev_b32_e32 v33, 20, v33
	v_and_b32_e32 v23, 0xf000, v23
	v_and_b32_e32 v30, 0xf000, v31
	v_or3_b32 v20, v20, v21, v22
	v_or3_b32 v21, v28, v27, v29
	v_and_b32_e32 v26, 0xf000000, v26
	v_and_b32_e32 v34, 0xf000000, v34
	v_and_b32_e32 v25, 0xf00000, v25
	v_and_b32_e32 v31, 0xf00000, v33
	v_or3_b32 v20, v20, v23, v24
	v_or3_b32 v21, v21, v30, v32
	v_or3_b32 v20, v20, v25, v26
	v_or3_b32 v21, v21, v31, v34
	global_store_dwordx2 v[10:11], v[20:21], off
	s_and_saveexec_b64 s[40:41], s[6:7]
	s_cbranch_execz .LBB0_461
	v_mul_f32_e32 v2, 0x3e124925, v2
	global_store_dword v3, v2, s[12:13]
	s_branch .LBB0_461

; __device__ __forceinline__ unsigned pk2(float lo, float hi) { return f2bf(lo) | (f2bf(hi) << 16); }
;     __device__ __forceinline__ void operator()(const pg8::f32x4 (&acc)[2][2][4][2], const pg8::Unit& u, int wr, int wc, int fr, int fq) const {
;         const int b = u.pm >> 3;
;         const int col0 = u.pn * 256 + wc * 32 + 4 * fq;
;         f32x4 gt[2][2], al[2][2];
; #pragma unroll
;         for (int bj = 0; bj < 2; ++bj)
; #pragma unroll
;             for (int n = 0; n < 2; ++n) { gt[bj][n] = *(const f32x4*)(mod + (size_t)b * NMODC + 2 * D + col0 + bj * 128 + n * 16); al[bj][n] = *(const f32x4*)(alpha2 + (size_t)b * D + col0 + bj * 128 + n * 16); }
; #pragma unroll
;         for (int ai = 0; ai < 2; ++ai)
; #pragma unroll
;             for (int mh = 0; mh < 4; mh += MB) {
;                 f32x4 xv[MB][2][2];
; #pragma unroll
;                 for (int mm = 0; mm < MB; ++mm) { const size_t row = (size_t)u.pm * 256 + ai * 128 + wr * 64 + (mh + mm) * 16 + fr;
; #pragma unroll
;                     for (int bj = 0; bj < 2; ++bj)
; #pragma unroll
;                         for (int n = 0; n < 2; ++n) xv[mm][bj][n] = *(const f32x4*)(x + row * D + col0 + bj * 128 + n * 16); }
; #pragma unroll
;                 for (int mm = 0; mm < MB; ++mm) { const int m = mh + mm;
;                     const size_t row = (size_t)u.pm * 256 + ai * 128 + wr * 64 + m * 16 + fr;
;                     float ss = 0.f;
; #pragma unroll
;                     for (int bj = 0; bj < 2; ++bj)
; #pragma unroll
;                         for (int n = 0; n < 2; ++n) { const size_t off = row * D + col0 + bj * 128 + n * 16;
;                             const f32x4 x1 = xv[mm][bj][n] + gt[bj][n] * acc[ai][bj][m][n];
;                             { v2u pb; pb.x = pk2(x1.x, x1.y); pb.y = pk2(x1.z, x1.w); *(v2u*)(x1b + off) = pb; } ss += (x1.x * x1.x + x1.y * x1.y) + (x1.z * x1.z + x1.w * x1.w);
;                             const f32x4 xa = x1 * al[bj][n]; v2u pk; pk.x = pk2(xa.x, xa.y); pk.y = pk2(xa.z, xa.w); *(v2u*)(x1a + off) = pk; }
;                     ss += __shfl_xor(ss, 16); ss += __shfl_xor(ss, 32);
;                     if (fq == 0) ssq[row * 16 + u.pn * 4 + wc] = ss;
.LBB0_716:
	s_ashr_i32 s62, s60, 3
	s_mul_i32 s53, s62, 0x6000
	s_add_u32 s64, s28, s53
	s_addc_u32 s65, s29, 0
	s_lshl_b32 s62, s62, 12
	s_add_u32 s62, s70, s62
	s_addc_u32 s63, s71, 0
	v_lshl_or_b32 v246, s8, 8, v208
	v_lshlrev_b32_e32 v246, 2, v246
	v_add_u32_e32 v247, 0x2000, v246
	global_load_dwordx4 v[58:61], v247, s[64:65]
	global_load_dwordx4 v[62:65], v247, s[64:65] offset:64
	global_load_dwordx4 v[66:69], v247, s[64:65] offset:512
	global_load_dwordx4 v[70:73], v247, s[64:65] offset:576
	global_load_dwordx4 v[74:77], v246, s[62:63]
	global_load_dwordx4 v[78:81], v246, s[62:63] offset:64
	global_load_dwordx4 v[82:85], v246, s[62:63] offset:512
	global_load_dwordx4 v[86:89], v246, s[62:63] offset:576
	s_lshl_b32 s10, s60, 8
	v_add_u32_e32 v203, s10, v184
	v_lshl_add_u32 v200, v203, 12, v246
	v_and_b32_e32 v246, 4, v208
	v_and_b32_e32 v247, 0x68, v208
	v_lshl_or_b32 v246, v246, 2, v247
	s_lshl_b32 s10, s8, 8
	v_or_b32_e32 v246, s10, v246
	v_lshl_add_u32 v246, v203, 10, v246
	v_lshlrev_b32_e32 v201, 1, v246
	s_lshl_b32 s10, s8, 2
	s_add_i32 s10, s10, s69
	s_lshl_b32 s10, s10, 2
	v_lshlrev_b32_e32 v203, 6, v203
	v_add_u32_e32 v202, s10, v203
	v_xor_b32_e32 v238, 16, v212
	v_xor_b32_e32 v239, 32, v212
	v_lshlrev_b32_e32 v238, 2, v238
	v_lshlrev_b32_e32 v239, 2, v239
	global_load_dwordx4 v[162:165], v200, s[36:37]
	global_load_dwordx4 v[166:169], v200, s[36:37] offset:64
	global_load_dwordx4 v[170:173], v200, s[36:37] offset:512
	global_load_dwordx4 v[174:177], v200, s[36:37] offset:576
	v_add_u32_e32 v203, 0x10000, v200
	global_load_dwordx4 v[214:217], v203, s[36:37]
	global_load_dwordx4 v[218:221], v203, s[36:37] offset:64
	global_load_dwordx4 v[222:225], v203, s[36:37] offset:512
	global_load_dwordx4 v[226:229], v203, s[36:37] offset:576
	v_add_u32_e32 v203, 0x20000, v200
	global_load_dwordx4 v[230:233], v203, s[36:37]
	global_load_dwordx4 v[234:237], v203, s[36:37] offset:64
	global_load_dwordx4 v[242:245], v203, s[36:37] offset:512
	global_load_dwordx4 v[204:207], v203, s[36:37] offset:576
	s_waitcnt vmcnt(8)
	v_pk_fma_f32 v[158:159], v[158:159], v[58:59], v[162:163]
	v_pk_fma_f32 v[160:161], v[160:161], v[60:61], v[164:165]
	v_pk_fma_f32 v[154:155], v[154:155], v[62:63], v[166:167]
	v_pk_fma_f32 v[156:157], v[156:157], v[64:65], v[168:169]
	v_pk_fma_f32 v[150:151], v[150:151], v[66:67], v[170:171]
	v_pk_fma_f32 v[152:153], v[152:153], v[68:69], v[172:173]
	v_pk_fma_f32 v[146:147], v[146:147], v[70:71], v[174:175]
	v_pk_fma_f32 v[148:149], v[148:149], v[72:73], v[176:177]
	v_mul_f32_e32 v241, v158, v158
	v_mul_f32_e32 v213, v159, v159
	v_fmac_f32_e32 v241, v160, v160
	v_fmac_f32_e32 v213, v161, v161
	v_fmac_f32_e32 v241, v154, v154
	v_fmac_f32_e32 v213, v155, v155
	v_fmac_f32_e32 v241, v156, v156
	v_fmac_f32_e32 v213, v157, v157
	v_fmac_f32_e32 v241, v150, v150
	v_fmac_f32_e32 v213, v151, v151
	v_fmac_f32_e32 v241, v152, v152
	v_fmac_f32_e32 v213, v153, v153
	v_fmac_f32_e32 v241, v146, v146
	v_fmac_f32_e32 v213, v147, v147
	v_fmac_f32_e32 v241, v148, v148
	v_fmac_f32_e32 v213, v149, v149
	v_add_f32_e32 v241, v241, v213
	ds_bpermute_b32 v213, v238, v241
	v_pk_mul_f32 v[162:163], v[158:159], v[74:75]
	v_pk_mul_f32 v[164:165], v[160:161], v[76:77]
	v_pk_mul_f32 v[166:167], v[154:155], v[78:79]
	v_pk_mul_f32 v[168:169], v[156:157], v[80:81]
	v_pk_mul_f32 v[170:171], v[150:151], v[82:83]
	v_pk_mul_f32 v[172:173], v[152:153], v[84:85]
	v_pk_mul_f32 v[174:175], v[146:147], v[86:87]
	v_pk_mul_f32 v[176:177], v[148:149], v[88:89]
	v_cvt_pk_bf16_f32 v158, v158, v159
	v_cvt_pk_bf16_f32 v159, v160, v161
	v_cvt_pk_bf16_f32 v160, v154, v155
	v_cvt_pk_bf16_f32 v161, v156, v157
	v_cvt_pk_bf16_f32 v150, v150, v151
	v_cvt_pk_bf16_f32 v151, v152, v153
	v_cvt_pk_bf16_f32 v152, v146, v147
	v_cvt_pk_bf16_f32 v153, v148, v149
	v_cvt_pk_bf16_f32 v162, v162, v163
	v_cvt_pk_bf16_f32 v163, v164, v165
	v_cvt_pk_bf16_f32 v164, v166, v167
	v_cvt_pk_bf16_f32 v165, v168, v169
	v_cvt_pk_bf16_f32 v170, v170, v171
	v_cvt_pk_bf16_f32 v171, v172, v173
	v_cvt_pk_bf16_f32 v172, v174, v175
	v_cvt_pk_bf16_f32 v173, v176, v177
	s_waitcnt lgkmcnt(0)
	v_add_f32_e32 v241, v241, v213
	ds_bpermute_b32 v213, v239, v241
	v_permlane16_swap_b32_e32 v158, v160
	v_permlane16_swap_b32_e32 v159, v161
	v_permlane16_swap_b32_e32 v150, v152
	v_permlane16_swap_b32_e32 v151, v153
	v_permlane16_swap_b32_e32 v162, v164
	v_permlane16_swap_b32_e32 v163, v165
	v_permlane16_swap_b32_e32 v170, v172
	v_permlane16_swap_b32_e32 v171, v173
	global_store_dwordx4 v201, v[158:161], s[14:15]
	global_store_dwordx4 v201, v[150:153], s[14:15] offset:256
	global_store_dwordx4 v201, v[162:165], s[44:45]
	global_store_dwordx4 v201, v[170:173], s[44:45] offset:256
	s_waitcnt lgkmcnt(0)
	v_add_f32_e32 v241, v241, v213
	v_mov_b32_e32 v203, v202
	s_and_saveexec_b64 s[60:61], s[4:5]
	global_store_dword v203, v241, s[16:17]
	s_or_b64 exec, exec, s[60:61]
	v_add_u32_e32 v203, 0x30000, v200
	global_load_dwordx4 v[162:165], v203, s[36:37]
	global_load_dwordx4 v[166:169], v203, s[36:37] offset:64
	global_load_dwordx4 v[170:173], v203, s[36:37] offset:512
	global_load_dwordx4 v[174:177], v203, s[36:37] offset:576
	s_waitcnt vmcnt(13)
; __device__ __forceinline__ unsigned pk2(float lo, float hi) { return f2bf(lo) | (f2bf(hi) << 16); }
;     __device__ __forceinline__ void operator()(const pg8::f32x4 (&acc)[2][2][4][2], const pg8::Unit& u, int wr, int wc, int fr, int fq) const {
;     ...
; #pragma unroll
;                 for (int mm = 0; mm < MB; ++mm) { const int m = mh + mm;
;                     const size_t row = (size_t)u.pm * 256 + ai * 128 + wr * 64 + m * 16 + fr;
;                     float ss = 0.f;
; #pragma unroll
;                     for (int bj = 0; bj < 2; ++bj)
; #pragma unroll
;                         for (int n = 0; n < 2; ++n) { const size_t off = row * D + col0 + bj * 128 + n * 16;
;                             const f32x4 x1 = xv[mm][bj][n] + gt[bj][n] * acc[ai][bj][m][n];
;                             { v2u pb; pb.x = pk2(x1.x, x1.y); pb.y = pk2(x1.z, x1.w); *(v2u*)(x1b + off) = pb; } ss += (x1.x * x1.x + x1.y * x1.y) + (x1.z * x1.z + x1.w * x1.w);
;                             const f32x4 xa = x1 * al[bj][n]; v2u pk; pk.x = pk2(xa.x, xa.y); pk.y = pk2(xa.z, xa.w); *(v2u*)(x1a + off) = pk; }
;                     ss += __shfl_xor(ss, 16); ss += __shfl_xor(ss, 32);
;                     if (fq == 0) ssq[row * 16 + u.pn * 4 + wc] = ss;
	v_pk_fma_f32 v[142:143], v[142:143], v[58:59], v[214:215]
	v_pk_fma_f32 v[144:145], v[144:145], v[60:61], v[216:217]
	v_pk_fma_f32 v[138:139], v[138:139], v[62:63], v[218:219]
	v_pk_fma_f32 v[140:141], v[140:141], v[64:65], v[220:221]
	v_pk_fma_f32 v[134:135], v[134:135], v[66:67], v[222:223]
	v_pk_fma_f32 v[136:137], v[136:137], v[68:69], v[224:225]
	v_pk_fma_f32 v[130:131], v[130:131], v[70:71], v[226:227]
	v_pk_fma_f32 v[132:133], v[132:133], v[72:73], v[228:229]
	v_mul_f32_e32 v241, v142, v142
	v_mul_f32_e32 v213, v143, v143
	v_fmac_f32_e32 v241, v144, v144
	v_fmac_f32_e32 v213, v145, v145
	v_fmac_f32_e32 v241, v138, v138
	v_fmac_f32_e32 v213, v139, v139
	v_fmac_f32_e32 v241, v140, v140
	v_fmac_f32_e32 v213, v141, v141
	v_fmac_f32_e32 v241, v134, v134
	v_fmac_f32_e32 v213, v135, v135
	v_fmac_f32_e32 v241, v136, v136
	v_fmac_f32_e32 v213, v137, v137
	v_fmac_f32_e32 v241, v130, v130
	v_fmac_f32_e32 v213, v131, v131
	v_fmac_f32_e32 v241, v132, v132
	v_fmac_f32_e32 v213, v133, v133
	v_add_f32_e32 v241, v241, v213
	ds_bpermute_b32 v213, v238, v241
	v_pk_mul_f32 v[214:215], v[142:143], v[74:75]
	v_pk_mul_f32 v[216:217], v[144:145], v[76:77]
	v_pk_mul_f32 v[218:219], v[138:139], v[78:79]
	v_pk_mul_f32 v[220:221], v[140:141], v[80:81]
	v_pk_mul_f32 v[222:223], v[134:135], v[82:83]
	v_pk_mul_f32 v[224:225], v[136:137], v[84:85]
	v_pk_mul_f32 v[226:227], v[130:131], v[86:87]
	v_pk_mul_f32 v[228:229], v[132:133], v[88:89]
	v_cvt_pk_bf16_f32 v142, v142, v143
	v_cvt_pk_bf16_f32 v143, v144, v145
	v_cvt_pk_bf16_f32 v144, v138, v139
	v_cvt_pk_bf16_f32 v145, v140, v141
	v_cvt_pk_bf16_f32 v134, v134, v135
	v_cvt_pk_bf16_f32 v135, v136, v137
	v_cvt_pk_bf16_f32 v136, v130, v131
	v_cvt_pk_bf16_f32 v137, v132, v133
	v_cvt_pk_bf16_f32 v214, v214, v215
	v_cvt_pk_bf16_f32 v215, v216, v217
	v_cvt_pk_bf16_f32 v216, v218, v219
	v_cvt_pk_bf16_f32 v217, v220, v221
	v_cvt_pk_bf16_f32 v222, v222, v223
	v_cvt_pk_bf16_f32 v223, v224, v225
	v_cvt_pk_bf16_f32 v224, v226, v227
	v_cvt_pk_bf16_f32 v225, v228, v229
	s_waitcnt lgkmcnt(0)
	v_add_f32_e32 v241, v241, v213
	ds_bpermute_b32 v213, v239, v241
	v_permlane16_swap_b32_e32 v142, v144
	v_permlane16_swap_b32_e32 v143, v145
	v_permlane16_swap_b32_e32 v134, v136
	v_permlane16_swap_b32_e32 v135, v137
	v_permlane16_swap_b32_e32 v214, v216
	v_permlane16_swap_b32_e32 v215, v217
	v_permlane16_swap_b32_e32 v222, v224
	v_permlane16_swap_b32_e32 v223, v225
	v_add_u32_e32 v203, 0x8000, v201
	global_store_dwordx4 v203, v[142:145], s[14:15]
	global_store_dwordx4 v203, v[134:137], s[14:15] offset:256
	global_store_dwordx4 v203, v[214:217], s[44:45]
	global_store_dwordx4 v203, v[222:225], s[44:45] offset:256
	s_waitcnt lgkmcnt(0)
	v_add_f32_e32 v241, v241, v213
	v_add_u32_e32 v203, 0x400, v202
	s_and_saveexec_b64 s[60:61], s[4:5]
	global_store_dword v203, v241, s[16:17]
	s_or_b64 exec, exec, s[60:61]
	v_add_u32_e32 v203, 0x80000, v200
	global_load_dwordx4 v[214:217], v203, s[36:37]
	global_load_dwordx4 v[218:221], v203, s[36:37] offset:64
	global_load_dwordx4 v[222:225], v203, s[36:37] offset:512
	global_load_dwordx4 v[226:229], v203, s[36:37] offset:576
	s_waitcnt vmcnt(18)
	v_pk_fma_f32 v[126:127], v[126:127], v[58:59], v[230:231]
	v_pk_fma_f32 v[128:129], v[128:129], v[60:61], v[232:233]
	v_pk_fma_f32 v[122:123], v[122:123], v[62:63], v[234:235]
	v_pk_fma_f32 v[124:125], v[124:125], v[64:65], v[236:237]
	v_pk_fma_f32 v[118:119], v[118:119], v[66:67], v[242:243]
	v_pk_fma_f32 v[120:121], v[120:121], v[68:69], v[244:245]
	v_pk_fma_f32 v[114:115], v[114:115], v[70:71], v[204:205]
	v_pk_fma_f32 v[116:117], v[116:117], v[72:73], v[206:207]
	v_mul_f32_e32 v241, v126, v126
	v_mul_f32_e32 v213, v127, v127
	v_fmac_f32_e32 v241, v128, v128
	v_fmac_f32_e32 v213, v129, v129
	v_fmac_f32_e32 v241, v122, v122
	v_fmac_f32_e32 v213, v123, v123
	v_fmac_f32_e32 v241, v124, v124
	v_fmac_f32_e32 v213, v125, v125
	v_fmac_f32_e32 v241, v118, v118
	v_fmac_f32_e32 v213, v119, v119
	v_fmac_f32_e32 v241, v120, v120
	v_fmac_f32_e32 v213, v121, v121
	v_fmac_f32_e32 v241, v114, v114
	v_fmac_f32_e32 v213, v115, v115
	v_fmac_f32_e32 v241, v116, v116
	v_fmac_f32_e32 v213, v117, v117
	v_add_f32_e32 v241, v241, v213
	ds_bpermute_b32 v213, v238, v241
	v_pk_mul_f32 v[230:231], v[126:127], v[74:75]
	v_pk_mul_f32 v[232:233], v[128:129], v[76:77]
	v_pk_mul_f32 v[234:235], v[122:123], v[78:79]
	v_pk_mul_f32 v[236:237], v[124:125], v[80:81]
	v_pk_mul_f32 v[242:243], v[118:119], v[82:83]
	v_pk_mul_f32 v[244:245], v[120:121], v[84:85]
	v_pk_mul_f32 v[204:205], v[114:115], v[86:87]
	v_pk_mul_f32 v[206:207], v[116:117], v[88:89]
	v_cvt_pk_bf16_f32 v126, v126, v127
	v_cvt_pk_bf16_f32 v127, v128, v129
	v_cvt_pk_bf16_f32 v128, v122, v123
	v_cvt_pk_bf16_f32 v129, v124, v125
	v_cvt_pk_bf16_f32 v118, v118, v119
	v_cvt_pk_bf16_f32 v119, v120, v121
	v_cvt_pk_bf16_f32 v120, v114, v115
	v_cvt_pk_bf16_f32 v121, v116, v117
	v_cvt_pk_bf16_f32 v230, v230, v231
	v_cvt_pk_bf16_f32 v231, v232, v233
	v_cvt_pk_bf16_f32 v232, v234, v235
	v_cvt_pk_bf16_f32 v233, v236, v237
	v_cvt_pk_bf16_f32 v242, v242, v243
	v_cvt_pk_bf16_f32 v243, v244, v245
	v_cvt_pk_bf16_f32 v244, v204, v205
	v_cvt_pk_bf16_f32 v245, v206, v207
	s_waitcnt lgkmcnt(0)
	v_add_f32_e32 v241, v241, v213
	ds_bpermute_b32 v213, v239, v241
	v_permlane16_swap_b32_e32 v126, v128
	v_permlane16_swap_b32_e32 v127, v129
	v_permlane16_swap_b32_e32 v118, v120
	v_permlane16_swap_b32_e32 v119, v121
	v_permlane16_swap_b32_e32 v230, v232
	v_permlane16_swap_b32_e32 v231, v233
	v_permlane16_swap_b32_e32 v242, v244
	v_permlane16_swap_b32_e32 v243, v245
	v_add_u32_e32 v203, 0x10000, v201
	global_store_dwordx4 v203, v[126:129], s[14:15]
	global_store_dwordx4 v203, v[118:121], s[14:15] offset:256
	global_store_dwordx4 v203, v[230:233], s[44:45]
	global_store_dwordx4 v203, v[242:245], s[44:45] offset:256
	s_waitcnt lgkmcnt(0)
; __device__ __forceinline__ unsigned pk2(float lo, float hi) { return f2bf(lo) | (f2bf(hi) << 16); }
;     __device__ __forceinline__ void operator()(const pg8::f32x4 (&acc)[2][2][4][2], const pg8::Unit& u, int wr, int wc, int fr, int fq) const {
;     ...
; #pragma unroll
;                 for (int mm = 0; mm < MB; ++mm) { const int m = mh + mm;
;                     const size_t row = (size_t)u.pm * 256 + ai * 128 + wr * 64 + m * 16 + fr;
;                     float ss = 0.f;
; #pragma unroll
;                     for (int bj = 0; bj < 2; ++bj)
; #pragma unroll
;                         for (int n = 0; n < 2; ++n) { const size_t off = row * D + col0 + bj * 128 + n * 16;
;                             const f32x4 x1 = xv[mm][bj][n] + gt[bj][n] * acc[ai][bj][m][n];
;                             { v2u pb; pb.x = pk2(x1.x, x1.y); pb.y = pk2(x1.z, x1.w); *(v2u*)(x1b + off) = pb; } ss += (x1.x * x1.x + x1.y * x1.y) + (x1.z * x1.z + x1.w * x1.w);
;                             const f32x4 xa = x1 * al[bj][n]; v2u pk; pk.x = pk2(xa.x, xa.y); pk.y = pk2(xa.z, xa.w); *(v2u*)(x1a + off) = pk; }
;                     ss += __shfl_xor(ss, 16); ss += __shfl_xor(ss, 32);
;                     if (fq == 0) ssq[row * 16 + u.pn * 4 + wc] = ss;
	v_add_f32_e32 v241, v241, v213
	v_add_u32_e32 v203, 0x800, v202
	s_and_saveexec_b64 s[60:61], s[4:5]
	global_store_dword v203, v241, s[16:17]
	s_or_b64 exec, exec, s[60:61]
	v_add_u32_e32 v203, 0x90000, v200
	global_load_dwordx4 v[230:233], v203, s[36:37]
	global_load_dwordx4 v[234:237], v203, s[36:37] offset:64
	global_load_dwordx4 v[242:245], v203, s[36:37] offset:512
	global_load_dwordx4 v[204:207], v203, s[36:37] offset:576
	s_waitcnt vmcnt(18)
	v_pk_fma_f32 v[110:111], v[110:111], v[58:59], v[162:163]
	v_pk_fma_f32 v[112:113], v[112:113], v[60:61], v[164:165]
	v_pk_fma_f32 v[106:107], v[106:107], v[62:63], v[166:167]
	v_pk_fma_f32 v[108:109], v[108:109], v[64:65], v[168:169]
	v_pk_fma_f32 v[102:103], v[102:103], v[66:67], v[170:171]
	v_pk_fma_f32 v[104:105], v[104:105], v[68:69], v[172:173]
	v_pk_fma_f32 v[98:99], v[98:99], v[70:71], v[174:175]
	v_pk_fma_f32 v[100:101], v[100:101], v[72:73], v[176:177]
	v_mul_f32_e32 v241, v110, v110
	v_mul_f32_e32 v213, v111, v111
	v_fmac_f32_e32 v241, v112, v112
	v_fmac_f32_e32 v213, v113, v113
	v_fmac_f32_e32 v241, v106, v106
	v_fmac_f32_e32 v213, v107, v107
	v_fmac_f32_e32 v241, v108, v108
	v_fmac_f32_e32 v213, v109, v109
	v_fmac_f32_e32 v241, v102, v102
	v_fmac_f32_e32 v213, v103, v103
	v_fmac_f32_e32 v241, v104, v104
	v_fmac_f32_e32 v213, v105, v105
	v_fmac_f32_e32 v241, v98, v98
	v_fmac_f32_e32 v213, v99, v99
	v_fmac_f32_e32 v241, v100, v100
	v_fmac_f32_e32 v213, v101, v101
	v_add_f32_e32 v241, v241, v213
	ds_bpermute_b32 v213, v238, v241
	v_pk_mul_f32 v[162:163], v[110:111], v[74:75]
	v_pk_mul_f32 v[164:165], v[112:113], v[76:77]
	v_pk_mul_f32 v[166:167], v[106:107], v[78:79]
	v_pk_mul_f32 v[168:169], v[108:109], v[80:81]
	v_pk_mul_f32 v[170:171], v[102:103], v[82:83]
	v_pk_mul_f32 v[172:173], v[104:105], v[84:85]
	v_pk_mul_f32 v[174:175], v[98:99], v[86:87]
	v_pk_mul_f32 v[176:177], v[100:101], v[88:89]
	v_cvt_pk_bf16_f32 v110, v110, v111
	v_cvt_pk_bf16_f32 v111, v112, v113
	v_cvt_pk_bf16_f32 v112, v106, v107
	v_cvt_pk_bf16_f32 v113, v108, v109
	v_cvt_pk_bf16_f32 v102, v102, v103
	v_cvt_pk_bf16_f32 v103, v104, v105
	v_cvt_pk_bf16_f32 v104, v98, v99
	v_cvt_pk_bf16_f32 v105, v100, v101
	v_cvt_pk_bf16_f32 v162, v162, v163
	v_cvt_pk_bf16_f32 v163, v164, v165
	v_cvt_pk_bf16_f32 v164, v166, v167
	v_cvt_pk_bf16_f32 v165, v168, v169
	v_cvt_pk_bf16_f32 v170, v170, v171
	v_cvt_pk_bf16_f32 v171, v172, v173
	v_cvt_pk_bf16_f32 v172, v174, v175
	v_cvt_pk_bf16_f32 v173, v176, v177
	s_waitcnt lgkmcnt(0)
	v_add_f32_e32 v241, v241, v213
	ds_bpermute_b32 v213, v239, v241
	v_permlane16_swap_b32_e32 v110, v112
	v_permlane16_swap_b32_e32 v111, v113
	v_permlane16_swap_b32_e32 v102, v104
	v_permlane16_swap_b32_e32 v103, v105
	v_permlane16_swap_b32_e32 v162, v164
	v_permlane16_swap_b32_e32 v163, v165
	v_permlane16_swap_b32_e32 v170, v172
	v_permlane16_swap_b32_e32 v171, v173
	v_add_u32_e32 v203, 0x18000, v201
	global_store_dwordx4 v203, v[110:113], s[14:15]
	global_store_dwordx4 v203, v[102:105], s[14:15] offset:256
	global_store_dwordx4 v203, v[162:165], s[44:45]
	global_store_dwordx4 v203, v[170:173], s[44:45] offset:256
	s_waitcnt lgkmcnt(0)
	v_add_f32_e32 v241, v241, v213
	v_add_u32_e32 v203, 0xc00, v202
	s_and_saveexec_b64 s[60:61], s[4:5]
	global_store_dword v203, v241, s[16:17]
	s_or_b64 exec, exec, s[60:61]
	v_add_u32_e32 v203, 0xa0000, v200
	global_load_dwordx4 v[162:165], v203, s[36:37]
	global_load_dwordx4 v[166:169], v203, s[36:37] offset:64
	global_load_dwordx4 v[170:173], v203, s[36:37] offset:512
	global_load_dwordx4 v[174:177], v203, s[36:37] offset:576
	s_waitcnt vmcnt(18)
	v_pk_fma_f32 v[94:95], v[94:95], v[58:59], v[214:215]
	v_pk_fma_f32 v[96:97], v[96:97], v[60:61], v[216:217]
	v_pk_fma_f32 v[90:91], v[90:91], v[62:63], v[218:219]
	v_pk_fma_f32 v[92:93], v[92:93], v[64:65], v[220:221]
	v_pk_fma_f32 v[54:55], v[54:55], v[66:67], v[222:223]
	v_pk_fma_f32 v[56:57], v[56:57], v[68:69], v[224:225]
	v_pk_fma_f32 v[50:51], v[50:51], v[70:71], v[226:227]
	v_pk_fma_f32 v[52:53], v[52:53], v[72:73], v[228:229]
	v_mul_f32_e32 v241, v94, v94
	v_mul_f32_e32 v213, v95, v95
	v_fmac_f32_e32 v241, v96, v96
	v_fmac_f32_e32 v213, v97, v97
	v_fmac_f32_e32 v241, v90, v90
	v_fmac_f32_e32 v213, v91, v91
	v_fmac_f32_e32 v241, v92, v92
	v_fmac_f32_e32 v213, v93, v93
	v_fmac_f32_e32 v241, v54, v54
	v_fmac_f32_e32 v213, v55, v55
	v_fmac_f32_e32 v241, v56, v56
	v_fmac_f32_e32 v213, v57, v57
	v_fmac_f32_e32 v241, v50, v50
	v_fmac_f32_e32 v213, v51, v51
	v_fmac_f32_e32 v241, v52, v52
	v_fmac_f32_e32 v213, v53, v53
	v_add_f32_e32 v241, v241, v213
	ds_bpermute_b32 v213, v238, v241
	v_pk_mul_f32 v[214:215], v[94:95], v[74:75]
	v_pk_mul_f32 v[216:217], v[96:97], v[76:77]
	v_pk_mul_f32 v[218:219], v[90:91], v[78:79]
	v_pk_mul_f32 v[220:221], v[92:93], v[80:81]
	v_pk_mul_f32 v[222:223], v[54:55], v[82:83]
	v_pk_mul_f32 v[224:225], v[56:57], v[84:85]
	v_pk_mul_f32 v[226:227], v[50:51], v[86:87]
	v_pk_mul_f32 v[228:229], v[52:53], v[88:89]
	v_cvt_pk_bf16_f32 v94, v94, v95
	v_cvt_pk_bf16_f32 v95, v96, v97
	v_cvt_pk_bf16_f32 v96, v90, v91
	v_cvt_pk_bf16_f32 v97, v92, v93
	v_cvt_pk_bf16_f32 v54, v54, v55
	v_cvt_pk_bf16_f32 v55, v56, v57
	v_cvt_pk_bf16_f32 v56, v50, v51
	v_cvt_pk_bf16_f32 v57, v52, v53
	v_cvt_pk_bf16_f32 v214, v214, v215
	v_cvt_pk_bf16_f32 v215, v216, v217
	v_cvt_pk_bf16_f32 v216, v218, v219
	v_cvt_pk_bf16_f32 v217, v220, v221
	v_cvt_pk_bf16_f32 v222, v222, v223
	v_cvt_pk_bf16_f32 v223, v224, v225
	v_cvt_pk_bf16_f32 v224, v226, v227
	v_cvt_pk_bf16_f32 v225, v228, v229
	s_waitcnt lgkmcnt(0)
; __device__ __forceinline__ unsigned pk2(float lo, float hi) { return f2bf(lo) | (f2bf(hi) << 16); }
;     __device__ __forceinline__ void operator()(const pg8::f32x4 (&acc)[2][2][4][2], const pg8::Unit& u, int wr, int wc, int fr, int fq) const {
;     ...
;                 for (int mm = 0; mm < MB; ++mm) { const size_t row = (size_t)u.pm * 256 + ai * 128 + wr * 64 + (mh + mm) * 16 + fr;
; #pragma unroll
;                     for (int bj = 0; bj < 2; ++bj)
; #pragma unroll
;                         for (int n = 0; n < 2; ++n) xv[mm][bj][n] = *(const f32x4*)(x + row * D + col0 + bj * 128 + n * 16); }
; #pragma unroll
;                 for (int mm = 0; mm < MB; ++mm) { const int m = mh + mm;
;                     const size_t row = (size_t)u.pm * 256 + ai * 128 + wr * 64 + m * 16 + fr;
;                     float ss = 0.f;
; #pragma unroll
;                     for (int bj = 0; bj < 2; ++bj)
; #pragma unroll
;                         for (int n = 0; n < 2; ++n) { const size_t off = row * D + col0 + bj * 128 + n * 16;
;                             const f32x4 x1 = xv[mm][bj][n] + gt[bj][n] * acc[ai][bj][m][n];
;                             { v2u pb; pb.x = pk2(x1.x, x1.y); pb.y = pk2(x1.z, x1.w); *(v2u*)(x1b + off) = pb; } ss += (x1.x * x1.x + x1.y * x1.y) + (x1.z * x1.z + x1.w * x1.w);
;                             const f32x4 xa = x1 * al[bj][n]; v2u pk; pk.x = pk2(xa.x, xa.y); pk.y = pk2(xa.z, xa.w); *(v2u*)(x1a + off) = pk; }
;                     ss += __shfl_xor(ss, 16); ss += __shfl_xor(ss, 32);
;                     if (fq == 0) ssq[row * 16 + u.pn * 4 + wc] = ss;
;                 }
	v_add_f32_e32 v241, v241, v213
	ds_bpermute_b32 v213, v239, v241
	v_permlane16_swap_b32_e32 v94, v96
	v_permlane16_swap_b32_e32 v95, v97
	v_permlane16_swap_b32_e32 v54, v56
	v_permlane16_swap_b32_e32 v55, v57
	v_permlane16_swap_b32_e32 v214, v216
	v_permlane16_swap_b32_e32 v215, v217
	v_permlane16_swap_b32_e32 v222, v224
	v_permlane16_swap_b32_e32 v223, v225
	v_add_u32_e32 v203, 0x40000, v201
	global_store_dwordx4 v203, v[94:97], s[14:15]
	global_store_dwordx4 v203, v[54:57], s[14:15] offset:256
	global_store_dwordx4 v203, v[214:217], s[44:45]
	global_store_dwordx4 v203, v[222:225], s[44:45] offset:256
	s_waitcnt lgkmcnt(0)
	v_add_f32_e32 v241, v241, v213
	v_add_u32_e32 v203, 0x2000, v202
	s_and_saveexec_b64 s[60:61], s[4:5]
	global_store_dword v203, v241, s[16:17]
	s_or_b64 exec, exec, s[60:61]
	v_add_u32_e32 v203, 0xb0000, v200
	global_load_dwordx4 v[214:217], v203, s[36:37]
	global_load_dwordx4 v[218:221], v203, s[36:37] offset:64
	global_load_dwordx4 v[222:225], v203, s[36:37] offset:512
	global_load_dwordx4 v[226:229], v203, s[36:37] offset:576
	s_waitcnt vmcnt(18)
	v_pk_fma_f32 v[46:47], v[46:47], v[58:59], v[230:231]
	v_pk_fma_f32 v[48:49], v[48:49], v[60:61], v[232:233]
	v_pk_fma_f32 v[42:43], v[42:43], v[62:63], v[234:235]
	v_pk_fma_f32 v[44:45], v[44:45], v[64:65], v[236:237]
	v_pk_fma_f32 v[38:39], v[38:39], v[66:67], v[242:243]
	v_pk_fma_f32 v[40:41], v[40:41], v[68:69], v[244:245]
	v_pk_fma_f32 v[34:35], v[34:35], v[70:71], v[204:205]
	v_pk_fma_f32 v[36:37], v[36:37], v[72:73], v[206:207]
	v_mul_f32_e32 v241, v46, v46
	v_mul_f32_e32 v213, v47, v47
	v_fmac_f32_e32 v241, v48, v48
	v_fmac_f32_e32 v213, v49, v49
	v_fmac_f32_e32 v241, v42, v42
	v_fmac_f32_e32 v213, v43, v43
	v_fmac_f32_e32 v241, v44, v44
	v_fmac_f32_e32 v213, v45, v45
	v_fmac_f32_e32 v241, v38, v38
	v_fmac_f32_e32 v213, v39, v39
	v_fmac_f32_e32 v241, v40, v40
	v_fmac_f32_e32 v213, v41, v41
	v_fmac_f32_e32 v241, v34, v34
	v_fmac_f32_e32 v213, v35, v35
	v_fmac_f32_e32 v241, v36, v36
	v_fmac_f32_e32 v213, v37, v37
	v_add_f32_e32 v241, v241, v213
	ds_bpermute_b32 v213, v238, v241
	v_pk_mul_f32 v[230:231], v[46:47], v[74:75]
	v_pk_mul_f32 v[232:233], v[48:49], v[76:77]
	v_pk_mul_f32 v[234:235], v[42:43], v[78:79]
	v_pk_mul_f32 v[236:237], v[44:45], v[80:81]
	v_pk_mul_f32 v[242:243], v[38:39], v[82:83]
	v_pk_mul_f32 v[244:245], v[40:41], v[84:85]
	v_pk_mul_f32 v[204:205], v[34:35], v[86:87]
	v_pk_mul_f32 v[206:207], v[36:37], v[88:89]
	v_cvt_pk_bf16_f32 v46, v46, v47
	v_cvt_pk_bf16_f32 v47, v48, v49
	v_cvt_pk_bf16_f32 v48, v42, v43
	v_cvt_pk_bf16_f32 v49, v44, v45
	v_cvt_pk_bf16_f32 v38, v38, v39
	v_cvt_pk_bf16_f32 v39, v40, v41
	v_cvt_pk_bf16_f32 v40, v34, v35
	v_cvt_pk_bf16_f32 v41, v36, v37
	v_cvt_pk_bf16_f32 v230, v230, v231
	v_cvt_pk_bf16_f32 v231, v232, v233
	v_cvt_pk_bf16_f32 v232, v234, v235
	v_cvt_pk_bf16_f32 v233, v236, v237
	v_cvt_pk_bf16_f32 v242, v242, v243
	v_cvt_pk_bf16_f32 v243, v244, v245
	v_cvt_pk_bf16_f32 v244, v204, v205
	v_cvt_pk_bf16_f32 v245, v206, v207
	s_waitcnt lgkmcnt(0)
	v_add_f32_e32 v241, v241, v213
	ds_bpermute_b32 v213, v239, v241
	v_permlane16_swap_b32_e32 v46, v48
	v_permlane16_swap_b32_e32 v47, v49
	v_permlane16_swap_b32_e32 v38, v40
	v_permlane16_swap_b32_e32 v39, v41
	v_permlane16_swap_b32_e32 v230, v232
	v_permlane16_swap_b32_e32 v231, v233
	v_permlane16_swap_b32_e32 v242, v244
	v_permlane16_swap_b32_e32 v243, v245
	v_add_u32_e32 v203, 0x48000, v201
	global_store_dwordx4 v203, v[46:49], s[14:15]
	global_store_dwordx4 v203, v[38:41], s[14:15] offset:256
	global_store_dwordx4 v203, v[230:233], s[44:45]
	global_store_dwordx4 v203, v[242:245], s[44:45] offset:256
	s_waitcnt lgkmcnt(0)
	v_add_f32_e32 v241, v241, v213
	v_add_u32_e32 v203, 0x2400, v202
	s_and_saveexec_b64 s[60:61], s[4:5]
	global_store_dword v203, v241, s[16:17]
	s_or_b64 exec, exec, s[60:61]
	s_waitcnt vmcnt(14)
; __device__ __forceinline__ unsigned pk2(float lo, float hi) { return f2bf(lo) | (f2bf(hi) << 16); }
;     __device__ __forceinline__ void operator()(const pg8::f32x4 (&acc)[2][2][4][2], const pg8::Unit& u, int wr, int wc, int fr, int fq) const {
;     ...
;                 for (int mm = 0; mm < MB; ++mm) { const size_t row = (size_t)u.pm * 256 + ai * 128 + wr * 64 + (mh + mm) * 16 + fr;
; #pragma unroll
;                     for (int bj = 0; bj < 2; ++bj)
; #pragma unroll
;                         for (int n = 0; n < 2; ++n) xv[mm][bj][n] = *(const f32x4*)(x + row * D + col0 + bj * 128 + n * 16); }
; #pragma unroll
;                 for (int mm = 0; mm < MB; ++mm) { const int m = mh + mm;
;                     const size_t row = (size_t)u.pm * 256 + ai * 128 + wr * 64 + m * 16 + fr;
;                     float ss = 0.f;
; #pragma unroll
;                     for (int bj = 0; bj < 2; ++bj)
; #pragma unroll
;                         for (int n = 0; n < 2; ++n) { const size_t off = row * D + col0 + bj * 128 + n * 16;
;                             const f32x4 x1 = xv[mm][bj][n] + gt[bj][n] * acc[ai][bj][m][n];
;                             { v2u pb; pb.x = pk2(x1.x, x1.y); pb.y = pk2(x1.z, x1.w); *(v2u*)(x1b + off) = pb; } ss += (x1.x * x1.x + x1.y * x1.y) + (x1.z * x1.z + x1.w * x1.w);
;                             const f32x4 xa = x1 * al[bj][n]; v2u pk; pk.x = pk2(xa.x, xa.y); pk.y = pk2(xa.z, xa.w); *(v2u*)(x1a + off) = pk; }
;                     ss += __shfl_xor(ss, 16); ss += __shfl_xor(ss, 32);
;                     if (fq == 0) ssq[row * 16 + u.pn * 4 + wc] = ss;
;                 }
	v_pk_fma_f32 v[30:31], v[30:31], v[58:59], v[162:163]
	v_pk_fma_f32 v[32:33], v[32:33], v[60:61], v[164:165]
	v_pk_fma_f32 v[26:27], v[26:27], v[62:63], v[166:167]
	v_pk_fma_f32 v[28:29], v[28:29], v[64:65], v[168:169]
	v_pk_fma_f32 v[22:23], v[22:23], v[66:67], v[170:171]
	v_pk_fma_f32 v[24:25], v[24:25], v[68:69], v[172:173]
	v_pk_fma_f32 v[18:19], v[18:19], v[70:71], v[174:175]
	v_pk_fma_f32 v[20:21], v[20:21], v[72:73], v[176:177]
	v_mul_f32_e32 v241, v30, v30
	v_mul_f32_e32 v213, v31, v31
	v_fmac_f32_e32 v241, v32, v32
	v_fmac_f32_e32 v213, v33, v33
	v_fmac_f32_e32 v241, v26, v26
	v_fmac_f32_e32 v213, v27, v27
	v_fmac_f32_e32 v241, v28, v28
	v_fmac_f32_e32 v213, v29, v29
	v_fmac_f32_e32 v241, v22, v22
	v_fmac_f32_e32 v213, v23, v23
	v_fmac_f32_e32 v241, v24, v24
	v_fmac_f32_e32 v213, v25, v25
	v_fmac_f32_e32 v241, v18, v18
	v_fmac_f32_e32 v213, v19, v19
	v_fmac_f32_e32 v241, v20, v20
	v_fmac_f32_e32 v213, v21, v21
	v_add_f32_e32 v241, v241, v213
	ds_bpermute_b32 v213, v238, v241
	v_pk_mul_f32 v[162:163], v[30:31], v[74:75]
	v_pk_mul_f32 v[164:165], v[32:33], v[76:77]
	v_pk_mul_f32 v[166:167], v[26:27], v[78:79]
	v_pk_mul_f32 v[168:169], v[28:29], v[80:81]
	v_pk_mul_f32 v[170:171], v[22:23], v[82:83]
	v_pk_mul_f32 v[172:173], v[24:25], v[84:85]
	v_pk_mul_f32 v[174:175], v[18:19], v[86:87]
	v_pk_mul_f32 v[176:177], v[20:21], v[88:89]
	v_cvt_pk_bf16_f32 v30, v30, v31
	v_cvt_pk_bf16_f32 v31, v32, v33
	v_cvt_pk_bf16_f32 v32, v26, v27
	v_cvt_pk_bf16_f32 v33, v28, v29
	v_cvt_pk_bf16_f32 v22, v22, v23
	v_cvt_pk_bf16_f32 v23, v24, v25
	v_cvt_pk_bf16_f32 v24, v18, v19
	v_cvt_pk_bf16_f32 v25, v20, v21
	v_cvt_pk_bf16_f32 v162, v162, v163
	v_cvt_pk_bf16_f32 v163, v164, v165
	v_cvt_pk_bf16_f32 v164, v166, v167
	v_cvt_pk_bf16_f32 v165, v168, v169
	v_cvt_pk_bf16_f32 v170, v170, v171
	v_cvt_pk_bf16_f32 v171, v172, v173
	v_cvt_pk_bf16_f32 v172, v174, v175
	v_cvt_pk_bf16_f32 v173, v176, v177
	s_waitcnt lgkmcnt(0)
	v_add_f32_e32 v241, v241, v213
	ds_bpermute_b32 v213, v239, v241
	v_permlane16_swap_b32_e32 v30, v32
	v_permlane16_swap_b32_e32 v31, v33
	v_permlane16_swap_b32_e32 v22, v24
	v_permlane16_swap_b32_e32 v23, v25
	v_permlane16_swap_b32_e32 v162, v164
	v_permlane16_swap_b32_e32 v163, v165
	v_permlane16_swap_b32_e32 v170, v172
	v_permlane16_swap_b32_e32 v171, v173
	v_add_u32_e32 v203, 0x50000, v201
	global_store_dwordx4 v203, v[30:33], s[14:15]
	global_store_dwordx4 v203, v[22:25], s[14:15] offset:256
	global_store_dwordx4 v203, v[162:165], s[44:45]
	global_store_dwordx4 v203, v[170:173], s[44:45] offset:256
	s_waitcnt lgkmcnt(0)
	v_add_f32_e32 v241, v241, v213
	v_add_u32_e32 v203, 0x2800, v202
	s_and_saveexec_b64 s[60:61], s[4:5]
	global_store_dword v203, v241, s[16:17]
	s_or_b64 exec, exec, s[60:61]
	s_waitcnt vmcnt(10)
	v_pk_fma_f32 v[14:15], v[14:15], v[58:59], v[214:215]
	v_pk_fma_f32 v[16:17], v[16:17], v[60:61], v[216:217]
	v_pk_fma_f32 v[10:11], v[10:11], v[62:63], v[218:219]
	v_pk_fma_f32 v[12:13], v[12:13], v[64:65], v[220:221]
	v_pk_fma_f32 v[6:7], v[6:7], v[66:67], v[222:223]
	v_pk_fma_f32 v[8:9], v[8:9], v[68:69], v[224:225]
	v_pk_fma_f32 v[2:3], v[2:3], v[70:71], v[226:227]
	v_pk_fma_f32 v[4:5], v[4:5], v[72:73], v[228:229]
	v_mul_f32_e32 v241, v14, v14
	v_mul_f32_e32 v213, v15, v15
	v_fmac_f32_e32 v241, v16, v16
	v_fmac_f32_e32 v213, v17, v17
	v_fmac_f32_e32 v241, v10, v10
	v_fmac_f32_e32 v213, v11, v11
	v_fmac_f32_e32 v241, v12, v12
	v_fmac_f32_e32 v213, v13, v13
	v_fmac_f32_e32 v241, v6, v6
	v_fmac_f32_e32 v213, v7, v7
	v_fmac_f32_e32 v241, v8, v8
	v_fmac_f32_e32 v213, v9, v9
	v_fmac_f32_e32 v241, v2, v2
	v_fmac_f32_e32 v213, v3, v3
	v_fmac_f32_e32 v241, v4, v4
	v_fmac_f32_e32 v213, v5, v5
	v_add_f32_e32 v241, v241, v213
	ds_bpermute_b32 v213, v238, v241
	v_pk_mul_f32 v[214:215], v[14:15], v[74:75]
	v_pk_mul_f32 v[216:217], v[16:17], v[76:77]
	v_pk_mul_f32 v[218:219], v[10:11], v[78:79]
	v_pk_mul_f32 v[220:221], v[12:13], v[80:81]
	v_pk_mul_f32 v[222:223], v[6:7], v[82:83]
	v_pk_mul_f32 v[224:225], v[8:9], v[84:85]
	v_pk_mul_f32 v[226:227], v[2:3], v[86:87]
	v_pk_mul_f32 v[228:229], v[4:5], v[88:89]
	v_cvt_pk_bf16_f32 v14, v14, v15
	v_cvt_pk_bf16_f32 v15, v16, v17
	v_cvt_pk_bf16_f32 v16, v10, v11
	v_cvt_pk_bf16_f32 v17, v12, v13
	v_cvt_pk_bf16_f32 v6, v6, v7
	v_cvt_pk_bf16_f32 v7, v8, v9
	v_cvt_pk_bf16_f32 v8, v2, v3
	v_cvt_pk_bf16_f32 v9, v4, v5
	v_cvt_pk_bf16_f32 v214, v214, v215
	v_cvt_pk_bf16_f32 v215, v216, v217
	v_cvt_pk_bf16_f32 v216, v218, v219
	v_cvt_pk_bf16_f32 v217, v220, v221
	v_cvt_pk_bf16_f32 v222, v222, v223
	v_cvt_pk_bf16_f32 v223, v224, v225
	v_cvt_pk_bf16_f32 v224, v226, v227
	v_cvt_pk_bf16_f32 v225, v228, v229
	s_waitcnt lgkmcnt(0)
	v_add_f32_e32 v241, v241, v213
	ds_bpermute_b32 v213, v239, v241
	v_permlane16_swap_b32_e32 v14, v16
	v_permlane16_swap_b32_e32 v15, v17
	v_permlane16_swap_b32_e32 v6, v8
	v_permlane16_swap_b32_e32 v7, v9
	v_permlane16_swap_b32_e32 v214, v216
	v_permlane16_swap_b32_e32 v215, v217
	v_permlane16_swap_b32_e32 v222, v224
	v_permlane16_swap_b32_e32 v223, v225
	v_add_u32_e32 v203, 0x58000, v201
	global_store_dwordx4 v203, v[14:17], s[14:15]
	global_store_dwordx4 v203, v[6:9], s[14:15] offset:256
	global_store_dwordx4 v203, v[214:217], s[44:45]
	global_store_dwordx4 v203, v[222:225], s[44:45] offset:256
	s_waitcnt lgkmcnt(0)
	v_add_f32_e32 v241, v241, v213
	v_add_u32_e32 v203, 0x2c00, v202
	s_and_saveexec_b64 s[60:61], s[4:5]
	global_store_dword v203, v241, s[16:17]
	s_or_b64 exec, exec, s[60:61]
	s_mov_b64 s[60:61], exec

; __global__ void __launch_bounds__(NTHR, 2) mega(Args args) {
	.amdhsa_kernel _ZN2mk4megaENS_4ArgsE
		.amdhsa_group_segment_fixed_size 0
		.amdhsa_private_segment_fixed_size 0
		.amdhsa_kernarg_size 432
		.amdhsa_user_sgpr_count 2
		.amdhsa_user_sgpr_dispatch_ptr 0
		.amdhsa_user_sgpr_queue_ptr 0
		.amdhsa_user_sgpr_kernarg_segment_ptr 1
		.amdhsa_user_sgpr_dispatch_id 0
		.amdhsa_user_sgpr_kernarg_preload_length 0
		.amdhsa_user_sgpr_kernarg_preload_offset 0
		.amdhsa_user_sgpr_private_segment_size 0
		.amdhsa_uses_dynamic_stack 0
		.amdhsa_enable_private_segment 0
		.amdhsa_system_sgpr_workgroup_id_x 1
		.amdhsa_system_sgpr_workgroup_id_y 0
		.amdhsa_system_sgpr_workgroup_id_z 0
		.amdhsa_system_sgpr_workgroup_info 0
		.amdhsa_system_vgpr_workitem_id 0
		.amdhsa_next_free_vgpr 248
		.amdhsa_next_free_sgpr 102
		.amdhsa_accum_offset 248
		.amdhsa_reserve_vcc 1
		.amdhsa_float_round_mode_32 0
		.amdhsa_float_round_mode_16_64 0
		.amdhsa_float_denorm_mode_32 3
		.amdhsa_float_denorm_mode_16_64 3
		.amdhsa_dx10_clamp 1
		.amdhsa_ieee_mode 1
		.amdhsa_fp16_overflow 0
		.amdhsa_tg_split 0
		.amdhsa_exception_fp_ieee_invalid_op 0
		.amdhsa_exception_fp_denorm_src 0
		.amdhsa_exception_fp_ieee_div_zero 0
		.amdhsa_exception_fp_ieee_overflow 0
		.amdhsa_exception_fp_ieee_underflow 0
		.amdhsa_exception_fp_ieee_inexact 0
		.amdhsa_exception_int_div_zero 0
	.end_amdhsa_kernel

; __global__ void __launch_bounds__(NTHR, 2) mega(Args args) {
amdhsa.kernels:
  - .agpr_count:     0
    .args:
      - .offset:         0
        .size:           176
        .value_kind:     by_value
      - .offset:         176
        .size:           4
        .value_kind:     hidden_block_count_x
      - .offset:         180
        .size:           4
        .value_kind:     hidden_block_count_y
      - .offset:         184
        .size:           4
        .value_kind:     hidden_block_count_z
      - .offset:         188
        .size:           2
        .value_kind:     hidden_group_size_x
      - .offset:         190
        .size:           2
        .value_kind:     hidden_group_size_y
      - .offset:         192
        .size:           2
        .value_kind:     hidden_group_size_z
      - .offset:         194
        .size:           2
        .value_kind:     hidden_remainder_x
      - .offset:         196
        .size:           2
        .value_kind:     hidden_remainder_y
      - .offset:         198
        .size:           2
        .value_kind:     hidden_remainder_z
      - .offset:         216
        .size:           8
        .value_kind:     hidden_global_offset_x
      - .offset:         224
        .size:           8
        .value_kind:     hidden_global_offset_y
      - .offset:         232
        .size:           8
        .value_kind:     hidden_global_offset_z
      - .offset:         240
        .size:           2
        .value_kind:     hidden_grid_dims
      - .offset:         296
        .size:           4
        .value_kind:     hidden_dynamic_lds_size
    .group_segment_fixed_size: 0
    .kernarg_segment_align: 8
    .kernarg_segment_size: 432
    .language:       OpenCL C
    .language_version:
      - 2
      - 0
    .max_flat_workgroup_size: 512
    .name:           _ZN2mk4megaENS_4ArgsE
    .private_segment_fixed_size: 0
    .sgpr_count:     108
    .sgpr_spill_count: 39
    .symbol:         _ZN2mk4megaENS_4ArgsE.kd
    .uniform_work_group_size: 1
    .uses_dynamic_stack: false
    .vgpr_count:     248
    .vgpr_spill_count: 0
    .wavefront_size: 64
